# adds: DPP LayerNorm reductions in conv mixer, ssq tile staged to LDS by DMA for GU0/GU1/CI epilogues, WIN sink load hoisted
# speedup vs baseline: 1.0022x; 1.0022x over previous
; #define ALAS __attribute__((address_space(3)))
; template <bool WIN> ...
;     ...
;     const int tid = threadIdx.x, lane = tid & 63, l31 = lane & 31, hi = lane >> 5;
;     const int wid = __builtin_amdgcn_readfirstlane(tid >> 6), half = wid >> 2, wq = wid & 3;
;     const int qw = q0 + 32 * wq;
;     int qcol, kcol0, kcol1, vrow0, bhead;
;     if (WIN) { qcol = (2 * hsel + half) * 64; kcol0 = 512 + (hsel >> 1) * 64; kcol1 = kcol0; vrow0 = (hsel >> 1) * 64; bhead = 2 * hsel; }
;     else { qcol = 640 + (2 * hsel + half) * 64; kcol0 = 1152 + (2 * hsel) * 64; kcol1 = kcol0 + 64; vrow0 = 128 + hsel * 128; bhead = 8 + hsel; }
;     const ALAS float* lut = (const ALAS float*)(lds + OFF_LUT) + (WIN ? (bhead + half) : bhead) * LUTW;
;     const int t_lo = WIN ? (q0 >= 128 ? (q0 - 128) / 64 : 0) : 0;
;     const int t_hi = WIN ? ((q0 + 256) / 64 < S / 64 ? (q0 + 256) / 64 : S / 64) : S / 64;
;     const int NT = t_hi - t_lo;
;     const unsigned ldsb = (unsigned)(uintptr_t)lds;
;     const int drow = 8 * wid + (lane >> 3), dch = (lane & 7) ^ ((4 * wid + (lane >> 4)) & 7);
;     const bf16_t* kg = QK + ((size_t)((seq_base >> 6) + t_lo) * 26 * 64 + drow) * 64 + dch * 8 + kcol0 * 64;
;     const bf16_t* vg = VT + ((size_t)((seq_base >> 6) + t_lo) * 640 + vrow0 + drow) * 64 + dch * 8;
;     const unsigned dk = ldsb + wid * 1024;
;     ...
;     constexpr int NPW = WIN ? 2 : 4;
;     bf16x8 qfr[4];
;     { const int qrow = seq_base + qw + l31; const bf16_t* qp = QK + ((size_t)((qrow >> 6) * 26 + (qcol >> 6)) * 64 + (qrow & 63)) * 64 + hi * 8;
; #pragma unroll
;       for (int ds = 0; ds < 4; ++ds) qfr[ds] = *(const bf16x8*)(qp + ds * 16); }
;     ...
;     AT_DMA(0); if (NT > 1) AT_DMA(1); if (NT > 2) AT_DMA(2);
; __device__ __forceinline__ void attn_phase(ALAS unsigned char* lds, const bf16_t* QK, const bf16_t* VT, bf16_t* Y, const float* rel_bias, const float* sinkp, const float* subln, const float* blam) {
;     ...
;     for (int u = bx; u < 4096; u += G) { const int hp = u & 3, qb = u >> 2;
;         const int row0 = qb * 128; int seq_base, S;
;         if (row0 < 65536) { seq_base = row0 & ~8191; S = 8192; } else { seq_base = row0 & ~2047; S = 2048; }
;         attn_unit<true>(lds, QK, VT, Y, rel_bias, sinkp, subln, lam, seq_base, S, row0 - seq_base, hp); }
.LBB0_294:
	s_lshl_b32 s30, s28, 5
	s_and_b32 s12, s28, 3
	s_and_b32 s29, s30, 0xffffff80
	s_cmp_lt_i32 s29, 0x10000
	s_cselect_b32 s31, s24, 0xfffff800
	s_cselect_b32 s52, 0x80, 32
	s_and_b32 s49, s31, s30
	v_readfirstlane_b32 s54, v230
	s_sub_i32 s53, s29, s49
	s_lshr_b32 s29, s54, 1
	s_lshr_b32 s51, s54, 8
	s_and_b32 s48, s29, 0x60
	s_lshl_b32 s12, s12, 1
	s_or_b32 s33, s48, s53
	s_add_i32 s29, s51, s12
	s_and_b32 s12, s30, 64
	s_add_i32 s30, s53, 0xffffff80
	s_lshr_b32 s55, s54, 6
	s_lshr_b32 s30, s30, 6
	v_or_b32_e32 v6, s33, v185
	s_cmpk_gt_i32 s53, 0x7f
	v_add_u32_e32 v116, s49, v6
	s_cselect_b32 s50, s30, 0
	s_ashr_i32 s30, s49, 6
	v_ashrrev_i32_e32 v5, 6, v116
	v_mov_b32_e32 v4, s29
	s_add_i32 s56, s50, s30
	v_mad_u64_u32 v[4:5], s[30:31], v5, 26, v[4:5]
	v_lshl_or_b32 v112, s55, 3, v188
	v_ashrrev_i32_e32 v5, 31, v4
	v_mad_i64_i32 v[0:1], s[30:31], s56, v132, v[112:113]
	v_add_u32_e32 v112, s12, v112
	v_lshlrev_b64 v[4:5], 13, v[4:5]
	v_lshlrev_b32_e32 v6, 7, v6
	v_mad_i64_i32 v[2:3], s[30:31], s56, v133, v[112:113]
	v_lshl_add_u64 v[4:5], s[6:7], 0, v[4:5]
	v_and_b32_e32 v112, 0x1f80, v6
	v_lshl_add_u64 v[4:5], v[4:5], 0, v[112:113]
	v_lshl_add_u64 v[4:5], v[4:5], 0, v[114:115]
	global_load_dwordx4 v[80:83], v[4:5], off
	global_load_dwordx4 v[84:87], v[4:5], off offset:32
	global_load_dwordx4 v[88:91], v[4:5], off offset:64
	global_load_dwordx4 v[92:95], v[4:5], off offset:96
	s_lshl_b32 s98, s29, 2
	v_mov_b32_e32 v238, s98
	global_load_dword v239, v238, s[44:45]
	s_lshr_b32 s31, s54, 4
	s_and_b32 s31, s31, 4
	v_bitop3_b32 v4, s31, v186, v189 bitop3:0x36
	v_lshlrev_b64 v[0:1], 7, v[0:1]
	s_addk_i32 s53, 0x100
	v_lshl_add_u64 v[0:1], s[6:7], 0, v[0:1]
	v_lshlrev_b32_e32 v6, 4, v4
	v_mov_b32_e32 v7, v113
	s_ashr_i32 s30, s53, 6
	v_lshl_add_u64 v[0:1], v[0:1], 0, v[6:7]
	s_lshl_b32 s12, s12, 7
	s_min_i32 s30, s30, s52
	v_lshl_add_u64 v[4:5], v[0:1], 0, s[12:13]
	v_lshlrev_b64 v[0:1], 7, v[2:3]
	s_lshl_b32 s31, s55, 10
	v_lshl_add_u64 v[2:3], s[4:5], 0, v[0:1]
	s_sub_i32 s12, s30, s50
	v_lshl_add_u64 v[0:1], v[4:5], 0, s[16:17]
	s_add_i32 s30, s31, 0
	s_mov_b32 s31, m0
	s_mov_b32 m0, s30
	s_nop 0
	global_load_lds_dwordx4 v[0:1], off
	s_mov_b32 m0, s31
	v_lshl_add_u64 v[2:3], v[2:3], 0, v[6:7]
	s_add_i32 s31, s30, 0x4000
	s_mov_b32 s52, m0
	s_mov_b32 m0, s31
	s_nop 0
	global_load_lds_dwordx4 v[2:3], off
	s_mov_b32 m0, s52
	s_cmp_lt_i32 s12, 2
	s_cbranch_scc1 .LBB0_296
	s_add_i32 s31, s30, 0x8000
	v_lshl_add_u64 v[6:7], v[4:5], 0, s[18:19]
	s_mov_b32 s52, m0
	s_mov_b32 m0, s31
	s_nop 0
	global_load_lds_dwordx4 v[6:7], off
	s_mov_b32 m0, s52
	v_lshl_add_u64 v[6:7], v[2:3], 0, s[20:21]
	s_add_i32 s31, s30, 0xc000
	s_mov_b32 s52, m0
	s_mov_b32 m0, s31
	s_nop 0
	global_load_lds_dwordx4 v[6:7], off
	s_mov_b32 m0, s52

; __device__ __forceinline__ int pi32(int r) { return (r & ~12) | ((r & 4) << 1) | ((r & 8) >> 1); }
; template <bool WIN> ...
;     ...
;     float m_ref = WIN ? sinkp[2 * hsel + half] * LOG2E : 0.f;
;     float l_run = (WIN && hi == 0) ? 1.f : 0.f;
;     float cbase = 0.f;
;     f32x16 cvec;
; #pragma unroll
;     for (int r = 0; r < 16; ++r) cvec[r] = cbase - m_ref;
;     f32x16 o[NDB];
; #pragma unroll
;     for (int db = 0; db < NDB; ++db)
; #pragma unroll
;         for (int r = 0; r < 16; ++r) o[db][r] = 0.f;
;     const int krow = pi32(l31), fK = (krow >> 1) & 7, fV = (l31 >> 1) & 7;
;     int kx[4], vx[4];
; #pragma unroll
;     for (int c = 0; c < 4; ++c) { kx[c] = (WIN ? OFF_K0 : (half ? OFF_K1 : OFF_K0)) + krow * 128 + (((2 * c + hi) ^ fK) << 4); vx[c] = OFF_V + l31 * 128 + (((2 * c + hi) ^ fV) << 4); }
;     const int qabs = qw + l31;
;     const float cfar_lo = __uint_as_float(__builtin_amdgcn_readfirstlane(__float_as_uint(lut[0]))), cfar_hi = __uint_as_float(__builtin_amdgcn_readfirstlane(__float_as_uint(lut[LUTW - 1])));
;     asm volatile("" : "+v"(qfr[0]), "+v"(qfr[1]), "+v"(qfr[2]), "+v"(qfr[3]));
.LBB0_298:
	s_cmp_lt_i32 s12, 1
	s_waitcnt vmcnt(0)
	s_cbranch_scc1 .LBB0_292
	v_mov_b32_e32 v15, v239
	s_and_b32 s53, s27, 3
	s_mul_i32 s55, s51, 0x700
	v_add_u32_e32 v4, s49, v131
	s_mul_i32 s49, s53, 0xe00
	s_lshl_b32 s56, s50, 8
	v_subrev_u32_e32 v32, s48, v4
	s_add_i32 s48, s49, s55
	s_add_i32 s48, s48, s56
	s_and_b32 s54, s22, 0x3fffff80
	s_add_i32 s48, s48, 0
	v_subrev_u32_e32 v32, s54, v32
	s_add_i32 s48, s48, 0x20380
	v_mov_b32_e32 v16, 0
	v_lshl_add_u32 v117, v32, 2, s48
	s_add_i32 s31, s33, 0x9f
	s_addk_i32 s33, 0xff80
	v_lshl_add_u64 v[118:119], v[0:1], 0, s[40:41]
	v_lshl_add_u64 v[120:121], v[2:3], 0, s[42:43]
	s_lshl_b32 s50, s50, 6
	s_mov_b32 s51, 0
	v_mov_b32_e32 v112, v130
	s_mov_b32 s52, 0
	v_mov_b32_e32 v17, v16
	v_mov_b32_e32 v18, v16
	v_mov_b32_e32 v19, v16
	v_mov_b32_e32 v20, v16
	v_mov_b32_e32 v21, v16
	v_mov_b32_e32 v22, v16
	v_mov_b32_e32 v23, v16
	v_mov_b32_e32 v24, v16
	v_mov_b32_e32 v25, v16
	v_mov_b32_e32 v26, v16
	v_mov_b32_e32 v27, v16
	v_mov_b32_e32 v28, v16
	v_mov_b32_e32 v29, v16
	v_mov_b32_e32 v30, v16
	v_mov_b32_e32 v31, v16
	v_mov_b32_e32 v0, v16
	v_mov_b32_e32 v1, v16
	v_mov_b32_e32 v2, v16
	v_mov_b32_e32 v3, v16
	v_mov_b32_e32 v4, v16
	v_mov_b32_e32 v5, v16
	v_mov_b32_e32 v6, v16
	v_mov_b32_e32 v7, v16
	v_mov_b32_e32 v8, v16
	v_mov_b32_e32 v9, v16
	v_mov_b32_e32 v10, v16
	v_mov_b32_e32 v11, v16
	v_mov_b32_e32 v12, v16
	v_mov_b32_e32 v13, v16
	v_mov_b32_e32 v14, v16
	s_waitcnt vmcnt(0)
	v_fma_f32 v32, v15, s25, 0
	v_mul_f32_e32 v134, 0x3fb8aa3b, v15
	v_mov_b32_e32 v33, v32
	v_mov_b32_e32 v34, v32
	v_mov_b32_e32 v35, v32
	v_mov_b32_e32 v36, v32
	v_mov_b32_e32 v37, v32
	v_mov_b32_e32 v38, v32
	v_mov_b32_e32 v39, v32
	v_mov_b32_e32 v40, v32
	v_mov_b32_e32 v41, v32
	v_mov_b32_e32 v42, v32
	v_mov_b32_e32 v43, v32
	v_mov_b32_e32 v44, v32
	v_mov_b32_e32 v45, v32
	v_mov_b32_e32 v46, v32
	v_mov_b32_e32 v47, v32
	v_mov_b32_e32 v15, v16
	s_branch .LBB0_302

; #define PG8_STAGE(bufoff, gbase, voff) do { _Pragma("unroll") for (int _i = 0; _i < 2; ++_i) \
;         __builtin_amdgcn_global_load_lds((const unsigned*)((const char*)(gbase) + (voff)[_i]), (PG8_LAS unsigned*)(lds + (bufoff) + ldsw + _i * 8192), 16, 0, 0); } while (0)
; #define PG8_LDA(dst, b, h) do { _Pragma("unroll") for (int m = 0; m < 4; ++m) _Pragma("unroll") for (int k = 0; k < 2; ++k) dst[m][k] = *(const PG8_LAS bf16x8*)(lds + PG8_SA(b, h) + aoff + m * 2048 + k * 1024); } while (0)
; #define PG8_LDB(dst, b, h) do { _Pragma("unroll") for (int n = 0; n < 2; ++n) _Pragma("unroll") for (int k = 0; k < 2; ++k) dst[n][k] = *(const PG8_LAS bf16x8*)(lds + PG8_SB(b, h) + boff + n * 2048 + k * 1024); } while (0)
; #define PG8_MMA(ai, bj, At, Bt) do { __builtin_amdgcn_s_setprio(1); _Pragma("unroll") for (int m = 0; m < 4; ++m) _Pragma("unroll") for (int n = 0; n < 2; ++n) _Pragma("unroll") for (int k = 0; k < 2; ++k) \
;         acc[ai][bj][m][n] = __builtin_amdgcn_mfma_f32_16x16x32_bf16(Bt[n][k], At[m][k], acc[ai][bj][m][n], 0, 0, 0); __builtin_amdgcn_s_setprio(0); } while (0)
; #define PG8_WAIT_V(n) asm volatile("s_waitcnt vmcnt(" #n ")" ::: "memory")
; #define PG8_BAR __builtin_amdgcn_s_barrier()
; template <class Epi, class Sched, bool ALIGN_EPI = false, bool SP2 = false>
; __device__ __forceinline__ void gemm_phase(PG8_LAS unsigned char* lds, const Gemm g, const Sched& S, const Epi& E) {
;     ...
;         for (int t = 0; t < nt; t += 2) {
;             const bool last = (t == nt - 2);
;             const char* a1 = cA + (size_t)(t + 1) * kstep;
;             const char* a2 = last ? nA : cA + (size_t)(t + 2) * kstep; const char* b2 = last ? nB : cB + (size_t)(t + 2) * kstep;
;             const char* a3 = a2 + kstep; const char* b3 = b2 + kstep;
;             if (last && has_next) S.a_ready(nxt);
;             if constexpr (SP2) {
;             PG8_LDB(B0, 0, 0); PG8_LDB(B1, 0, 1); PG8_SCHED; PG8_LDA(At, 0, 0); PG8_STAGE(PG8_SA(1, 1), a1 + hstep, voffA);
;             PG8_WAIT_V(8); PG8_WAIT_L(0); PG8_BAR; PG8_MMA(0, 0, At, B0); PG8_MMA(0, 1, At, B1); PG8_BAR; PG8_SCHED;
;             PG8_LDA(At, 0, 1); PG8_STAGE(PG8_SB(0, 0), b2, voffB); PG8_STAGE(PG8_SB(0, 1), b2 + hstep, voffB); PG8_STAGE(PG8_SA(0, 0), a2, voffA);
;             PG8_WAIT_V(8); PG8_WAIT_L(0); PG8_BAR; PG8_MMA(1, 0, At, B0); PG8_MMA(1, 1, At, B1); PG8_BAR; PG8_SCHED;
.LBB0_482:
	ds_read_b128 v[144:147], v161
	ds_read_b128 v[170:173], v161 offset:1024
	ds_read_b128 v[178:181], v161 offset:2048
	ds_read_b128 v[182:185], v161 offset:3072
	ds_read_b128 v[186:189], v165
	ds_read_b128 v[190:193], v165 offset:1024
	ds_read_b128 v[194:197], v165 offset:2048
	ds_read_b128 v[198:201], v165 offset:3072
	s_add_u32 s44, s42, 0xfffc0080
	s_addc_u32 s45, s43, -1
	s_cmp_eq_u32 s59, 12
	s_cselect_b32 s47, s19, s45
	s_cselect_b32 s46, s55, s44
	s_cselect_b32 s45, s17, s58
	s_cselect_b32 s44, s56, s57
	v_lshl_add_u64 v[150:151], s[42:43], 0, v[138:139]
	s_add_i32 m0, s28, 0xc000
	ds_read_b128 v[202:205], v169
	ds_read_b128 v[206:209], v169 offset:1024
	ds_read_b128 v[210:213], v169 offset:2048
	ds_read_b128 v[214:217], v169 offset:3072
	ds_read_b128 v[218:221], v169 offset:4096
	ds_read_b128 v[222:225], v169 offset:5120
	ds_read_b128 v[226:229], v169 offset:6144
	ds_read_b128 v[232:235], v169 offset:7168
	global_load_lds_dwordx4 v[150:151], off
	v_lshl_add_u64 v[150:151], s[42:43], 0, v[140:141]
	s_add_i32 m0, s28, 0xe000
	s_nop 0
	global_load_lds_dwordx4 v[150:151], off
	s_waitcnt vmcnt(8)
	s_waitcnt lgkmcnt(0)
	s_barrier
	s_setprio 1
	s_waitcnt lgkmcnt(0)
	v_mfma_f32_16x16x32_bf16 v[124:127], v[144:147], v[202:205], v[124:127]
	v_mfma_f32_16x16x32_bf16 v[116:119], v[178:181], v[202:205], v[116:119]
	v_mfma_f32_16x16x32_bf16 v[108:111], v[144:147], v[210:213], v[108:111]
	v_mfma_f32_16x16x32_bf16 v[100:103], v[178:181], v[210:213], v[100:103]
	v_mfma_f32_16x16x32_bf16 v[92:95], v[144:147], v[218:221], v[92:95]
	v_mfma_f32_16x16x32_bf16 v[84:87], v[178:181], v[218:221], v[84:87]
	v_mfma_f32_16x16x32_bf16 v[76:79], v[144:147], v[226:229], v[76:79]
	v_mfma_f32_16x16x32_bf16 v[68:71], v[178:181], v[226:229], v[68:71]
	v_mfma_f32_16x16x32_bf16 v[124:127], v[170:173], v[206:209], v[124:127]
	v_mfma_f32_16x16x32_bf16 v[116:119], v[182:185], v[206:209], v[116:119]
	v_mfma_f32_16x16x32_bf16 v[108:111], v[170:173], v[214:217], v[108:111]
	v_mfma_f32_16x16x32_bf16 v[100:103], v[182:185], v[214:217], v[100:103]
	v_mfma_f32_16x16x32_bf16 v[92:95], v[170:173], v[222:225], v[92:95]
	v_mfma_f32_16x16x32_bf16 v[84:87], v[182:185], v[222:225], v[84:87]
	v_mfma_f32_16x16x32_bf16 v[76:79], v[170:173], v[232:235], v[76:79]
	v_mfma_f32_16x16x32_bf16 v[68:71], v[182:185], v[232:235], v[68:71]
	s_setprio 0
	s_setprio 1
	v_mfma_f32_16x16x32_bf16 v[120:123], v[186:189], v[202:205], v[120:123]
	v_mfma_f32_16x16x32_bf16 v[112:115], v[194:197], v[202:205], v[112:115]
	v_mfma_f32_16x16x32_bf16 v[104:107], v[186:189], v[210:213], v[104:107]
	v_mfma_f32_16x16x32_bf16 v[96:99], v[194:197], v[210:213], v[96:99]
	v_mfma_f32_16x16x32_bf16 v[88:91], v[186:189], v[218:221], v[88:91]
	v_mfma_f32_16x16x32_bf16 v[80:83], v[194:197], v[218:221], v[80:83]
	v_mfma_f32_16x16x32_bf16 v[72:75], v[186:189], v[226:229], v[72:75]
	v_mfma_f32_16x16x32_bf16 v[64:67], v[194:197], v[226:229], v[64:67]
	v_mfma_f32_16x16x32_bf16 v[120:123], v[190:193], v[206:209], v[120:123]
	v_mfma_f32_16x16x32_bf16 v[112:115], v[198:201], v[206:209], v[112:115]
	v_mfma_f32_16x16x32_bf16 v[104:107], v[190:193], v[214:217], v[104:107]
	v_mfma_f32_16x16x32_bf16 v[96:99], v[198:201], v[214:217], v[96:99]
	v_mfma_f32_16x16x32_bf16 v[88:91], v[190:193], v[222:225], v[88:91]
	v_mfma_f32_16x16x32_bf16 v[80:83], v[198:201], v[222:225], v[80:83]
	v_mfma_f32_16x16x32_bf16 v[72:75], v[190:193], v[232:235], v[72:75]
	v_mfma_f32_16x16x32_bf16 v[64:67], v[198:201], v[232:235], v[64:67]
	s_setprio 0
	s_barrier
	s_add_i32 s60, s51, s25
	v_lshl_add_u64 v[150:151], s[44:45], 0, v[130:131]
	s_mov_b32 m0, s60
	ds_read_b128 v[202:205], v169 offset:16384
	ds_read_b128 v[206:209], v169 offset:17408
	ds_read_b128 v[210:213], v169 offset:18432
	ds_read_b128 v[214:217], v169 offset:19456
	ds_read_b128 v[218:221], v169 offset:20480
	ds_read_b128 v[222:225], v169 offset:21504
	ds_read_b128 v[226:229], v169 offset:22528
	ds_read_b128 v[232:235], v169 offset:23552
	global_load_lds_dwordx4 v[150:151], off
	s_add_i32 m0, s60, 0x2000
	s_add_u32 s60, s44, 0x40000
	v_lshl_add_u64 v[154:155], s[44:45], 0, v[134:135]
	s_addc_u32 s61, s45, 0
	s_add_i32 s62, s52, s25
	global_load_lds_dwordx4 v[154:155], off
	v_lshl_add_u64 v[158:159], s[60:61], 0, v[130:131]
	s_mov_b32 m0, s62
	v_lshl_add_u64 v[162:163], s[46:47], 0, v[132:133]
	global_load_lds_dwordx4 v[158:159], off
	v_lshl_add_u64 v[158:159], s[60:61], 0, v[134:135]
	s_add_i32 m0, s62, 0x2000
	s_nop 0
	global_load_lds_dwordx4 v[158:159], off
	v_lshl_add_u64 v[158:159], s[46:47], 0, v[128:129]
	s_mov_b32 m0, s28
	s_nop 0
	global_load_lds_dwordx4 v[158:159], off
	s_mov_b32 m0, s29
	s_nop 0
	global_load_lds_dwordx4 v[162:163], off
	s_cmp_lg_i32 s59, -2
	s_cbranch_scc1 .Lrsa_a
	v_lshrrev_b32_e32 v250, 6, v230
	v_lshlrev_b32_e32 v250, 11, v250
	v_and_b32_e32 v251, 63, v230
	v_lshl_or_b32 v250, v251, 4, v250
	v_lshl_add_u32 v250, s40, 14, v250
	v_readfirstlane_b32 s98, v230
	s_lshr_b32 s98, s98, 6
	s_lshl_b32 s98, s98, 11
	s_add_i32 m0, s98, 0x20000
	s_add_u32 s100, s70, 0x3f000000
	s_addc_u32 s101, s71, 0
	global_load_lds_dwordx4 v250, s[100:101]
	global_load_lds_dwordx4 v250, s[100:101] offset:1024
	s_waitcnt vmcnt(10)
	s_branch .Lrsa_b
; #define PG8_STAGE(bufoff, gbase, voff) do { _Pragma("unroll") for (int _i = 0; _i < 2; ++_i) \
;         __builtin_amdgcn_global_load_lds((const unsigned*)((const char*)(gbase) + (voff)[_i]), (PG8_LAS unsigned*)(lds + (bufoff) + ldsw + _i * 8192), 16, 0, 0); } while (0)
; #define PG8_LDA(dst, b, h) do { _Pragma("unroll") for (int m = 0; m < 4; ++m) _Pragma("unroll") for (int k = 0; k < 2; ++k) dst[m][k] = *(const PG8_LAS bf16x8*)(lds + PG8_SA(b, h) + aoff + m * 2048 + k * 1024); } while (0)
; #define PG8_LDB(dst, b, h) do { _Pragma("unroll") for (int n = 0; n < 2; ++n) _Pragma("unroll") for (int k = 0; k < 2; ++k) dst[n][k] = *(const PG8_LAS bf16x8*)(lds + PG8_SB(b, h) + boff + n * 2048 + k * 1024); } while (0)
; #define PG8_MMA(ai, bj, At, Bt) do { __builtin_amdgcn_s_setprio(1); _Pragma("unroll") for (int m = 0; m < 4; ++m) _Pragma("unroll") for (int n = 0; n < 2; ++n) _Pragma("unroll") for (int k = 0; k < 2; ++k) \
;         acc[ai][bj][m][n] = __builtin_amdgcn_mfma_f32_16x16x32_bf16(Bt[n][k], At[m][k], acc[ai][bj][m][n], 0, 0, 0); __builtin_amdgcn_s_setprio(0); } while (0)
; #define PG8_WAIT_V(n) asm volatile("s_waitcnt vmcnt(" #n ")" ::: "memory")
; #define PG8_WAIT_L(n) asm volatile("s_waitcnt lgkmcnt(" #n ")" ::: "memory")
; #define PG8_BAR __builtin_amdgcn_s_barrier()
; #define PG8_SCHED __builtin_amdgcn_sched_barrier(0)
; template <class Epi, class Sched, bool ALIGN_EPI = false, bool SP2 = false>
; __device__ __forceinline__ void gemm_phase(PG8_LAS unsigned char* lds, const Gemm g, const Sched& S, const Epi& E) {
;     ...
;             PG8_WAIT_V(8); PG8_WAIT_L(0); PG8_BAR; PG8_MMA(1, 0, At, B0); PG8_MMA(1, 1, At, B1); PG8_BAR; PG8_SCHED;
;             PG8_LDB(B0, 1, 0); PG8_LDB(B1, 1, 1); PG8_SCHED; PG8_LDA(At, 1, 0); PG8_STAGE(PG8_SA(0, 1), a2 + hstep, voffA);
;             PG8_WAIT_V(8); PG8_WAIT_L(0); PG8_BAR; PG8_MMA(0, 0, At, B0); PG8_MMA(0, 1, At, B1); PG8_BAR; PG8_SCHED;
;             PG8_LDA(At, 1, 1); PG8_STAGE(PG8_SB(1, 0), b3, voffB); PG8_STAGE(PG8_SB(1, 1), b3 + hstep, voffB); PG8_STAGE(PG8_SA(1, 0), a3, voffA);
.Lrsa_a:
	s_waitcnt vmcnt(8)
.Lrsa_b:
	s_waitcnt lgkmcnt(0)
	s_barrier
	s_setprio 1
	s_waitcnt lgkmcnt(0)
	v_mfma_f32_16x16x32_bf16 v[60:63], v[144:147], v[202:205], v[60:63]
	v_mfma_f32_16x16x32_bf16 v[52:55], v[178:181], v[202:205], v[52:55]
	v_mfma_f32_16x16x32_bf16 v[44:47], v[144:147], v[210:213], v[44:47]
	v_mfma_f32_16x16x32_bf16 v[36:39], v[178:181], v[210:213], v[36:39]
	v_mfma_f32_16x16x32_bf16 v[28:31], v[144:147], v[218:221], v[28:31]
	v_mfma_f32_16x16x32_bf16 v[20:23], v[178:181], v[218:221], v[20:23]
	v_mfma_f32_16x16x32_bf16 v[12:15], v[144:147], v[226:229], v[12:15]
	v_mfma_f32_16x16x32_bf16 v[4:7], v[178:181], v[226:229], v[4:7]
	v_mfma_f32_16x16x32_bf16 v[60:63], v[170:173], v[206:209], v[60:63]
	v_mfma_f32_16x16x32_bf16 v[52:55], v[182:185], v[206:209], v[52:55]
	v_mfma_f32_16x16x32_bf16 v[44:47], v[170:173], v[214:217], v[44:47]
	v_mfma_f32_16x16x32_bf16 v[36:39], v[182:185], v[214:217], v[36:39]
	v_mfma_f32_16x16x32_bf16 v[28:31], v[170:173], v[222:225], v[28:31]
	v_mfma_f32_16x16x32_bf16 v[20:23], v[182:185], v[222:225], v[20:23]
	v_mfma_f32_16x16x32_bf16 v[12:15], v[170:173], v[232:235], v[12:15]
	v_mfma_f32_16x16x32_bf16 v[4:7], v[182:185], v[232:235], v[4:7]
	s_setprio 0
	s_setprio 1
	v_mfma_f32_16x16x32_bf16 v[56:59], v[186:189], v[202:205], v[56:59]
	v_mfma_f32_16x16x32_bf16 v[48:51], v[194:197], v[202:205], v[48:51]
	v_mfma_f32_16x16x32_bf16 v[40:43], v[186:189], v[210:213], v[40:43]
	v_mfma_f32_16x16x32_bf16 v[32:35], v[194:197], v[210:213], v[32:35]
	v_mfma_f32_16x16x32_bf16 v[24:27], v[186:189], v[218:221], v[24:27]
	v_mfma_f32_16x16x32_bf16 v[16:19], v[194:197], v[218:221], v[16:19]
	v_mfma_f32_16x16x32_bf16 v[8:11], v[186:189], v[226:229], v[8:11]
	v_mfma_f32_16x16x32_bf16 v[0:3], v[194:197], v[226:229], v[0:3]
	v_mfma_f32_16x16x32_bf16 v[56:59], v[190:193], v[206:209], v[56:59]
	v_mfma_f32_16x16x32_bf16 v[48:51], v[198:201], v[206:209], v[48:51]
	v_mfma_f32_16x16x32_bf16 v[40:43], v[190:193], v[214:217], v[40:43]
	v_mfma_f32_16x16x32_bf16 v[32:35], v[198:201], v[214:217], v[32:35]
	v_mfma_f32_16x16x32_bf16 v[24:27], v[190:193], v[222:225], v[24:27]
	v_mfma_f32_16x16x32_bf16 v[16:19], v[198:201], v[222:225], v[16:19]
	v_mfma_f32_16x16x32_bf16 v[8:11], v[190:193], v[232:235], v[8:11]
	v_mfma_f32_16x16x32_bf16 v[0:3], v[198:201], v[232:235], v[0:3]
	s_setprio 0
	s_barrier
	s_add_i32 s60, 0, 0x18000
	v_add_u32_e32 v148, s60, v153
	s_add_i32 s61, 0, 0x1c000
	ds_read_b128 v[144:147], v148
	ds_read_b128 v[170:173], v148 offset:1024
	ds_read_b128 v[178:181], v148 offset:2048
	ds_read_b128 v[182:185], v148 offset:3072
	v_add_u32_e32 v148, s61, v153
	ds_read_b128 v[186:189], v148
	ds_read_b128 v[190:193], v148 offset:1024
	ds_read_b128 v[194:197], v148 offset:2048
	ds_read_b128 v[198:201], v148 offset:3072
	s_add_u32 s46, s46, 0x40000
	s_addc_u32 s47, s47, 0
	s_mov_b32 m0, s30
	v_lshl_add_u64 v[166:167], s[46:47], 0, v[128:129]
	ds_read_b128 v[202:205], v169 offset:32768
	ds_read_b128 v[206:209], v169 offset:33792
	ds_read_b128 v[210:213], v169 offset:34816
	ds_read_b128 v[214:217], v169 offset:35840
	ds_read_b128 v[218:221], v169 offset:36864
	ds_read_b128 v[222:225], v169 offset:37888
	ds_read_b128 v[226:229], v169 offset:38912
	ds_read_b128 v[232:235], v169 offset:39936
	global_load_lds_dwordx4 v[166:167], off
	v_lshl_add_u64 v[166:167], s[46:47], 0, v[132:133]
	s_mov_b32 m0, s31
	s_nop 0
	global_load_lds_dwordx4 v[166:167], off
	s_cmp_lg_i32 s59, -2
	s_cbranch_scc1 .Lrsa_c
	s_waitcnt vmcnt(10)
	s_branch .Lrsa_d

; #define PG8_STAGE(bufoff, gbase, voff) do { _Pragma("unroll") for (int _i = 0; _i < 2; ++_i) \
;         __builtin_amdgcn_global_load_lds((const unsigned*)((const char*)(gbase) + (voff)[_i]), (PG8_LAS unsigned*)(lds + (bufoff) + ldsw + _i * 8192), 16, 0, 0); } while (0)
; #define PG8_LDA(dst, b, h) do { _Pragma("unroll") for (int m = 0; m < 4; ++m) _Pragma("unroll") for (int k = 0; k < 2; ++k) dst[m][k] = *(const PG8_LAS bf16x8*)(lds + PG8_SA(b, h) + aoff + m * 2048 + k * 1024); } while (0)
; #define PG8_MMA(ai, bj, At, Bt) do { __builtin_amdgcn_s_setprio(1); _Pragma("unroll") for (int m = 0; m < 4; ++m) _Pragma("unroll") for (int n = 0; n < 2; ++n) _Pragma("unroll") for (int k = 0; k < 2; ++k) \
;         acc[ai][bj][m][n] = __builtin_amdgcn_mfma_f32_16x16x32_bf16(Bt[n][k], At[m][k], acc[ai][bj][m][n], 0, 0, 0); __builtin_amdgcn_s_setprio(0); } while (0)
; #define PG8_WAIT_V(n) asm volatile("s_waitcnt vmcnt(" #n ")" ::: "memory")
; #define PG8_WAIT_L(n) asm volatile("s_waitcnt lgkmcnt(" #n ")" ::: "memory")
; #define PG8_BAR __builtin_amdgcn_s_barrier()
; #define PG8_SCHED __builtin_amdgcn_sched_barrier(0)
; template <class Epi, class Sched, bool ALIGN_EPI = false, bool SP2 = false>
; __device__ __forceinline__ void gemm_phase(PG8_LAS unsigned char* lds, const Gemm g, const Sched& S, const Epi& E) {
;     ...
;             PG8_WAIT_V(8); PG8_WAIT_L(0); PG8_BAR; PG8_MMA(0, 0, At, B0); PG8_MMA(0, 1, At, B1); PG8_BAR; PG8_SCHED;
;             PG8_LDA(At, 1, 1); PG8_STAGE(PG8_SB(1, 0), b3, voffB); PG8_STAGE(PG8_SB(1, 1), b3 + hstep, voffB); PG8_STAGE(PG8_SA(1, 0), a3, voffA);
;             PG8_WAIT_V(8); PG8_WAIT_L(0); PG8_BAR; PG8_MMA(1, 0, At, B0); PG8_MMA(1, 1, At, B1); PG8_BAR; PG8_SCHED;
;     ...
;         if constexpr (ALIGN_EPI) { if (wr == 0) PG8_BAR; }
.Lrsa_d:
	s_waitcnt lgkmcnt(0)
	s_barrier
	s_setprio 1
	s_waitcnt lgkmcnt(0)
	v_mfma_f32_16x16x32_bf16 v[124:127], v[144:147], v[202:205], v[124:127]
	v_mfma_f32_16x16x32_bf16 v[116:119], v[178:181], v[202:205], v[116:119]
	v_mfma_f32_16x16x32_bf16 v[108:111], v[144:147], v[210:213], v[108:111]
	v_mfma_f32_16x16x32_bf16 v[100:103], v[178:181], v[210:213], v[100:103]
	v_mfma_f32_16x16x32_bf16 v[92:95], v[144:147], v[218:221], v[92:95]
	v_mfma_f32_16x16x32_bf16 v[84:87], v[178:181], v[218:221], v[84:87]
	v_mfma_f32_16x16x32_bf16 v[76:79], v[144:147], v[226:229], v[76:79]
	v_mfma_f32_16x16x32_bf16 v[68:71], v[178:181], v[226:229], v[68:71]
	v_mfma_f32_16x16x32_bf16 v[124:127], v[170:173], v[206:209], v[124:127]
	v_mfma_f32_16x16x32_bf16 v[116:119], v[182:185], v[206:209], v[116:119]
	v_mfma_f32_16x16x32_bf16 v[108:111], v[170:173], v[214:217], v[108:111]
	v_mfma_f32_16x16x32_bf16 v[100:103], v[182:185], v[214:217], v[100:103]
	v_mfma_f32_16x16x32_bf16 v[92:95], v[170:173], v[222:225], v[92:95]
	v_mfma_f32_16x16x32_bf16 v[84:87], v[182:185], v[222:225], v[84:87]
	v_mfma_f32_16x16x32_bf16 v[76:79], v[170:173], v[232:235], v[76:79]
	v_mfma_f32_16x16x32_bf16 v[68:71], v[182:185], v[232:235], v[68:71]
	s_setprio 0
	s_setprio 1
	v_mfma_f32_16x16x32_bf16 v[120:123], v[186:189], v[202:205], v[120:123]
	v_mfma_f32_16x16x32_bf16 v[112:115], v[194:197], v[202:205], v[112:115]
	v_mfma_f32_16x16x32_bf16 v[104:107], v[186:189], v[210:213], v[104:107]
	v_mfma_f32_16x16x32_bf16 v[96:99], v[194:197], v[210:213], v[96:99]
	v_mfma_f32_16x16x32_bf16 v[88:91], v[186:189], v[218:221], v[88:91]
	v_mfma_f32_16x16x32_bf16 v[80:83], v[194:197], v[218:221], v[80:83]
	v_mfma_f32_16x16x32_bf16 v[72:75], v[186:189], v[226:229], v[72:75]
	v_mfma_f32_16x16x32_bf16 v[64:67], v[194:197], v[226:229], v[64:67]
	v_mfma_f32_16x16x32_bf16 v[120:123], v[190:193], v[206:209], v[120:123]
	v_mfma_f32_16x16x32_bf16 v[112:115], v[198:201], v[206:209], v[112:115]
	v_mfma_f32_16x16x32_bf16 v[104:107], v[190:193], v[214:217], v[104:107]
	v_mfma_f32_16x16x32_bf16 v[96:99], v[198:201], v[214:217], v[96:99]
	v_mfma_f32_16x16x32_bf16 v[88:91], v[190:193], v[222:225], v[88:91]
	v_mfma_f32_16x16x32_bf16 v[80:83], v[198:201], v[222:225], v[80:83]
	v_mfma_f32_16x16x32_bf16 v[72:75], v[190:193], v[232:235], v[72:75]
	v_mfma_f32_16x16x32_bf16 v[64:67], v[198:201], v[232:235], v[64:67]
	s_setprio 0
	s_barrier
	s_add_i32 s46, s60, s25
	v_lshl_add_u64 v[150:151], v[150:151], 0, s[8:9]
	s_mov_b32 m0, s46
	ds_read_b128 v[202:205], v169 offset:49152
	ds_read_b128 v[206:209], v169 offset:50176
	ds_read_b128 v[210:213], v169 offset:51200
	ds_read_b128 v[214:217], v169 offset:52224
	ds_read_b128 v[218:221], v169 offset:53248
	ds_read_b128 v[222:225], v169 offset:54272
	ds_read_b128 v[226:229], v169 offset:55296
	ds_read_b128 v[232:235], v169 offset:56320
	global_load_lds_dwordx4 v[150:151], off
	s_add_i32 m0, s46, 0x2000
	s_add_u32 s44, s44, 0x40080
	v_lshl_add_u64 v[150:151], v[154:155], 0, s[8:9]
	s_addc_u32 s45, s45, 0
	s_add_i32 s46, s61, s25
	global_load_lds_dwordx4 v[150:151], off
	v_lshl_add_u64 v[150:151], s[44:45], 0, v[130:131]
	s_mov_b32 m0, s46
	s_nop 0
	global_load_lds_dwordx4 v[150:151], off
	v_lshl_add_u64 v[150:151], s[44:45], 0, v[134:135]
	s_add_i32 m0, s46, 0x2000
	s_nop 0
	global_load_lds_dwordx4 v[150:151], off
	v_lshl_add_u64 v[150:151], v[158:159], 0, s[8:9]
	s_mov_b32 m0, s48
	s_nop 0
	global_load_lds_dwordx4 v[150:151], off
	v_lshl_add_u64 v[150:151], v[162:163], 0, s[8:9]
	s_mov_b32 m0, s49
	s_nop 0
	global_load_lds_dwordx4 v[150:151], off
	s_waitcnt vmcnt(8)
	s_waitcnt lgkmcnt(0)
	s_barrier
	s_setprio 1
	s_waitcnt lgkmcnt(0)
	v_mfma_f32_16x16x32_bf16 v[60:63], v[144:147], v[202:205], v[60:63]
	v_mfma_f32_16x16x32_bf16 v[52:55], v[178:181], v[202:205], v[52:55]
	v_mfma_f32_16x16x32_bf16 v[44:47], v[144:147], v[210:213], v[44:47]
	v_mfma_f32_16x16x32_bf16 v[36:39], v[178:181], v[210:213], v[36:39]
	v_mfma_f32_16x16x32_bf16 v[28:31], v[144:147], v[218:221], v[28:31]
	v_mfma_f32_16x16x32_bf16 v[20:23], v[178:181], v[218:221], v[20:23]
	v_mfma_f32_16x16x32_bf16 v[12:15], v[144:147], v[226:229], v[12:15]
	v_mfma_f32_16x16x32_bf16 v[4:7], v[178:181], v[226:229], v[4:7]
	v_mfma_f32_16x16x32_bf16 v[60:63], v[170:173], v[206:209], v[60:63]
	v_mfma_f32_16x16x32_bf16 v[52:55], v[182:185], v[206:209], v[52:55]
	v_mfma_f32_16x16x32_bf16 v[44:47], v[170:173], v[214:217], v[44:47]
	v_mfma_f32_16x16x32_bf16 v[36:39], v[182:185], v[214:217], v[36:39]
	v_mfma_f32_16x16x32_bf16 v[28:31], v[170:173], v[222:225], v[28:31]
	v_mfma_f32_16x16x32_bf16 v[20:23], v[182:185], v[222:225], v[20:23]
	v_mfma_f32_16x16x32_bf16 v[12:15], v[170:173], v[232:235], v[12:15]
	v_mfma_f32_16x16x32_bf16 v[4:7], v[182:185], v[232:235], v[4:7]
	s_setprio 0
	s_setprio 1
	v_mfma_f32_16x16x32_bf16 v[56:59], v[186:189], v[202:205], v[56:59]
	v_mfma_f32_16x16x32_bf16 v[48:51], v[194:197], v[202:205], v[48:51]
	v_mfma_f32_16x16x32_bf16 v[40:43], v[186:189], v[210:213], v[40:43]
	v_mfma_f32_16x16x32_bf16 v[32:35], v[194:197], v[210:213], v[32:35]
	v_mfma_f32_16x16x32_bf16 v[24:27], v[186:189], v[218:221], v[24:27]
	v_mfma_f32_16x16x32_bf16 v[16:19], v[194:197], v[218:221], v[16:19]
	v_mfma_f32_16x16x32_bf16 v[8:11], v[186:189], v[226:229], v[8:11]
	v_mfma_f32_16x16x32_bf16 v[0:3], v[194:197], v[226:229], v[0:3]
	v_mfma_f32_16x16x32_bf16 v[56:59], v[190:193], v[206:209], v[56:59]
	v_mfma_f32_16x16x32_bf16 v[48:51], v[198:201], v[206:209], v[48:51]
	v_mfma_f32_16x16x32_bf16 v[40:43], v[190:193], v[214:217], v[40:43]
	v_mfma_f32_16x16x32_bf16 v[32:35], v[198:201], v[214:217], v[32:35]
	v_mfma_f32_16x16x32_bf16 v[24:27], v[190:193], v[222:225], v[24:27]
	v_mfma_f32_16x16x32_bf16 v[16:19], v[198:201], v[222:225], v[16:19]
	v_mfma_f32_16x16x32_bf16 v[8:11], v[190:193], v[232:235], v[8:11]
	v_mfma_f32_16x16x32_bf16 v[0:3], v[198:201], v[232:235], v[0:3]
	s_setprio 0
	s_barrier
	s_add_i32 s59, s59, 2
	s_add_u32 s42, s42, 0x100
	s_addc_u32 s43, s43, 0
	s_add_u32 s57, s57, 0x100
	s_addc_u32 s58, s58, 0
	s_cmp_gt_u32 s59, 13
	s_cbranch_scc0 .LBB0_482
	s_and_b64 vcc, exec, s[12:13]
	s_cbranch_vccz .LBB0_485
	s_barrier
; __device__ __forceinline__ float fast_sigmoid(float x) { return __builtin_amdgcn_rcpf(1.0f + __expf(-x)); }
; __device__ __forceinline__ void rows_rstd(const float* ssq, int row0, int fq, float (&rs)[2][4]) {
;     f32x4 pr[2][4];
; #pragma unroll
;     for (int ai = 0; ai < 2; ++ai)
; #pragma unroll
;         for (int m = 0; m < 4; ++m) pr[ai][m] = *(const f32x4*)(ssq + (size_t)(row0 + ai * HALF + m * 16) * 16 + 4 * fq);
; #pragma unroll
;     for (int ai = 0; ai < 2; ++ai)
; #pragma unroll
;         for (int m = 0; m < 4; ++m) { float t = (pr[ai][m][0] + pr[ai][m][1]) + (pr[ai][m][2] + pr[ai][m][3]); t += __shfl_xor(t, 16); t += __shfl_xor(t, 32); rs[ai][m] = __builtin_amdgcn_rsqf(t * (1.0f / 1024.0f) + 1e-6f); }
;     __device__ __forceinline__ void operator()(const f32x4 (&acc)[2][2][4][2], const Unit& u, int wr, int wc, int fr, int fq) const {
;     ...
;         float rsv[2][4]; rows_rstd(ssq, u.pm * BM + wr * 64 + fr, fq, rsv);
; #pragma unroll
;         for (int ai = 0; ai < 2; ++ai)
; #pragma unroll
;             for (int m = 0; m < 4; ++m) {
;                 const int row = u.pm * BM + ai * HALF + wr * 64 + m * 16 + fr;
;                 const float rs = rsv[ai][m];
;                 float h[8];
; #pragma unroll
;                 for (int n = 0; n < 2; ++n)
; #pragma unroll
;                     for (int i = 0; i < 4; ++i) { const float g = acc[ai][0][m][n][i] * rs, up = acc[ai][1][m][n][i] * rs; h[4 * n + i] = g * up * fast_sigmoid(g); }
.LBB0_485:
	v_mbcnt_lo_u32_b32 v252, -1, 0
	v_mbcnt_hi_u32_b32 v252, -1, v252
	v_and_b32_e32 v252, 48, v252
	v_lshl_add_u32 v252, v149, 6, v252
	v_add_u32_e32 v252, 0x20000, v252
	v_lshl_add_u32 v170, s40, 8, v149
	v_ashrrev_i32_e32 v171, 31, v170
	v_or_b32_e32 v166, 16, v170
	v_lshlrev_b64 v[144:145], 6, v[170:171]
	v_ashrrev_i32_e32 v167, 31, v166
	v_or_b32_e32 v162, 32, v170
	v_lshl_add_u64 v[144:145], v[136:137], 0, v[144:145]
	v_lshlrev_b64 v[146:147], 6, v[166:167]
	v_ashrrev_i32_e32 v163, 31, v162
	v_or_b32_e32 v158, 48, v170
	v_lshl_add_u64 v[146:147], v[136:137], 0, v[146:147]
	ds_read_b128 v[178:181], v252 offset:0
	ds_read_b128 v[182:185], v252 offset:1024
	v_lshlrev_b64 v[144:145], 6, v[162:163]
	v_ashrrev_i32_e32 v159, 31, v158
	v_add_u32_e32 v154, 0x80, v170
	v_lshl_add_u64 v[144:145], v[136:137], 0, v[144:145]
	v_lshlrev_b64 v[146:147], 6, v[158:159]
	v_ashrrev_i32_e32 v155, 31, v154
	v_lshl_add_u64 v[146:147], v[136:137], 0, v[146:147]
	ds_read_b128 v[186:189], v252 offset:2048
	ds_read_b128 v[190:193], v252 offset:3072
	v_lshlrev_b64 v[144:145], 6, v[154:155]
	v_lshl_add_u64 v[144:145], v[136:137], 0, v[144:145]
	ds_read_b128 v[194:197], v252 offset:8192
	v_add_u32_e32 v150, 0x90, v170
	v_ashrrev_i32_e32 v151, 31, v150
	v_lshlrev_b64 v[144:145], 6, v[150:151]
	v_add_u32_e32 v146, 0xa0, v170
	v_lshl_add_u64 v[144:145], v[136:137], 0, v[144:145]
	v_ashrrev_i32_e32 v147, 31, v146
	ds_read_b128 v[198:201], v252 offset:9216
	v_lshlrev_b64 v[144:145], 6, v[146:147]
	v_lshl_add_u64 v[144:145], v[136:137], 0, v[144:145]
	ds_read_b128 v[202:205], v252 offset:10240
	v_add_u32_e32 v144, 0xb0, v170
	v_ashrrev_i32_e32 v145, 31, v144
	v_lshlrev_b64 v[206:207], 6, v[144:145]
	v_lshl_add_u64 v[206:207], v[136:137], 0, v[206:207]
	ds_read_b128 v[206:209], v252 offset:11264
	v_and_b32_e32 v147, 64, v175
	v_xor_b32_e32 v145, 16, v175
	v_add_u32_e32 v147, 64, v147
	v_xor_b32_e32 v148, 32, v175
	v_cmp_lt_i32_e32 vcc, v145, v147
	v_lshl_or_b32 v172, s54, 7, v157
	v_ashrrev_i32_e32 v173, 31, v172
	v_cndmask_b32_e32 v145, v175, v145, vcc
	v_cmp_lt_i32_e32 vcc, v148, v147
	v_lshlrev_b32_e32 v145, 2, v145
	s_waitcnt lgkmcnt(0)
	v_mov_b32_e32 v210, v179
	v_mov_b32_e32 v211, v180
	v_mov_b32_e32 v179, v181
	v_pk_add_f32 v[178:179], v[210:211], v[178:179]
	v_mov_b32_e32 v180, v183
	v_mov_b32_e32 v181, v184
	v_mov_b32_e32 v183, v185
	v_cndmask_b32_e32 v147, v175, v148, vcc
	v_mov_b32_e32 v184, v187
	v_mov_b32_e32 v185, v188
	v_mov_b32_e32 v187, v189
	v_mov_b32_e32 v188, v191
	v_mov_b32_e32 v189, v192
	v_mov_b32_e32 v191, v193
	v_add_f32_e32 v148, v178, v179
	v_pk_add_f32 v[178:179], v[180:181], v[182:183]
	v_pk_add_f32 v[180:181], v[184:185], v[186:187]
	v_pk_add_f32 v[182:183], v[188:189], v[190:191]
	v_mov_b32_e32 v192, v195
	v_mov_b32_e32 v193, v196
	v_mov_b32_e32 v195, v197
	ds_bpermute_b32 v151, v145, v148
	v_add_f32_e32 v152, v178, v179
	v_add_f32_e32 v155, v180, v181
	v_add_f32_e32 v156, v182, v183
	v_pk_add_f32 v[184:185], v[192:193], v[194:195]
	ds_bpermute_b32 v160, v145, v152
	ds_bpermute_b32 v163, v145, v155
	ds_bpermute_b32 v164, v145, v156
	v_add_f32_e32 v159, v184, v185
	ds_bpermute_b32 v167, v145, v159
	v_lshlrev_b32_e32 v147, 2, v147
	s_waitcnt lgkmcnt(4)
	v_add_f32_e32 v148, v148, v151
	ds_bpermute_b32 v151, v147, v148
	s_waitcnt lgkmcnt(4)
	v_add_f32_e32 v152, v152, v160
	s_waitcnt lgkmcnt(3)
	v_add_f32_e32 v155, v155, v163
	s_waitcnt lgkmcnt(2)
	v_add_f32_e32 v156, v156, v164
	ds_bpermute_b32 v160, v147, v152
	ds_bpermute_b32 v163, v147, v155
	ds_bpermute_b32 v164, v147, v156
	s_waitcnt lgkmcnt(4)
	v_add_f32_e32 v159, v159, v167
	ds_bpermute_b32 v167, v147, v159
	s_waitcnt lgkmcnt(4)
	v_add_f32_e32 v148, v148, v151
	v_fmamk_f32 v148, v148, 0x3a800000, v176
	s_waitcnt lgkmcnt(3)
	v_add_f32_e32 v151, v152, v160
	s_waitcnt lgkmcnt(2)
	v_add_f32_e32 v152, v155, v163
	s_waitcnt lgkmcnt(1)
	v_add_f32_e32 v155, v156, v164
	v_mov_b32_e32 v180, v199
	v_mov_b32_e32 v181, v200
	v_mov_b32_e32 v199, v201
	v_rsq_f32_e32 v178, v148
	v_fmamk_f32 v148, v151, 0x3a800000, v176
	v_fmamk_f32 v151, v152, 0x3a800000, v176
	v_fmamk_f32 v152, v155, 0x3a800000, v176
	v_pk_add_f32 v[180:181], v[180:181], v[198:199]
	v_rsq_f32_e32 v174, v148
	v_add_f32_e32 v148, v180, v181
	v_rsq_f32_e32 v164, v152
	s_waitcnt lgkmcnt(0)
	v_add_f32_e32 v152, v159, v167
	v_mov_b32_e32 v180, v203
	v_mov_b32_e32 v181, v204
	v_mov_b32_e32 v203, v205
	v_fmamk_f32 v152, v152, 0x3a800000, v176
	v_pk_add_f32 v[180:181], v[180:181], v[202:203]
	v_rsq_f32_e32 v160, v152
	v_add_f32_e32 v152, v180, v181
	v_mov_b32_e32 v180, v207
	v_mov_b32_e32 v181, v208
	v_mov_b32_e32 v207, v209
	v_pk_add_f32 v[180:181], v[180:181], v[206:207]
	v_rsq_f32_e32 v168, v151
	v_add_f32_e32 v156, v180, v181
	v_mov_b32_e32 v180, v124
	v_mov_b32_e32 v181, v120
	v_pk_mul_f32 v[180:181], v[180:181], v[178:179] op_sel_hi:[1,0]
	ds_bpermute_b32 v151, v145, v148
	v_mul_f32_e32 v120, 0xbfb8aa3b, v180
	v_exp_f32_e32 v124, v120
	v_mov_b32_e32 v120, v125
	v_pk_mul_f32 v[120:121], v[120:121], v[178:179] op_sel_hi:[1,0]
	s_waitcnt lgkmcnt(0)
	v_add_f32_e32 v148, v148, v151
	v_mul_f32_e32 v125, 0xbfb8aa3b, v120
	v_exp_f32_e32 v125, v125
	ds_bpermute_b32 v151, v147, v148
	ds_bpermute_b32 v155, v145, v152
	ds_bpermute_b32 v145, v145, v156
	v_add_f32_e32 v125, 1.0, v125
	v_rcp_f32_e32 v125, v125
	v_mul_f32_e32 v120, v120, v121
	s_waitcnt lgkmcnt(2)
	v_add_f32_e32 v148, v148, v151
	s_waitcnt lgkmcnt(1)
	v_add_f32_e32 v151, v152, v155
	s_waitcnt lgkmcnt(0)
; __device__ __forceinline__ unsigned cvt_pk_bf16(float lo, float hi) { unsigned r; asm volatile("v_cvt_pk_bf16_f32 %0, %1, %2" : "=v"(r) : "v"(lo), "v"(hi)); return r; }
; __device__ __forceinline__ float fast_sigmoid(float x) { return __builtin_amdgcn_rcpf(1.0f + __expf(-x)); }
;     __device__ __forceinline__ void operator()(const f32x4 (&acc)[2][2][4][2], const Unit& u, int wr, int wc, int fr, int fq) const {
;     ...
;         for (int ai = 0; ai < 2; ++ai)
; #pragma unroll
;             for (int m = 0; m < 4; ++m) {
;                 const int row = u.pm * BM + ai * HALF + wr * 64 + m * 16 + fr;
;                 const float rs = rsv[ai][m];
;                 float h[8];
; #pragma unroll
;                 for (int n = 0; n < 2; ++n)
; #pragma unroll
;                     for (int i = 0; i < 4; ++i) { const float g = acc[ai][0][m][n][i] * rs, up = acc[ai][1][m][n][i] * rs; h[4 * n + i] = g * up * fast_sigmoid(g); }
;                 u32x4 w; w.x = cvt_pk_bf16(h[0], h[1]); w.y = cvt_pk_bf16(h[2], h[3]); w.z = cvt_pk_bf16(h[4], h[5]); w.w = cvt_pk_bf16(h[6], h[7]);
;                 *(u32x4*)(H + (size_t)row * 2816 + col0) = w;
	v_add_f32_e32 v145, v156, v145
	v_mul_f32_e32 v125, v120, v125
	v_mov_b32_e32 v120, v126
	v_mov_b32_e32 v121, v122
	ds_bpermute_b32 v152, v147, v151
	ds_bpermute_b32 v147, v147, v145
	v_pk_mul_f32 v[120:121], v[120:121], v[178:179] op_sel_hi:[1,0]
	v_add_f32_e32 v124, 1.0, v124
	v_mul_f32_e32 v122, 0xbfb8aa3b, v120
	v_exp_f32_e32 v126, v122
	v_mov_b32_e32 v122, v127
	v_pk_mul_f32 v[122:123], v[122:123], v[178:179] op_sel_hi:[1,0]
	v_fmamk_f32 v148, v148, 0x3a800000, v176
	v_rcp_f32_e32 v124, v124
	v_mul_f32_e32 v127, 0xbfb8aa3b, v122
	v_rsq_f32_e32 v156, v148
	s_waitcnt lgkmcnt(1)
	v_add_f32_e32 v148, v151, v152
	s_waitcnt lgkmcnt(0)
	v_add_f32_e32 v145, v145, v147
	v_exp_f32_e32 v127, v127
	v_fmamk_f32 v148, v148, 0x3a800000, v176
	v_fmamk_f32 v145, v145, 0x3a800000, v176
	v_rsq_f32_e32 v152, v148
	v_rsq_f32_e32 v148, v145
	v_mul_f32_e32 v145, v180, v181
	v_mul_f32_e32 v124, v145, v124
	v_mul_f32_e32 v145, v120, v121
	v_add_f32_e32 v120, 1.0, v126
	v_rcp_f32_e32 v126, v120
	v_add_f32_e32 v120, 1.0, v127
	v_rcp_f32_e32 v127, v120
	v_mov_b32_e32 v120, v116
	v_mov_b32_e32 v121, v112
	v_pk_mul_f32 v[120:121], v[120:121], v[178:179] op_sel_hi:[1,0]
	v_mul_f32_e32 v116, v122, v123
	v_mul_f32_e32 v112, 0xbfb8aa3b, v120
	v_exp_f32_e32 v112, v112
	v_mul_f32_e32 v122, v116, v127
	v_mul_f32_e32 v120, v120, v121
	v_mul_f32_e32 v126, v145, v126
	v_add_f32_e32 v112, 1.0, v112
	v_rcp_f32_e32 v116, v112
	v_mov_b32_e32 v112, v117
	v_pk_mul_f32 v[112:113], v[112:113], v[178:179] op_sel_hi:[1,0]
	v_mov_b32_e32 v123, v104
	v_mul_f32_e32 v117, 0xbfb8aa3b, v112
	v_exp_f32_e32 v117, v117
	v_mul_f32_e32 v120, v120, v116
	v_mul_f32_e32 v116, v112, v113
	v_mov_b32_e32 v113, v114
	v_add_f32_e32 v112, 1.0, v117
	v_rcp_f32_e32 v117, v112
	v_mov_b32_e32 v112, v118
	v_pk_mul_f32 v[112:113], v[112:113], v[178:179] op_sel_hi:[1,0]
	s_andn2_b64 vcc, exec, s[20:21]
	v_mul_f32_e32 v114, 0xbfb8aa3b, v112
	v_exp_f32_e32 v118, v114
	v_mov_b32_e32 v114, v119
	v_pk_mul_f32 v[114:115], v[114:115], v[178:179] op_sel_hi:[1,0]
	v_mul_f32_e32 v121, v116, v117
	v_mul_f32_e32 v119, 0xbfb8aa3b, v114
	v_exp_f32_e32 v119, v119
	v_add_f32_e32 v116, 1.0, v118
	v_rcp_f32_e32 v116, v116
	v_mul_f32_e32 v112, v112, v113
	v_add_f32_e32 v117, 1.0, v119
	v_rcp_f32_e32 v117, v117
	v_mul_f32_e32 v113, v114, v115
	v_mul_f32_e32 v112, v112, v116
	v_cvt_pk_bf16_f32 v116, v124, v125
	v_mul_f32_e32 v113, v113, v117
	v_cvt_pk_bf16_f32 v117, v126, v122
	v_mov_b32_e32 v122, v108
	v_pk_mul_f32 v[122:123], v[122:123], v[174:175] op_sel_hi:[1,0]
	v_cvt_pk_bf16_f32 v118, v120, v121
	v_cvt_pk_bf16_f32 v119, v112, v113
	v_mov_b64_e32 v[112:113], s[6:7]
	v_mul_f32_e32 v104, 0xbfb8aa3b, v122
	v_exp_f32_e32 v108, v104
	v_mov_b32_e32 v104, v109
	v_pk_mul_f32 v[104:105], v[104:105], v[174:175] op_sel_hi:[1,0]
	v_mad_i64_i32 v[120:121], s[42:43], v170, s53, v[112:113]
	v_mul_f32_e32 v109, 0xbfb8aa3b, v104
	v_exp_f32_e32 v109, v109
	v_mul_f32_e32 v104, v104, v105
	v_mov_b32_e32 v105, v106
	v_add_f32_e32 v108, 1.0, v108
	v_add_f32_e32 v109, 1.0, v109
	v_rcp_f32_e32 v109, v109
	v_rcp_f32_e32 v108, v108
	v_lshlrev_b64 v[114:115], 1, v[172:173]
	v_lshl_add_u64 v[120:121], v[120:121], 0, v[114:115]
	v_mul_f32_e32 v109, v104, v109
	v_mov_b32_e32 v104, v110
	v_pk_mul_f32 v[104:105], v[104:105], v[174:175] op_sel_hi:[1,0]
	global_store_dwordx4 v[120:121], v[116:119], off
	v_mul_f32_e32 v106, 0xbfb8aa3b, v104
	v_exp_f32_e32 v110, v106
	v_mov_b32_e32 v106, v111
	v_pk_mul_f32 v[106:107], v[106:107], v[174:175] op_sel_hi:[1,0]
	v_mul_f32_e32 v116, v122, v123
	v_mul_f32_e32 v111, 0xbfb8aa3b, v106
	v_exp_f32_e32 v111, v111
	v_mul_f32_e32 v108, v116, v108
	v_mul_f32_e32 v116, v104, v105
	v_add_f32_e32 v104, 1.0, v110
	v_rcp_f32_e32 v110, v104
	v_add_f32_e32 v104, 1.0, v111
	v_rcp_f32_e32 v111, v104
	v_mov_b32_e32 v104, v100
	v_mov_b32_e32 v105, v96
	v_pk_mul_f32 v[104:105], v[104:105], v[174:175] op_sel_hi:[1,0]
	v_mul_f32_e32 v106, v106, v107
	v_mul_f32_e32 v96, 0xbfb8aa3b, v104
	v_exp_f32_e32 v96, v96
	v_mul_f32_e32 v104, v104, v105
	v_mul_f32_e32 v100, v116, v110
	v_mul_f32_e32 v106, v106, v111
	v_add_f32_e32 v96, 1.0, v96
	v_rcp_f32_e32 v107, v96
	v_mov_b32_e32 v96, v101
	v_pk_mul_f32 v[96:97], v[96:97], v[174:175] op_sel_hi:[1,0]
	s_mov_b64 s[20:21], -1
	v_mul_f32_e32 v101, 0xbfb8aa3b, v96
	v_exp_f32_e32 v101, v101
	v_mul_f32_e32 v105, v96, v97
	v_mov_b32_e32 v97, v98
	v_mul_f32_e32 v104, v104, v107
	v_add_f32_e32 v96, 1.0, v101
	v_rcp_f32_e32 v101, v96
	v_mov_b32_e32 v96, v102
	v_pk_mul_f32 v[96:97], v[96:97], v[174:175] op_sel_hi:[1,0]
	v_mul_f32_e32 v101, v105, v101
	v_mul_f32_e32 v98, 0xbfb8aa3b, v96
	v_exp_f32_e32 v102, v98
	v_mov_b32_e32 v98, v103
	v_pk_mul_f32 v[98:99], v[98:99], v[174:175] op_sel_hi:[1,0]
	v_mul_f32_e32 v96, v96, v97
	v_mul_f32_e32 v103, 0xbfb8aa3b, v98
	v_exp_f32_e32 v103, v103
	v_add_f32_e32 v102, 1.0, v102
	v_rcp_f32_e32 v102, v102
	v_add_f32_e32 v103, 1.0, v103
	v_rcp_f32_e32 v103, v103
	v_mul_f32_e32 v102, v96, v102
	v_mul_f32_e32 v96, v98, v99
	v_mul_f32_e32 v99, v96, v103
	v_cvt_pk_bf16_f32 v96, v108, v109
	v_cvt_pk_bf16_f32 v97, v100, v106
	v_cvt_pk_bf16_f32 v98, v104, v101
	v_cvt_pk_bf16_f32 v99, v102, v99
	v_mov_b32_e32 v102, v92
	v_mov_b32_e32 v103, v88
	v_pk_mul_f32 v[102:103], v[102:103], v[168:169] op_sel_hi:[1,0]
	v_mad_i64_i32 v[100:101], s[42:43], v166, s53, v[112:113]
	v_mul_f32_e32 v88, 0xbfb8aa3b, v102
	v_exp_f32_e32 v92, v88
	v_mov_b32_e32 v88, v93
	v_pk_mul_f32 v[88:89], v[88:89], v[168:169] op_sel_hi:[1,0]
	v_lshl_add_u64 v[100:101], v[100:101], 0, v[114:115]
	v_mul_f32_e32 v93, 0xbfb8aa3b, v88
	v_exp_f32_e32 v93, v93
	v_mul_f32_e32 v88, v88, v89
	v_mov_b32_e32 v89, v90
; __device__ __forceinline__ unsigned cvt_pk_bf16(float lo, float hi) { unsigned r; asm volatile("v_cvt_pk_bf16_f32 %0, %1, %2" : "=v"(r) : "v"(lo), "v"(hi)); return r; }
; __device__ __forceinline__ float fast_sigmoid(float x) { return __builtin_amdgcn_rcpf(1.0f + __expf(-x)); }
;     __device__ __forceinline__ void operator()(const f32x4 (&acc)[2][2][4][2], const Unit& u, int wr, int wc, int fr, int fq) const {
;     ...
;         for (int ai = 0; ai < 2; ++ai)
; #pragma unroll
;             for (int m = 0; m < 4; ++m) {
;                 const int row = u.pm * BM + ai * HALF + wr * 64 + m * 16 + fr;
;                 const float rs = rsv[ai][m];
;                 float h[8];
; #pragma unroll
;                 for (int n = 0; n < 2; ++n)
; #pragma unroll
;                     for (int i = 0; i < 4; ++i) { const float g = acc[ai][0][m][n][i] * rs, up = acc[ai][1][m][n][i] * rs; h[4 * n + i] = g * up * fast_sigmoid(g); }
;                 u32x4 w; w.x = cvt_pk_bf16(h[0], h[1]); w.y = cvt_pk_bf16(h[2], h[3]); w.z = cvt_pk_bf16(h[4], h[5]); w.w = cvt_pk_bf16(h[6], h[7]);
;                 *(u32x4*)(H + (size_t)row * 2816 + col0) = w;
	v_add_f32_e32 v92, 1.0, v92
	v_add_f32_e32 v93, 1.0, v93
	v_rcp_f32_e32 v93, v93
	v_rcp_f32_e32 v92, v92
	global_store_dwordx4 v[100:101], v[96:99], off
	v_mul_f32_e32 v93, v88, v93
	v_mov_b32_e32 v88, v94
	v_pk_mul_f32 v[88:89], v[88:89], v[168:169] op_sel_hi:[1,0]
	v_mul_f32_e32 v96, v102, v103
	v_mul_f32_e32 v90, 0xbfb8aa3b, v88
	v_exp_f32_e32 v94, v90
	v_mov_b32_e32 v90, v95
	v_pk_mul_f32 v[90:91], v[90:91], v[168:169] op_sel_hi:[1,0]
	v_mul_f32_e32 v92, v96, v92
	v_mul_f32_e32 v95, 0xbfb8aa3b, v90
	v_exp_f32_e32 v95, v95
	v_mul_f32_e32 v96, v88, v89
	v_add_f32_e32 v88, 1.0, v94
	v_rcp_f32_e32 v94, v88
	v_add_f32_e32 v88, 1.0, v95
	v_rcp_f32_e32 v95, v88
	v_mov_b32_e32 v88, v84
	v_mov_b32_e32 v89, v80
	v_pk_mul_f32 v[88:89], v[88:89], v[168:169] op_sel_hi:[1,0]
	v_mul_f32_e32 v90, v90, v91
	v_mul_f32_e32 v80, 0xbfb8aa3b, v88
	v_exp_f32_e32 v80, v80
	v_mul_f32_e32 v88, v88, v89
	v_mul_f32_e32 v84, v96, v94
	v_mul_f32_e32 v90, v90, v95
	v_add_f32_e32 v80, 1.0, v80
	v_rcp_f32_e32 v91, v80
	v_mov_b32_e32 v80, v85
	v_pk_mul_f32 v[80:81], v[80:81], v[168:169] op_sel_hi:[1,0]
	v_mul_f32_e32 v88, v88, v91
	v_mul_f32_e32 v85, 0xbfb8aa3b, v80
	v_exp_f32_e32 v85, v85
	v_mul_f32_e32 v89, v80, v81
	v_mov_b32_e32 v81, v82
	v_add_f32_e32 v80, 1.0, v85
	v_rcp_f32_e32 v85, v80
	v_mov_b32_e32 v80, v86
	v_pk_mul_f32 v[80:81], v[80:81], v[168:169] op_sel_hi:[1,0]
	v_mul_f32_e32 v85, v89, v85
	v_mul_f32_e32 v82, 0xbfb8aa3b, v80
	v_exp_f32_e32 v86, v82
	v_mov_b32_e32 v82, v87
	v_pk_mul_f32 v[82:83], v[82:83], v[168:169] op_sel_hi:[1,0]
	v_mul_f32_e32 v80, v80, v81
	v_mul_f32_e32 v87, 0xbfb8aa3b, v82
	v_exp_f32_e32 v87, v87
	v_add_f32_e32 v86, 1.0, v86
	v_rcp_f32_e32 v86, v86
	v_add_f32_e32 v87, 1.0, v87
	v_rcp_f32_e32 v87, v87
	v_mul_f32_e32 v86, v80, v86
	v_mul_f32_e32 v80, v82, v83
	v_mul_f32_e32 v83, v80, v87
	v_cvt_pk_bf16_f32 v80, v92, v93
	v_cvt_pk_bf16_f32 v81, v84, v90
	v_cvt_pk_bf16_f32 v82, v88, v85
	v_cvt_pk_bf16_f32 v83, v86, v83
	v_mov_b32_e32 v86, v76
	v_mov_b32_e32 v87, v72
	v_pk_mul_f32 v[86:87], v[86:87], v[164:165] op_sel_hi:[1,0]
	v_mad_i64_i32 v[84:85], s[42:43], v162, s53, v[112:113]
	v_mul_f32_e32 v72, 0xbfb8aa3b, v86
	v_exp_f32_e32 v76, v72
	v_mov_b32_e32 v72, v77
	v_pk_mul_f32 v[72:73], v[72:73], v[164:165] op_sel_hi:[1,0]
	v_lshl_add_u64 v[84:85], v[84:85], 0, v[114:115]
	v_mul_f32_e32 v77, 0xbfb8aa3b, v72
	v_exp_f32_e32 v77, v77
	v_mul_f32_e32 v72, v72, v73
	v_mov_b32_e32 v73, v74
	v_add_f32_e32 v76, 1.0, v76
	v_add_f32_e32 v77, 1.0, v77
	v_rcp_f32_e32 v77, v77
	v_rcp_f32_e32 v76, v76
	global_store_dwordx4 v[84:85], v[80:83], off
	v_mul_f32_e32 v77, v72, v77
	v_mov_b32_e32 v72, v78
	v_pk_mul_f32 v[72:73], v[72:73], v[164:165] op_sel_hi:[1,0]
	v_mul_f32_e32 v80, v86, v87
	v_mul_f32_e32 v74, 0xbfb8aa3b, v72
	v_exp_f32_e32 v78, v74
	v_mov_b32_e32 v74, v79
	v_pk_mul_f32 v[74:75], v[74:75], v[164:165] op_sel_hi:[1,0]
	v_mul_f32_e32 v76, v80, v76
	v_mul_f32_e32 v79, 0xbfb8aa3b, v74
	v_exp_f32_e32 v79, v79
	v_mul_f32_e32 v80, v72, v73
	v_add_f32_e32 v72, 1.0, v78
	v_rcp_f32_e32 v78, v72
	v_add_f32_e32 v72, 1.0, v79
	v_rcp_f32_e32 v79, v72
	v_mov_b32_e32 v72, v68
	v_mov_b32_e32 v73, v64
	v_pk_mul_f32 v[72:73], v[72:73], v[164:165] op_sel_hi:[1,0]
	v_mul_f32_e32 v74, v74, v75
	v_mul_f32_e32 v64, 0xbfb8aa3b, v72
	v_exp_f32_e32 v64, v64
	v_mul_f32_e32 v72, v72, v73
	v_mul_f32_e32 v68, v80, v78
	v_mul_f32_e32 v74, v74, v79
	v_add_f32_e32 v64, 1.0, v64
	v_rcp_f32_e32 v75, v64
	v_mov_b32_e32 v64, v69
	v_pk_mul_f32 v[64:65], v[64:65], v[164:165] op_sel_hi:[1,0]
	v_mul_f32_e32 v72, v72, v75
	v_mul_f32_e32 v69, 0xbfb8aa3b, v64
	v_exp_f32_e32 v69, v69
	v_mul_f32_e32 v73, v64, v65
	v_mov_b32_e32 v65, v66
	v_add_f32_e32 v64, 1.0, v69
	v_rcp_f32_e32 v69, v64
	v_mov_b32_e32 v64, v70
	v_pk_mul_f32 v[64:65], v[64:65], v[164:165] op_sel_hi:[1,0]
	v_mul_f32_e32 v69, v73, v69
	v_mul_f32_e32 v66, 0xbfb8aa3b, v64
	v_exp_f32_e32 v70, v66
	v_mov_b32_e32 v66, v71
	v_pk_mul_f32 v[66:67], v[66:67], v[164:165] op_sel_hi:[1,0]
	v_mul_f32_e32 v64, v64, v65
	v_mul_f32_e32 v71, 0xbfb8aa3b, v66
	v_exp_f32_e32 v71, v71
	v_add_f32_e32 v70, 1.0, v70
	v_rcp_f32_e32 v70, v70
	v_add_f32_e32 v71, 1.0, v71
	v_rcp_f32_e32 v71, v71
	v_mul_f32_e32 v70, v64, v70
	v_mul_f32_e32 v64, v66, v67
	v_mul_f32_e32 v67, v64, v71
	v_cvt_pk_bf16_f32 v64, v76, v77
	v_cvt_pk_bf16_f32 v65, v68, v74
	v_cvt_pk_bf16_f32 v66, v72, v69
	v_cvt_pk_bf16_f32 v67, v70, v67
	v_mov_b32_e32 v70, v60
	v_mov_b32_e32 v71, v56
	v_pk_mul_f32 v[70:71], v[70:71], v[160:161] op_sel_hi:[1,0]
	v_mad_i64_i32 v[68:69], s[42:43], v158, s53, v[112:113]
	v_mul_f32_e32 v56, 0xbfb8aa3b, v70
	v_exp_f32_e32 v60, v56
	v_mov_b32_e32 v56, v61
	v_pk_mul_f32 v[56:57], v[56:57], v[160:161] op_sel_hi:[1,0]
	v_lshl_add_u64 v[68:69], v[68:69], 0, v[114:115]
	v_mul_f32_e32 v61, 0xbfb8aa3b, v56
	v_exp_f32_e32 v61, v61
	v_mul_f32_e32 v56, v56, v57
	v_mov_b32_e32 v57, v58
	v_add_f32_e32 v60, 1.0, v60
	v_add_f32_e32 v61, 1.0, v61
	v_rcp_f32_e32 v61, v61
	v_rcp_f32_e32 v60, v60
	global_store_dwordx4 v[68:69], v[64:67], off
	v_mul_f32_e32 v61, v56, v61
	v_mov_b32_e32 v56, v62
	v_pk_mul_f32 v[56:57], v[56:57], v[160:161] op_sel_hi:[1,0]
	v_mul_f32_e32 v64, v70, v71
	v_mul_f32_e32 v58, 0xbfb8aa3b, v56
	v_exp_f32_e32 v62, v58
	v_mov_b32_e32 v58, v63
	v_pk_mul_f32 v[58:59], v[58:59], v[160:161] op_sel_hi:[1,0]
	v_mul_f32_e32 v60, v64, v60
	v_mul_f32_e32 v63, 0xbfb8aa3b, v58
	v_exp_f32_e32 v63, v63
	v_mul_f32_e32 v64, v56, v57
	v_add_f32_e32 v56, 1.0, v62
	v_rcp_f32_e32 v62, v56
	v_add_f32_e32 v56, 1.0, v63
	v_rcp_f32_e32 v63, v56
	v_mov_b32_e32 v56, v52
	v_mov_b32_e32 v57, v48
	v_pk_mul_f32 v[56:57], v[56:57], v[160:161] op_sel_hi:[1,0]
; __device__ __forceinline__ unsigned cvt_pk_bf16(float lo, float hi) { unsigned r; asm volatile("v_cvt_pk_bf16_f32 %0, %1, %2" : "=v"(r) : "v"(lo), "v"(hi)); return r; }
; __device__ __forceinline__ float fast_sigmoid(float x) { return __builtin_amdgcn_rcpf(1.0f + __expf(-x)); }
;     __device__ __forceinline__ void operator()(const f32x4 (&acc)[2][2][4][2], const Unit& u, int wr, int wc, int fr, int fq) const {
;     ...
;         for (int ai = 0; ai < 2; ++ai)
; #pragma unroll
;             for (int m = 0; m < 4; ++m) {
;                 const int row = u.pm * BM + ai * HALF + wr * 64 + m * 16 + fr;
;                 const float rs = rsv[ai][m];
;                 float h[8];
; #pragma unroll
;                 for (int n = 0; n < 2; ++n)
; #pragma unroll
;                     for (int i = 0; i < 4; ++i) { const float g = acc[ai][0][m][n][i] * rs, up = acc[ai][1][m][n][i] * rs; h[4 * n + i] = g * up * fast_sigmoid(g); }
;                 u32x4 w; w.x = cvt_pk_bf16(h[0], h[1]); w.y = cvt_pk_bf16(h[2], h[3]); w.z = cvt_pk_bf16(h[4], h[5]); w.w = cvt_pk_bf16(h[6], h[7]);
;                 *(u32x4*)(H + (size_t)row * 2816 + col0) = w;
	v_mul_f32_e32 v58, v58, v59
	v_mul_f32_e32 v48, 0xbfb8aa3b, v56
	v_exp_f32_e32 v48, v48
	v_mul_f32_e32 v56, v56, v57
	v_mul_f32_e32 v52, v64, v62
	v_mul_f32_e32 v58, v58, v63
	v_add_f32_e32 v48, 1.0, v48
	v_rcp_f32_e32 v59, v48
	v_mov_b32_e32 v48, v53
	v_pk_mul_f32 v[48:49], v[48:49], v[160:161] op_sel_hi:[1,0]
	v_mul_f32_e32 v56, v56, v59
	v_mul_f32_e32 v53, 0xbfb8aa3b, v48
	v_exp_f32_e32 v53, v53
	v_mul_f32_e32 v57, v48, v49
	v_mov_b32_e32 v49, v50
	v_add_f32_e32 v48, 1.0, v53
	v_rcp_f32_e32 v53, v48
	v_mov_b32_e32 v48, v54
	v_pk_mul_f32 v[48:49], v[48:49], v[160:161] op_sel_hi:[1,0]
	v_mul_f32_e32 v53, v57, v53
	v_mul_f32_e32 v50, 0xbfb8aa3b, v48
	v_exp_f32_e32 v54, v50
	v_mov_b32_e32 v50, v55
	v_pk_mul_f32 v[50:51], v[50:51], v[160:161] op_sel_hi:[1,0]
	v_mul_f32_e32 v48, v48, v49
	v_mul_f32_e32 v55, 0xbfb8aa3b, v50
	v_exp_f32_e32 v55, v55
	v_add_f32_e32 v54, 1.0, v54
	v_rcp_f32_e32 v54, v54
	v_add_f32_e32 v55, 1.0, v55
	v_rcp_f32_e32 v55, v55
	v_mul_f32_e32 v54, v48, v54
	v_mul_f32_e32 v48, v50, v51
	v_mul_f32_e32 v51, v48, v55
	v_cvt_pk_bf16_f32 v48, v60, v61
	v_cvt_pk_bf16_f32 v49, v52, v58
	v_cvt_pk_bf16_f32 v50, v56, v53
	v_cvt_pk_bf16_f32 v51, v54, v51
	v_mov_b32_e32 v54, v44
	v_mov_b32_e32 v55, v40
	v_pk_mul_f32 v[54:55], v[54:55], v[156:157] op_sel_hi:[1,0]
	v_mad_i64_i32 v[52:53], s[42:43], v154, s53, v[112:113]
	v_mul_f32_e32 v40, 0xbfb8aa3b, v54
	v_exp_f32_e32 v44, v40
	v_mov_b32_e32 v40, v45
	v_pk_mul_f32 v[40:41], v[40:41], v[156:157] op_sel_hi:[1,0]
	v_lshl_add_u64 v[52:53], v[52:53], 0, v[114:115]
	v_mul_f32_e32 v45, 0xbfb8aa3b, v40
	v_exp_f32_e32 v45, v45
	v_mul_f32_e32 v40, v40, v41
	v_mov_b32_e32 v41, v42
	v_add_f32_e32 v44, 1.0, v44
	v_add_f32_e32 v45, 1.0, v45
	v_rcp_f32_e32 v45, v45
	v_rcp_f32_e32 v44, v44
	global_store_dwordx4 v[52:53], v[48:51], off
	v_mul_f32_e32 v45, v40, v45
	v_mov_b32_e32 v40, v46
	v_pk_mul_f32 v[40:41], v[40:41], v[156:157] op_sel_hi:[1,0]
	v_mul_f32_e32 v48, v54, v55
	v_mul_f32_e32 v42, 0xbfb8aa3b, v40
	v_exp_f32_e32 v46, v42
	v_mov_b32_e32 v42, v47
	v_pk_mul_f32 v[42:43], v[42:43], v[156:157] op_sel_hi:[1,0]
	v_mul_f32_e32 v44, v48, v44
	v_mul_f32_e32 v47, 0xbfb8aa3b, v42
	v_exp_f32_e32 v47, v47
	v_mul_f32_e32 v48, v40, v41
	v_add_f32_e32 v40, 1.0, v46
	v_rcp_f32_e32 v46, v40
	v_add_f32_e32 v40, 1.0, v47
	v_rcp_f32_e32 v47, v40
	v_mov_b32_e32 v40, v36
	v_mov_b32_e32 v41, v32
	v_pk_mul_f32 v[40:41], v[40:41], v[156:157] op_sel_hi:[1,0]
	v_mul_f32_e32 v42, v42, v43
	v_mul_f32_e32 v32, 0xbfb8aa3b, v40
	v_exp_f32_e32 v32, v32
	v_mul_f32_e32 v40, v40, v41
	v_mul_f32_e32 v36, v48, v46
	v_mul_f32_e32 v42, v42, v47
	v_add_f32_e32 v32, 1.0, v32
	v_rcp_f32_e32 v43, v32
	v_mov_b32_e32 v32, v37
	v_pk_mul_f32 v[32:33], v[32:33], v[156:157] op_sel_hi:[1,0]
	v_mul_f32_e32 v40, v40, v43
	v_mul_f32_e32 v37, 0xbfb8aa3b, v32
	v_exp_f32_e32 v37, v37
	v_mul_f32_e32 v41, v32, v33
	v_mov_b32_e32 v33, v34
	v_add_f32_e32 v32, 1.0, v37
	v_rcp_f32_e32 v37, v32
	v_mov_b32_e32 v32, v38
	v_pk_mul_f32 v[32:33], v[32:33], v[156:157] op_sel_hi:[1,0]
	v_mul_f32_e32 v37, v41, v37
	v_mul_f32_e32 v34, 0xbfb8aa3b, v32
	v_exp_f32_e32 v38, v34
	v_mov_b32_e32 v34, v39
	v_pk_mul_f32 v[34:35], v[34:35], v[156:157] op_sel_hi:[1,0]
	v_mul_f32_e32 v32, v32, v33
	v_mul_f32_e32 v39, 0xbfb8aa3b, v34
	v_exp_f32_e32 v39, v39
	v_add_f32_e32 v38, 1.0, v38
	v_rcp_f32_e32 v38, v38
	v_add_f32_e32 v39, 1.0, v39
	v_rcp_f32_e32 v39, v39
	v_mul_f32_e32 v38, v32, v38
	v_mul_f32_e32 v32, v34, v35
	v_mul_f32_e32 v35, v32, v39
	v_cvt_pk_bf16_f32 v32, v44, v45
	v_cvt_pk_bf16_f32 v33, v36, v42
	v_cvt_pk_bf16_f32 v34, v40, v37
	v_cvt_pk_bf16_f32 v35, v38, v35
	v_mov_b32_e32 v38, v28
	v_mov_b32_e32 v39, v24
	v_pk_mul_f32 v[38:39], v[38:39], v[152:153] op_sel_hi:[1,0]
	v_mad_i64_i32 v[36:37], s[42:43], v150, s53, v[112:113]
	v_mul_f32_e32 v24, 0xbfb8aa3b, v38
	v_exp_f32_e32 v28, v24
	v_mov_b32_e32 v24, v29
	v_pk_mul_f32 v[24:25], v[24:25], v[152:153] op_sel_hi:[1,0]
	v_lshl_add_u64 v[36:37], v[36:37], 0, v[114:115]
	v_mul_f32_e32 v29, 0xbfb8aa3b, v24
	v_exp_f32_e32 v29, v29
	v_mul_f32_e32 v24, v24, v25
	v_mov_b32_e32 v25, v26
	v_add_f32_e32 v28, 1.0, v28
	v_add_f32_e32 v29, 1.0, v29
	v_rcp_f32_e32 v29, v29
	v_rcp_f32_e32 v28, v28
	global_store_dwordx4 v[36:37], v[32:35], off
	v_mul_f32_e32 v29, v24, v29
	v_mov_b32_e32 v24, v30
; __device__ __forceinline__ unsigned cvt_pk_bf16(float lo, float hi) { unsigned r; asm volatile("v_cvt_pk_bf16_f32 %0, %1, %2" : "=v"(r) : "v"(lo), "v"(hi)); return r; }
; __device__ __forceinline__ float fast_sigmoid(float x) { return __builtin_amdgcn_rcpf(1.0f + __expf(-x)); }
; #define PG8_BAR __builtin_amdgcn_s_barrier()
;     __device__ __forceinline__ void operator()(const f32x4 (&acc)[2][2][4][2], const Unit& u, int wr, int wc, int fr, int fq) const {
;     ...
;         for (int ai = 0; ai < 2; ++ai)
; #pragma unroll
;             for (int m = 0; m < 4; ++m) {
;                 const int row = u.pm * BM + ai * HALF + wr * 64 + m * 16 + fr;
;                 const float rs = rsv[ai][m];
;                 float h[8];
; #pragma unroll
;                 for (int n = 0; n < 2; ++n)
; #pragma unroll
;                     for (int i = 0; i < 4; ++i) { const float g = acc[ai][0][m][n][i] * rs, up = acc[ai][1][m][n][i] * rs; h[4 * n + i] = g * up * fast_sigmoid(g); }
;                 u32x4 w; w.x = cvt_pk_bf16(h[0], h[1]); w.y = cvt_pk_bf16(h[2], h[3]); w.z = cvt_pk_bf16(h[4], h[5]); w.w = cvt_pk_bf16(h[6], h[7]);
;                 *(u32x4*)(H + (size_t)row * 2816 + col0) = w;
; template <class Epi, class Sched, bool ALIGN_EPI = false, bool SP2 = false>
; __device__ __forceinline__ void gemm_phase(PG8_LAS unsigned char* lds, const Gemm g, const Sched& S, const Epi& E) {
;     ...
;         if constexpr (!Epi::AFTER_DRAIN) { E(acc, cur, wr, wc, fr, fq); S.done(cur); }
;         if (!has_next) break;
; #pragma unroll
;         for (int a = 0; a < 2; ++a)
; #pragma unroll
;             for (int b = 0; b < 2; ++b)
; #pragma unroll
;                 for (int m = 0; m < 4; ++m)
; #pragma unroll
;                     for (int n = 0; n < 2; ++n) acc[a][b][m][n] = (f32x4){0.f, 0.f, 0.f, 0.f};
;         cur = nxt; cA = nA; cB = nB; ++ui;
;         if constexpr (ALIGN_EPI) { if (wr == 1) PG8_BAR; }
	v_pk_mul_f32 v[24:25], v[24:25], v[152:153] op_sel_hi:[1,0]
	v_mul_f32_e32 v32, v38, v39
	v_mul_f32_e32 v26, 0xbfb8aa3b, v24
	v_exp_f32_e32 v30, v26
	v_mov_b32_e32 v26, v31
	v_pk_mul_f32 v[26:27], v[26:27], v[152:153] op_sel_hi:[1,0]
	v_mul_f32_e32 v28, v32, v28
	v_mul_f32_e32 v31, 0xbfb8aa3b, v26
	v_exp_f32_e32 v31, v31
	v_mul_f32_e32 v32, v24, v25
	v_add_f32_e32 v24, 1.0, v30
	v_rcp_f32_e32 v30, v24
	v_add_f32_e32 v24, 1.0, v31
	v_rcp_f32_e32 v31, v24
	v_mov_b32_e32 v24, v20
	v_mov_b32_e32 v25, v16
	v_pk_mul_f32 v[24:25], v[24:25], v[152:153] op_sel_hi:[1,0]
	v_mul_f32_e32 v26, v26, v27
	v_mul_f32_e32 v16, 0xbfb8aa3b, v24
	v_exp_f32_e32 v16, v16
	v_mul_f32_e32 v24, v24, v25
	v_mul_f32_e32 v20, v32, v30
	v_mul_f32_e32 v26, v26, v31
	v_add_f32_e32 v16, 1.0, v16
	v_rcp_f32_e32 v27, v16
	v_mov_b32_e32 v16, v21
	v_pk_mul_f32 v[16:17], v[16:17], v[152:153] op_sel_hi:[1,0]
	v_mul_f32_e32 v24, v24, v27
	v_mul_f32_e32 v21, 0xbfb8aa3b, v16
	v_exp_f32_e32 v21, v21
	v_mul_f32_e32 v25, v16, v17
	v_mov_b32_e32 v17, v18
	v_add_f32_e32 v16, 1.0, v21
	v_rcp_f32_e32 v21, v16
	v_mov_b32_e32 v16, v22
	v_pk_mul_f32 v[16:17], v[16:17], v[152:153] op_sel_hi:[1,0]
	v_mul_f32_e32 v21, v25, v21
	v_mul_f32_e32 v18, 0xbfb8aa3b, v16
	v_exp_f32_e32 v22, v18
	v_mov_b32_e32 v18, v23
	v_pk_mul_f32 v[18:19], v[18:19], v[152:153] op_sel_hi:[1,0]
	v_mul_f32_e32 v16, v16, v17
	v_mul_f32_e32 v23, 0xbfb8aa3b, v18
	v_exp_f32_e32 v23, v23
	v_add_f32_e32 v22, 1.0, v22
	v_rcp_f32_e32 v22, v22
	v_add_f32_e32 v23, 1.0, v23
	v_rcp_f32_e32 v23, v23
	v_mul_f32_e32 v22, v16, v22
	v_mul_f32_e32 v16, v18, v19
	v_mul_f32_e32 v19, v16, v23
	v_cvt_pk_bf16_f32 v16, v28, v29
	v_cvt_pk_bf16_f32 v17, v20, v26
	v_cvt_pk_bf16_f32 v18, v24, v21
	v_cvt_pk_bf16_f32 v19, v22, v19
	v_mov_b32_e32 v22, v12
	v_mov_b32_e32 v23, v8
	v_pk_mul_f32 v[22:23], v[22:23], v[148:149] op_sel_hi:[1,0]
	v_mad_i64_i32 v[20:21], s[42:43], v146, s53, v[112:113]
	v_mul_f32_e32 v8, 0xbfb8aa3b, v22
	v_exp_f32_e32 v12, v8
	v_mov_b32_e32 v8, v13
	v_pk_mul_f32 v[8:9], v[8:9], v[148:149] op_sel_hi:[1,0]
	v_lshl_add_u64 v[20:21], v[20:21], 0, v[114:115]
	v_mul_f32_e32 v13, 0xbfb8aa3b, v8
	v_exp_f32_e32 v13, v13
	v_mul_f32_e32 v8, v8, v9
	v_mov_b32_e32 v9, v10
	v_add_f32_e32 v12, 1.0, v12
	v_add_f32_e32 v13, 1.0, v13
	v_rcp_f32_e32 v13, v13
	v_rcp_f32_e32 v12, v12
	global_store_dwordx4 v[20:21], v[16:19], off
	v_mul_f32_e32 v13, v8, v13
	v_mov_b32_e32 v8, v14
	v_pk_mul_f32 v[8:9], v[8:9], v[148:149] op_sel_hi:[1,0]
	v_mul_f32_e32 v16, v22, v23
	v_mul_f32_e32 v10, 0xbfb8aa3b, v8
	v_exp_f32_e32 v14, v10
	v_mov_b32_e32 v10, v15
	v_pk_mul_f32 v[10:11], v[10:11], v[148:149] op_sel_hi:[1,0]
	v_mul_f32_e32 v12, v16, v12
	v_mul_f32_e32 v15, 0xbfb8aa3b, v10
	v_exp_f32_e32 v15, v15
	v_mul_f32_e32 v16, v8, v9
	v_add_f32_e32 v8, 1.0, v14
	v_rcp_f32_e32 v14, v8
	v_add_f32_e32 v8, 1.0, v15
	v_rcp_f32_e32 v15, v8
	v_mov_b32_e32 v8, v4
	v_mov_b32_e32 v9, v0
	v_pk_mul_f32 v[8:9], v[8:9], v[148:149] op_sel_hi:[1,0]
	v_mul_f32_e32 v10, v10, v11
	v_mul_f32_e32 v0, 0xbfb8aa3b, v8
	v_exp_f32_e32 v0, v0
	v_mul_f32_e32 v8, v8, v9
	v_mul_f32_e32 v4, v16, v14
	v_mul_f32_e32 v10, v10, v15
	v_add_f32_e32 v0, 1.0, v0
	v_rcp_f32_e32 v11, v0
	v_mov_b32_e32 v0, v5
	v_pk_mul_f32 v[0:1], v[0:1], v[148:149] op_sel_hi:[1,0]
	v_mul_f32_e32 v8, v8, v11
	v_mul_f32_e32 v5, 0xbfb8aa3b, v0
	v_exp_f32_e32 v5, v5
	v_mul_f32_e32 v9, v0, v1
	v_mov_b32_e32 v1, v2
	v_add_f32_e32 v0, 1.0, v5
	v_rcp_f32_e32 v5, v0
	v_mov_b32_e32 v0, v6
	v_pk_mul_f32 v[0:1], v[0:1], v[148:149] op_sel_hi:[1,0]
	v_mul_f32_e32 v5, v9, v5
	v_mul_f32_e32 v2, 0xbfb8aa3b, v0
	v_exp_f32_e32 v6, v2
	v_mov_b32_e32 v2, v7
	v_pk_mul_f32 v[2:3], v[2:3], v[148:149] op_sel_hi:[1,0]
	v_mul_f32_e32 v0, v0, v1
	v_mul_f32_e32 v7, 0xbfb8aa3b, v2
	v_exp_f32_e32 v7, v7
	v_add_f32_e32 v6, 1.0, v6
	v_rcp_f32_e32 v6, v6
	v_add_f32_e32 v7, 1.0, v7
	v_rcp_f32_e32 v7, v7
	v_mul_f32_e32 v6, v0, v6
	v_mul_f32_e32 v0, v2, v3
	v_mul_f32_e32 v3, v0, v7
	v_cvt_pk_bf16_f32 v0, v12, v13
	v_cvt_pk_bf16_f32 v1, v4, v10
	v_cvt_pk_bf16_f32 v2, v8, v5
	v_mad_i64_i32 v[4:5], s[42:43], v144, s53, v[112:113]
	v_lshl_add_u64 v[4:5], v[4:5], 0, v[114:115]
	v_cvt_pk_bf16_f32 v3, v6, v3
	global_store_dwordx4 v[4:5], v[0:3], off
	s_cbranch_vccnz .LBB0_477
	s_andn2_b64 vcc, exec, s[4:5]
	s_cbranch_vccnz .LBB0_476
	s_barrier
	s_branch .LBB0_476

; #define PG8_STAGE(bufoff, gbase, voff) do { _Pragma("unroll") for (int _i = 0; _i < 2; ++_i) \
;         __builtin_amdgcn_global_load_lds((const unsigned*)((const char*)(gbase) + (voff)[_i]), (PG8_LAS unsigned*)(lds + (bufoff) + ldsw + _i * 8192), 16, 0, 0); } while (0)
; #define PG8_LDA(dst, b, h) do { _Pragma("unroll") for (int m = 0; m < 4; ++m) _Pragma("unroll") for (int k = 0; k < 2; ++k) dst[m][k] = *(const PG8_LAS bf16x8*)(lds + PG8_SA(b, h) + aoff + m * 2048 + k * 1024); } while (0)
; #define PG8_LDB(dst, b, h) do { _Pragma("unroll") for (int n = 0; n < 2; ++n) _Pragma("unroll") for (int k = 0; k < 2; ++k) dst[n][k] = *(const PG8_LAS bf16x8*)(lds + PG8_SB(b, h) + boff + n * 2048 + k * 1024); } while (0)
; #define PG8_MMA(ai, bj, At, Bt) do { __builtin_amdgcn_s_setprio(1); _Pragma("unroll") for (int m = 0; m < 4; ++m) _Pragma("unroll") for (int n = 0; n < 2; ++n) _Pragma("unroll") for (int k = 0; k < 2; ++k) \
;         acc[ai][bj][m][n] = __builtin_amdgcn_mfma_f32_16x16x32_bf16(Bt[n][k], At[m][k], acc[ai][bj][m][n], 0, 0, 0); __builtin_amdgcn_s_setprio(0); } while (0)
; #define PG8_WAIT_V(n) asm volatile("s_waitcnt vmcnt(" #n ")" ::: "memory")
; #define PG8_BAR __builtin_amdgcn_s_barrier()
; template <class Epi, class Sched, bool ALIGN_EPI = false, bool SP2 = false>
; __device__ __forceinline__ void gemm_phase(PG8_LAS unsigned char* lds, const Gemm g, const Sched& S, const Epi& E) {
;     ...
;         for (int t = 0; t < nt; t += 2) {
;             const bool last = (t == nt - 2);
;             const char* a1 = cA + (size_t)(t + 1) * kstep;
;             const char* a2 = last ? nA : cA + (size_t)(t + 2) * kstep; const char* b2 = last ? nB : cB + (size_t)(t + 2) * kstep;
;             const char* a3 = a2 + kstep; const char* b3 = b2 + kstep;
;             if (last && has_next) S.a_ready(nxt);
;             if constexpr (SP2) {
;             PG8_LDB(B0, 0, 0); PG8_LDB(B1, 0, 1); PG8_SCHED; PG8_LDA(At, 0, 0); PG8_STAGE(PG8_SA(1, 1), a1 + hstep, voffA);
;             PG8_WAIT_V(8); PG8_WAIT_L(0); PG8_BAR; PG8_MMA(0, 0, At, B0); PG8_MMA(0, 1, At, B1); PG8_BAR; PG8_SCHED;
;             PG8_LDA(At, 0, 1); PG8_STAGE(PG8_SB(0, 0), b2, voffB); PG8_STAGE(PG8_SB(0, 1), b2 + hstep, voffB); PG8_STAGE(PG8_SA(0, 0), a2, voffA);
;             PG8_WAIT_V(8); PG8_WAIT_L(0); PG8_BAR; PG8_MMA(1, 0, At, B0); PG8_MMA(1, 1, At, B1); PG8_BAR; PG8_SCHED;
.LBB0_660:
	ds_read_b128 v[146:149], v165
	ds_read_b128 v[150:153], v165 offset:1024
	ds_read_b128 v[154:157], v165 offset:2048
	ds_read_b128 v[170:173], v165 offset:3072
	ds_read_b128 v[174:177], v166
	ds_read_b128 v[178:181], v166 offset:1024
	ds_read_b128 v[182:185], v166 offset:2048
	ds_read_b128 v[186:189], v166 offset:3072
	s_add_u32 s46, s0, 0xfffc0080
	s_addc_u32 s47, s1, -1
	s_cmp_eq_u32 s59, 12
	s_cselect_b32 s49, s5, s47
	s_cselect_b32 s48, s37, s46
	s_cselect_b32 s47, s21, s51
	s_cselect_b32 s46, s45, s50
	v_lshl_add_u64 v[158:159], s[0:1], 0, v[140:141]
	s_add_i32 m0, s26, 0xc000
	ds_read_b128 v[190:193], v167
	ds_read_b128 v[194:197], v167 offset:1024
	ds_read_b128 v[198:201], v167 offset:2048
	ds_read_b128 v[202:205], v167 offset:3072
	ds_read_b128 v[206:209], v167 offset:4096
	ds_read_b128 v[210:213], v167 offset:5120
	ds_read_b128 v[214:217], v167 offset:6144
	ds_read_b128 v[218:221], v167 offset:7168
	global_load_lds_dwordx4 v[158:159], off
	v_lshl_add_u64 v[158:159], s[0:1], 0, v[142:143]
	s_add_i32 m0, s26, 0xe000
	s_nop 0
	global_load_lds_dwordx4 v[158:159], off
	s_waitcnt vmcnt(8)
	s_waitcnt lgkmcnt(0)
	s_barrier
	s_setprio 1
	s_waitcnt lgkmcnt(0)
	v_mfma_f32_16x16x32_bf16 v[124:127], v[146:149], v[190:193], v[124:127]
	v_mfma_f32_16x16x32_bf16 v[120:123], v[154:157], v[190:193], v[120:123]
	v_mfma_f32_16x16x32_bf16 v[108:111], v[146:149], v[198:201], v[108:111]
	v_mfma_f32_16x16x32_bf16 v[104:107], v[154:157], v[198:201], v[104:107]
	v_mfma_f32_16x16x32_bf16 v[92:95], v[146:149], v[206:209], v[92:95]
	v_mfma_f32_16x16x32_bf16 v[88:91], v[154:157], v[206:209], v[88:91]
	v_mfma_f32_16x16x32_bf16 v[76:79], v[146:149], v[214:217], v[76:79]
	v_mfma_f32_16x16x32_bf16 v[72:75], v[154:157], v[214:217], v[72:75]
	v_mfma_f32_16x16x32_bf16 v[124:127], v[150:153], v[194:197], v[124:127]
	v_mfma_f32_16x16x32_bf16 v[120:123], v[170:173], v[194:197], v[120:123]
	v_mfma_f32_16x16x32_bf16 v[108:111], v[150:153], v[202:205], v[108:111]
	v_mfma_f32_16x16x32_bf16 v[104:107], v[170:173], v[202:205], v[104:107]
	v_mfma_f32_16x16x32_bf16 v[92:95], v[150:153], v[210:213], v[92:95]
	v_mfma_f32_16x16x32_bf16 v[88:91], v[170:173], v[210:213], v[88:91]
	v_mfma_f32_16x16x32_bf16 v[76:79], v[150:153], v[218:221], v[76:79]
	v_mfma_f32_16x16x32_bf16 v[72:75], v[170:173], v[218:221], v[72:75]
	s_setprio 0
	s_setprio 1
	v_mfma_f32_16x16x32_bf16 v[116:119], v[174:177], v[190:193], v[116:119]
	v_mfma_f32_16x16x32_bf16 v[112:115], v[182:185], v[190:193], v[112:115]
	v_mfma_f32_16x16x32_bf16 v[100:103], v[174:177], v[198:201], v[100:103]
	v_mfma_f32_16x16x32_bf16 v[96:99], v[182:185], v[198:201], v[96:99]
	v_mfma_f32_16x16x32_bf16 v[84:87], v[174:177], v[206:209], v[84:87]
	v_mfma_f32_16x16x32_bf16 v[80:83], v[182:185], v[206:209], v[80:83]
	v_mfma_f32_16x16x32_bf16 v[68:71], v[174:177], v[214:217], v[68:71]
	v_mfma_f32_16x16x32_bf16 v[64:67], v[182:185], v[214:217], v[64:67]
	v_mfma_f32_16x16x32_bf16 v[116:119], v[178:181], v[194:197], v[116:119]
	v_mfma_f32_16x16x32_bf16 v[112:115], v[186:189], v[194:197], v[112:115]
	v_mfma_f32_16x16x32_bf16 v[100:103], v[178:181], v[202:205], v[100:103]
	v_mfma_f32_16x16x32_bf16 v[96:99], v[186:189], v[202:205], v[96:99]
	v_mfma_f32_16x16x32_bf16 v[84:87], v[178:181], v[210:213], v[84:87]
	v_mfma_f32_16x16x32_bf16 v[80:83], v[186:189], v[210:213], v[80:83]
	v_mfma_f32_16x16x32_bf16 v[68:71], v[178:181], v[218:221], v[68:71]
	v_mfma_f32_16x16x32_bf16 v[64:67], v[186:189], v[218:221], v[64:67]
	s_setprio 0
	s_barrier
	s_add_i32 s60, s56, s25
	v_lshl_add_u64 v[158:159], s[46:47], 0, v[130:131]
	s_mov_b32 m0, s60
	ds_read_b128 v[190:193], v167 offset:16384
	ds_read_b128 v[194:197], v167 offset:17408
	ds_read_b128 v[198:201], v167 offset:18432
	ds_read_b128 v[202:205], v167 offset:19456
	ds_read_b128 v[206:209], v167 offset:20480
	ds_read_b128 v[210:213], v167 offset:21504
	ds_read_b128 v[214:217], v167 offset:22528
	ds_read_b128 v[218:221], v167 offset:23552
	global_load_lds_dwordx4 v[158:159], off
	s_add_i32 m0, s60, 0x2000
	s_add_u32 s60, s46, 0x40000
	v_lshl_add_u64 v[162:163], s[46:47], 0, v[134:135]
	s_addc_u32 s61, s47, 0
	s_add_i32 s62, s57, s25
	global_load_lds_dwordx4 v[162:163], off
	v_lshl_add_u64 v[222:223], s[60:61], 0, v[130:131]
	s_mov_b32 m0, s62
	v_lshl_add_u64 v[224:225], s[48:49], 0, v[132:133]
	global_load_lds_dwordx4 v[222:223], off
	v_lshl_add_u64 v[222:223], s[60:61], 0, v[134:135]
	s_add_i32 m0, s62, 0x2000
	s_nop 0
	global_load_lds_dwordx4 v[222:223], off
	v_lshl_add_u64 v[222:223], s[48:49], 0, v[128:129]
	s_mov_b32 m0, s26
	s_nop 0
	global_load_lds_dwordx4 v[222:223], off
	s_mov_b32 m0, s27
	s_nop 0
	global_load_lds_dwordx4 v[224:225], off
	s_cmp_lg_i32 s59, -2
	s_cbranch_scc1 .Lrsc_a
	v_lshrrev_b32_e32 v250, 6, v230
	v_lshlrev_b32_e32 v250, 11, v250
	v_and_b32_e32 v251, 63, v230
	v_lshl_or_b32 v250, v251, 4, v250
	v_lshl_add_u32 v250, s44, 14, v250
	v_readfirstlane_b32 s98, v230
	s_lshr_b32 s98, s98, 6
	s_lshl_b32 s98, s98, 11
	s_add_i32 m0, s98, 0x20000
	s_add_u32 s100, s70, 0x3f000000
	s_addc_u32 s101, s71, 0
	global_load_lds_dwordx4 v250, s[100:101]
	global_load_lds_dwordx4 v250, s[100:101] offset:1024
	s_waitcnt vmcnt(10)
	s_branch .Lrsc_b

; #define PG8_STAGE(bufoff, gbase, voff) do { _Pragma("unroll") for (int _i = 0; _i < 2; ++_i) \
;         __builtin_amdgcn_global_load_lds((const unsigned*)((const char*)(gbase) + (voff)[_i]), (PG8_LAS unsigned*)(lds + (bufoff) + ldsw + _i * 8192), 16, 0, 0); } while (0)
; #define PG8_LDA(dst, b, h) do { _Pragma("unroll") for (int m = 0; m < 4; ++m) _Pragma("unroll") for (int k = 0; k < 2; ++k) dst[m][k] = *(const PG8_LAS bf16x8*)(lds + PG8_SA(b, h) + aoff + m * 2048 + k * 1024); } while (0)
; #define PG8_LDB(dst, b, h) do { _Pragma("unroll") for (int n = 0; n < 2; ++n) _Pragma("unroll") for (int k = 0; k < 2; ++k) dst[n][k] = *(const PG8_LAS bf16x8*)(lds + PG8_SB(b, h) + boff + n * 2048 + k * 1024); } while (0)
; #define PG8_MMA(ai, bj, At, Bt) do { __builtin_amdgcn_s_setprio(1); _Pragma("unroll") for (int m = 0; m < 4; ++m) _Pragma("unroll") for (int n = 0; n < 2; ++n) _Pragma("unroll") for (int k = 0; k < 2; ++k) \
;         acc[ai][bj][m][n] = __builtin_amdgcn_mfma_f32_16x16x32_bf16(Bt[n][k], At[m][k], acc[ai][bj][m][n], 0, 0, 0); __builtin_amdgcn_s_setprio(0); } while (0)
; #define PG8_WAIT_V(n) asm volatile("s_waitcnt vmcnt(" #n ")" ::: "memory")
; #define PG8_WAIT_L(n) asm volatile("s_waitcnt lgkmcnt(" #n ")" ::: "memory")
; #define PG8_BAR __builtin_amdgcn_s_barrier()
; #define PG8_SCHED __builtin_amdgcn_sched_barrier(0)
; template <class Epi, class Sched, bool ALIGN_EPI = false, bool SP2 = false>
; __device__ __forceinline__ void gemm_phase(PG8_LAS unsigned char* lds, const Gemm g, const Sched& S, const Epi& E) {
;     ...
;             PG8_WAIT_V(8); PG8_WAIT_L(0); PG8_BAR; PG8_MMA(1, 0, At, B0); PG8_MMA(1, 1, At, B1); PG8_BAR; PG8_SCHED;
;             PG8_LDB(B0, 1, 0); PG8_LDB(B1, 1, 1); PG8_SCHED; PG8_LDA(At, 1, 0); PG8_STAGE(PG8_SA(0, 1), a2 + hstep, voffA);
;             PG8_WAIT_V(8); PG8_WAIT_L(0); PG8_BAR; PG8_MMA(0, 0, At, B0); PG8_MMA(0, 1, At, B1); PG8_BAR; PG8_SCHED;
;             PG8_LDA(At, 1, 1); PG8_STAGE(PG8_SB(1, 0), b3, voffB); PG8_STAGE(PG8_SB(1, 1), b3 + hstep, voffB); PG8_STAGE(PG8_SA(1, 0), a3, voffA);
.Lrsc_b:
	s_waitcnt lgkmcnt(0)
	s_barrier
	s_setprio 1
	s_waitcnt lgkmcnt(0)
	v_mfma_f32_16x16x32_bf16 v[60:63], v[146:149], v[190:193], v[60:63]
	v_mfma_f32_16x16x32_bf16 v[56:59], v[154:157], v[190:193], v[56:59]
	v_mfma_f32_16x16x32_bf16 v[44:47], v[146:149], v[198:201], v[44:47]
	v_mfma_f32_16x16x32_bf16 v[40:43], v[154:157], v[198:201], v[40:43]
	v_mfma_f32_16x16x32_bf16 v[28:31], v[146:149], v[206:209], v[28:31]
	v_mfma_f32_16x16x32_bf16 v[24:27], v[154:157], v[206:209], v[24:27]
	v_mfma_f32_16x16x32_bf16 v[12:15], v[146:149], v[214:217], v[12:15]
	v_mfma_f32_16x16x32_bf16 v[8:11], v[154:157], v[214:217], v[8:11]
	v_mfma_f32_16x16x32_bf16 v[60:63], v[150:153], v[194:197], v[60:63]
	v_mfma_f32_16x16x32_bf16 v[56:59], v[170:173], v[194:197], v[56:59]
	v_mfma_f32_16x16x32_bf16 v[44:47], v[150:153], v[202:205], v[44:47]
	v_mfma_f32_16x16x32_bf16 v[40:43], v[170:173], v[202:205], v[40:43]
	v_mfma_f32_16x16x32_bf16 v[28:31], v[150:153], v[210:213], v[28:31]
	v_mfma_f32_16x16x32_bf16 v[24:27], v[170:173], v[210:213], v[24:27]
	v_mfma_f32_16x16x32_bf16 v[12:15], v[150:153], v[218:221], v[12:15]
	v_mfma_f32_16x16x32_bf16 v[8:11], v[170:173], v[218:221], v[8:11]
	s_setprio 0
	s_setprio 1
	v_mfma_f32_16x16x32_bf16 v[52:55], v[174:177], v[190:193], v[52:55]
	v_mfma_f32_16x16x32_bf16 v[48:51], v[182:185], v[190:193], v[48:51]
	v_mfma_f32_16x16x32_bf16 v[36:39], v[174:177], v[198:201], v[36:39]
	v_mfma_f32_16x16x32_bf16 v[32:35], v[182:185], v[198:201], v[32:35]
	v_mfma_f32_16x16x32_bf16 v[20:23], v[174:177], v[206:209], v[20:23]
	v_mfma_f32_16x16x32_bf16 v[16:19], v[182:185], v[206:209], v[16:19]
	v_mfma_f32_16x16x32_bf16 v[4:7], v[174:177], v[214:217], v[4:7]
	v_mfma_f32_16x16x32_bf16 v[0:3], v[182:185], v[214:217], v[0:3]
	v_mfma_f32_16x16x32_bf16 v[52:55], v[178:181], v[194:197], v[52:55]
	v_mfma_f32_16x16x32_bf16 v[48:51], v[186:189], v[194:197], v[48:51]
	v_mfma_f32_16x16x32_bf16 v[36:39], v[178:181], v[202:205], v[36:39]
	v_mfma_f32_16x16x32_bf16 v[32:35], v[186:189], v[202:205], v[32:35]
	v_mfma_f32_16x16x32_bf16 v[20:23], v[178:181], v[210:213], v[20:23]
	v_mfma_f32_16x16x32_bf16 v[16:19], v[186:189], v[210:213], v[16:19]
	v_mfma_f32_16x16x32_bf16 v[4:7], v[178:181], v[218:221], v[4:7]
	v_mfma_f32_16x16x32_bf16 v[0:3], v[186:189], v[218:221], v[0:3]
	s_setprio 0
	s_barrier
	s_add_i32 s60, 0, 0x18000
	v_add_u32_e32 v160, s60, v164
	s_add_i32 s61, 0, 0x1c000
	ds_read_b128 v[146:149], v160
	ds_read_b128 v[150:153], v160 offset:1024
	ds_read_b128 v[154:157], v160 offset:2048
	ds_read_b128 v[170:173], v160 offset:3072
	v_add_u32_e32 v160, s61, v164
	ds_read_b128 v[174:177], v160
	ds_read_b128 v[178:181], v160 offset:1024
	ds_read_b128 v[182:185], v160 offset:2048
	ds_read_b128 v[186:189], v160 offset:3072
	s_add_u32 s48, s48, 0x40000
	s_addc_u32 s49, s49, 0
	s_mov_b32 m0, s28
	v_lshl_add_u64 v[226:227], s[48:49], 0, v[128:129]
	ds_read_b128 v[190:193], v167 offset:32768
	ds_read_b128 v[194:197], v167 offset:33792
	ds_read_b128 v[198:201], v167 offset:34816
	ds_read_b128 v[202:205], v167 offset:35840
	ds_read_b128 v[206:209], v167 offset:36864
	ds_read_b128 v[210:213], v167 offset:37888
	ds_read_b128 v[214:217], v167 offset:38912
	ds_read_b128 v[218:221], v167 offset:39936
	global_load_lds_dwordx4 v[226:227], off
	v_lshl_add_u64 v[226:227], s[48:49], 0, v[132:133]
	s_mov_b32 m0, s29
	s_nop 0
	global_load_lds_dwordx4 v[226:227], off
	s_cmp_lg_i32 s59, -2
	s_cbranch_scc1 .Lrsc_c
	s_waitcnt vmcnt(10)
	s_branch .Lrsc_d

; #define PG8_STAGE(bufoff, gbase, voff) do { _Pragma("unroll") for (int _i = 0; _i < 2; ++_i) \
;         __builtin_amdgcn_global_load_lds((const unsigned*)((const char*)(gbase) + (voff)[_i]), (PG8_LAS unsigned*)(lds + (bufoff) + ldsw + _i * 8192), 16, 0, 0); } while (0)
; #define PG8_LDA(dst, b, h) do { _Pragma("unroll") for (int m = 0; m < 4; ++m) _Pragma("unroll") for (int k = 0; k < 2; ++k) dst[m][k] = *(const PG8_LAS bf16x8*)(lds + PG8_SA(b, h) + aoff + m * 2048 + k * 1024); } while (0)
; #define PG8_MMA(ai, bj, At, Bt) do { __builtin_amdgcn_s_setprio(1); _Pragma("unroll") for (int m = 0; m < 4; ++m) _Pragma("unroll") for (int n = 0; n < 2; ++n) _Pragma("unroll") for (int k = 0; k < 2; ++k) \
;         acc[ai][bj][m][n] = __builtin_amdgcn_mfma_f32_16x16x32_bf16(Bt[n][k], At[m][k], acc[ai][bj][m][n], 0, 0, 0); __builtin_amdgcn_s_setprio(0); } while (0)
; #define PG8_WAIT_V(n) asm volatile("s_waitcnt vmcnt(" #n ")" ::: "memory")
; #define PG8_WAIT_L(n) asm volatile("s_waitcnt lgkmcnt(" #n ")" ::: "memory")
; #define PG8_BAR __builtin_amdgcn_s_barrier()
; #define PG8_SCHED __builtin_amdgcn_sched_barrier(0)
; template <class Epi, class Sched, bool ALIGN_EPI = false, bool SP2 = false>
; __device__ __forceinline__ void gemm_phase(PG8_LAS unsigned char* lds, const Gemm g, const Sched& S, const Epi& E) {
;     ...
;             PG8_WAIT_V(8); PG8_WAIT_L(0); PG8_BAR; PG8_MMA(0, 0, At, B0); PG8_MMA(0, 1, At, B1); PG8_BAR; PG8_SCHED;
;             PG8_LDA(At, 1, 1); PG8_STAGE(PG8_SB(1, 0), b3, voffB); PG8_STAGE(PG8_SB(1, 1), b3 + hstep, voffB); PG8_STAGE(PG8_SA(1, 0), a3, voffA);
;             PG8_WAIT_V(8); PG8_WAIT_L(0); PG8_BAR; PG8_MMA(1, 0, At, B0); PG8_MMA(1, 1, At, B1); PG8_BAR; PG8_SCHED;
;     ...
;         if constexpr (ALIGN_EPI) { if (wr == 0) PG8_BAR; }
.Lrsc_d:
	s_waitcnt lgkmcnt(0)
	s_barrier
	s_setprio 1
	s_waitcnt lgkmcnt(0)
	v_mfma_f32_16x16x32_bf16 v[124:127], v[146:149], v[190:193], v[124:127]
	v_mfma_f32_16x16x32_bf16 v[120:123], v[154:157], v[190:193], v[120:123]
	v_mfma_f32_16x16x32_bf16 v[108:111], v[146:149], v[198:201], v[108:111]
	v_mfma_f32_16x16x32_bf16 v[104:107], v[154:157], v[198:201], v[104:107]
	v_mfma_f32_16x16x32_bf16 v[92:95], v[146:149], v[206:209], v[92:95]
	v_mfma_f32_16x16x32_bf16 v[88:91], v[154:157], v[206:209], v[88:91]
	v_mfma_f32_16x16x32_bf16 v[76:79], v[146:149], v[214:217], v[76:79]
	v_mfma_f32_16x16x32_bf16 v[72:75], v[154:157], v[214:217], v[72:75]
	v_mfma_f32_16x16x32_bf16 v[124:127], v[150:153], v[194:197], v[124:127]
	v_mfma_f32_16x16x32_bf16 v[120:123], v[170:173], v[194:197], v[120:123]
	v_mfma_f32_16x16x32_bf16 v[108:111], v[150:153], v[202:205], v[108:111]
	v_mfma_f32_16x16x32_bf16 v[104:107], v[170:173], v[202:205], v[104:107]
	v_mfma_f32_16x16x32_bf16 v[92:95], v[150:153], v[210:213], v[92:95]
	v_mfma_f32_16x16x32_bf16 v[88:91], v[170:173], v[210:213], v[88:91]
	v_mfma_f32_16x16x32_bf16 v[76:79], v[150:153], v[218:221], v[76:79]
	v_mfma_f32_16x16x32_bf16 v[72:75], v[170:173], v[218:221], v[72:75]
	s_setprio 0
	s_setprio 1
	v_mfma_f32_16x16x32_bf16 v[116:119], v[174:177], v[190:193], v[116:119]
	v_mfma_f32_16x16x32_bf16 v[112:115], v[182:185], v[190:193], v[112:115]
	v_mfma_f32_16x16x32_bf16 v[100:103], v[174:177], v[198:201], v[100:103]
	v_mfma_f32_16x16x32_bf16 v[96:99], v[182:185], v[198:201], v[96:99]
	v_mfma_f32_16x16x32_bf16 v[84:87], v[174:177], v[206:209], v[84:87]
	v_mfma_f32_16x16x32_bf16 v[80:83], v[182:185], v[206:209], v[80:83]
	v_mfma_f32_16x16x32_bf16 v[68:71], v[174:177], v[214:217], v[68:71]
	v_mfma_f32_16x16x32_bf16 v[64:67], v[182:185], v[214:217], v[64:67]
	v_mfma_f32_16x16x32_bf16 v[116:119], v[178:181], v[194:197], v[116:119]
	v_mfma_f32_16x16x32_bf16 v[112:115], v[186:189], v[194:197], v[112:115]
	v_mfma_f32_16x16x32_bf16 v[100:103], v[178:181], v[202:205], v[100:103]
	v_mfma_f32_16x16x32_bf16 v[96:99], v[186:189], v[202:205], v[96:99]
	v_mfma_f32_16x16x32_bf16 v[84:87], v[178:181], v[210:213], v[84:87]
	v_mfma_f32_16x16x32_bf16 v[80:83], v[186:189], v[210:213], v[80:83]
	v_mfma_f32_16x16x32_bf16 v[68:71], v[178:181], v[218:221], v[68:71]
	v_mfma_f32_16x16x32_bf16 v[64:67], v[186:189], v[218:221], v[64:67]
	s_setprio 0
	s_barrier
	s_add_i32 s48, s60, s25
	v_lshl_add_u64 v[158:159], v[158:159], 0, s[16:17]
	s_mov_b32 m0, s48
	ds_read_b128 v[190:193], v167 offset:49152
	ds_read_b128 v[194:197], v167 offset:50176
	ds_read_b128 v[198:201], v167 offset:51200
	ds_read_b128 v[202:205], v167 offset:52224
	ds_read_b128 v[206:209], v167 offset:53248
	ds_read_b128 v[210:213], v167 offset:54272
	ds_read_b128 v[214:217], v167 offset:55296
	ds_read_b128 v[218:221], v167 offset:56320
	global_load_lds_dwordx4 v[158:159], off
	s_add_i32 m0, s48, 0x2000
	s_add_u32 s46, s46, 0x40080
	v_lshl_add_u64 v[158:159], v[162:163], 0, s[16:17]
	s_addc_u32 s47, s47, 0
	s_add_i32 s48, s61, s25
	global_load_lds_dwordx4 v[158:159], off
	v_lshl_add_u64 v[158:159], s[46:47], 0, v[130:131]
	s_mov_b32 m0, s48
	s_nop 0
	global_load_lds_dwordx4 v[158:159], off
	v_lshl_add_u64 v[158:159], s[46:47], 0, v[134:135]
	s_add_i32 m0, s48, 0x2000
	s_nop 0
	global_load_lds_dwordx4 v[158:159], off
	v_lshl_add_u64 v[158:159], v[222:223], 0, s[16:17]
	s_mov_b32 m0, s31
	s_nop 0
	global_load_lds_dwordx4 v[158:159], off
	v_lshl_add_u64 v[158:159], v[224:225], 0, s[16:17]
	s_mov_b32 m0, s33
	s_nop 0
	global_load_lds_dwordx4 v[158:159], off
	s_waitcnt vmcnt(8)
	s_waitcnt lgkmcnt(0)
	s_barrier
	s_setprio 1
	s_waitcnt lgkmcnt(0)
	v_mfma_f32_16x16x32_bf16 v[60:63], v[146:149], v[190:193], v[60:63]
	v_mfma_f32_16x16x32_bf16 v[56:59], v[154:157], v[190:193], v[56:59]
	v_mfma_f32_16x16x32_bf16 v[44:47], v[146:149], v[198:201], v[44:47]
	v_mfma_f32_16x16x32_bf16 v[40:43], v[154:157], v[198:201], v[40:43]
	v_mfma_f32_16x16x32_bf16 v[28:31], v[146:149], v[206:209], v[28:31]
	v_mfma_f32_16x16x32_bf16 v[24:27], v[154:157], v[206:209], v[24:27]
	v_mfma_f32_16x16x32_bf16 v[12:15], v[146:149], v[214:217], v[12:15]
	v_mfma_f32_16x16x32_bf16 v[8:11], v[154:157], v[214:217], v[8:11]
	v_mfma_f32_16x16x32_bf16 v[60:63], v[150:153], v[194:197], v[60:63]
	v_mfma_f32_16x16x32_bf16 v[56:59], v[170:173], v[194:197], v[56:59]
	v_mfma_f32_16x16x32_bf16 v[44:47], v[150:153], v[202:205], v[44:47]
	v_mfma_f32_16x16x32_bf16 v[40:43], v[170:173], v[202:205], v[40:43]
	v_mfma_f32_16x16x32_bf16 v[28:31], v[150:153], v[210:213], v[28:31]
	v_mfma_f32_16x16x32_bf16 v[24:27], v[170:173], v[210:213], v[24:27]
	v_mfma_f32_16x16x32_bf16 v[12:15], v[150:153], v[218:221], v[12:15]
	v_mfma_f32_16x16x32_bf16 v[8:11], v[170:173], v[218:221], v[8:11]
	s_setprio 0
	s_setprio 1
	v_mfma_f32_16x16x32_bf16 v[52:55], v[174:177], v[190:193], v[52:55]
	v_mfma_f32_16x16x32_bf16 v[48:51], v[182:185], v[190:193], v[48:51]
	v_mfma_f32_16x16x32_bf16 v[36:39], v[174:177], v[198:201], v[36:39]
	v_mfma_f32_16x16x32_bf16 v[32:35], v[182:185], v[198:201], v[32:35]
	v_mfma_f32_16x16x32_bf16 v[20:23], v[174:177], v[206:209], v[20:23]
	v_mfma_f32_16x16x32_bf16 v[16:19], v[182:185], v[206:209], v[16:19]
	v_mfma_f32_16x16x32_bf16 v[4:7], v[174:177], v[214:217], v[4:7]
	v_mfma_f32_16x16x32_bf16 v[0:3], v[182:185], v[214:217], v[0:3]
	v_mfma_f32_16x16x32_bf16 v[52:55], v[178:181], v[194:197], v[52:55]
	v_mfma_f32_16x16x32_bf16 v[48:51], v[186:189], v[194:197], v[48:51]
	v_mfma_f32_16x16x32_bf16 v[36:39], v[178:181], v[202:205], v[36:39]
	v_mfma_f32_16x16x32_bf16 v[32:35], v[186:189], v[202:205], v[32:35]
	v_mfma_f32_16x16x32_bf16 v[20:23], v[178:181], v[210:213], v[20:23]
	v_mfma_f32_16x16x32_bf16 v[16:19], v[186:189], v[210:213], v[16:19]
	v_mfma_f32_16x16x32_bf16 v[4:7], v[178:181], v[218:221], v[4:7]
	v_mfma_f32_16x16x32_bf16 v[0:3], v[186:189], v[218:221], v[0:3]
	s_setprio 0
	s_barrier
	s_add_i32 s59, s59, 2
	s_add_u32 s0, s0, 0x100
	s_addc_u32 s1, s1, 0
	s_add_u32 s50, s50, 0x100
	s_addc_u32 s51, s51, 0
	s_cmp_gt_u32 s59, 13
	s_cbranch_scc0 .LBB0_660
	s_and_b64 vcc, exec, s[18:19]
	s_cbranch_vccz .LBB0_663
	s_barrier
; __device__ __forceinline__ unsigned cvt_pk_bf16(float lo, float hi) { unsigned r; asm volatile("v_cvt_pk_bf16_f32 %0, %1, %2" : "=v"(r) : "v"(lo), "v"(hi)); return r; }
; __device__ __forceinline__ void rows_rstd(const float* ssq, int row0, int fq, float (&rs)[2][4]) {
;     f32x4 pr[2][4];
; #pragma unroll
;     for (int ai = 0; ai < 2; ++ai)
; #pragma unroll
;         for (int m = 0; m < 4; ++m) pr[ai][m] = *(const f32x4*)(ssq + (size_t)(row0 + ai * HALF + m * 16) * 16 + 4 * fq);
; #pragma unroll
;     for (int ai = 0; ai < 2; ++ai)
; #pragma unroll
;         for (int m = 0; m < 4; ++m) { float t = (pr[ai][m][0] + pr[ai][m][1]) + (pr[ai][m][2] + pr[ai][m][3]); t += __shfl_xor(t, 16); t += __shfl_xor(t, 32); rs[ai][m] = __builtin_amdgcn_rsqf(t * (1.0f / 1024.0f) + 1e-6f); }
;     __device__ __forceinline__ void operator()(const f32x4 (&acc)[2][2][4][2], const Unit& u, int wr, int wc, int fr, int fq) const {
;         float rsv[2][4]; rows_rstd(ssq, u.pm * BM + wr * 64 + fr, fq, rsv);
; #pragma unroll
;         for (int ai = 0; ai < 2; ++ai)
; #pragma unroll
;             for (int m = 0; m < 4; ++m) {
;                 const int row = u.pm * BM + ai * HALF + wr * 64 + m * 16 + fr;
;                 const float rs = rsv[ai][m];
;                 bf16_t* rp = O + (size_t)row * 1536 + wc * 32 + 8 * fq;
;                 if (u.pn < 2) {
; #pragma unroll
;                     for (int bj = 0; bj < 2; ++bj) {
;                         const f32x4 v0 = acc[ai][bj][m][0] * rs, v1 = acc[ai][bj][m][1] * rs;
;                         u32x4 w; w.x = cvt_pk_bf16(v0[0], v0[1]); w.y = cvt_pk_bf16(v0[2], v0[3]); w.z = cvt_pk_bf16(v1[0], v1[1]); w.w = cvt_pk_bf16(v1[2], v1[3]);
;                         *(u32x4*)(rp + u.pn * BM + bj * HALF) = w;
;                     }
;                 } else {
;                     float h[8];
;                     const bool glu = u.pn >= 6;
; #pragma unroll
;                     for (int n = 0; n < 2; ++n)
; #pragma unroll
;                         for (int i = 0; i < 4; ++i) { const float a = acc[ai][0][m][n][i] * rs, b = acc[ai][1][m][n][i] * rs; h[4 * n + i] = glu ? a * fast_sigmoid(b) : a * b; }
;                     u32x4 w; w.x = cvt_pk_bf16(h[0], h[1]); w.y = cvt_pk_bf16(h[2], h[3]); w.z = cvt_pk_bf16(h[4], h[5]); w.w = cvt_pk_bf16(h[6], h[7]);
;                     *(u32x4*)(rp + 512 + (u.pn - 2) * HALF) = w;
.LBB0_663:
	v_mbcnt_lo_u32_b32 v252, -1, 0
	v_mbcnt_hi_u32_b32 v252, -1, v252
	v_and_b32_e32 v252, 48, v252
	v_lshl_add_u32 v252, v161, 6, v252
	v_add_u32_e32 v252, 0x20000, v252
	v_lshl_add_u32 v162, s44, 8, v161
	v_or_b32_e32 v158, 16, v162
	v_ashrrev_i32_e32 v163, 31, v162
	v_ashrrev_i32_e32 v159, 31, v158
	v_lshlrev_b64 v[146:147], 6, v[162:163]
	v_lshlrev_b64 v[148:149], 6, v[158:159]
	v_or_b32_e32 v156, 32, v162
	v_or_b32_e32 v154, 48, v162
	v_lshl_add_u64 v[146:147], v[136:137], 0, v[146:147]
	v_lshl_add_u64 v[148:149], v[136:137], 0, v[148:149]
	v_ashrrev_i32_e32 v157, 31, v156
	v_ashrrev_i32_e32 v155, 31, v154
	ds_read_b128 v[170:173], v252 offset:0
	ds_read_b128 v[174:177], v252 offset:1024
	v_lshlrev_b64 v[146:147], 6, v[156:157]
	v_lshlrev_b64 v[148:149], 6, v[154:155]
	v_add_u32_e32 v152, 0x80, v162
	v_add_u32_e32 v150, 0x90, v162
	v_lshl_add_u64 v[146:147], v[136:137], 0, v[146:147]
	v_lshl_add_u64 v[148:149], v[136:137], 0, v[148:149]
	v_ashrrev_i32_e32 v153, 31, v152
	v_ashrrev_i32_e32 v151, 31, v150
	ds_read_b128 v[178:181], v252 offset:2048
	ds_read_b128 v[182:185], v252 offset:3072
	v_lshlrev_b64 v[146:147], 6, v[152:153]
	v_lshlrev_b64 v[148:149], 6, v[150:151]
	v_lshl_add_u64 v[146:147], v[136:137], 0, v[146:147]
	v_lshl_add_u64 v[148:149], v[136:137], 0, v[148:149]
	ds_read_b128 v[186:189], v252 offset:8192
	ds_read_b128 v[190:193], v252 offset:9216
	v_add_u32_e32 v148, 0xa0, v162
	v_ashrrev_i32_e32 v149, 31, v148
	v_lshlrev_b64 v[146:147], 6, v[148:149]
	v_lshl_add_u64 v[146:147], v[136:137], 0, v[146:147]
	ds_read_b128 v[194:197], v252 offset:10240
	v_add_u32_e32 v146, 0xb0, v162
	v_ashrrev_i32_e32 v147, 31, v146
	v_lshlrev_b64 v[198:199], 6, v[146:147]
	v_lshl_add_u64 v[198:199], v[136:137], 0, v[198:199]
	ds_read_b128 v[198:201], v252 offset:11264
	v_and_b32_e32 v149, 64, v168
	v_xor_b32_e32 v147, 16, v168
	v_add_u32_e32 v149, 64, v149
	v_xor_b32_e32 v151, 32, v168
	v_cmp_lt_i32_e32 vcc, v147, v149
	s_cmp_gt_i32 s4, 1
	s_cselect_b64 s[48:49], -1, 0
	v_cndmask_b32_e32 v147, v168, v147, vcc
	v_cmp_lt_i32_e32 vcc, v151, v149
	v_lshlrev_b32_e32 v147, 2, v147
	s_cmp_gt_u32 s4, 5
	v_cndmask_b32_e32 v149, v168, v151, vcc
	v_lshlrev_b32_e32 v149, 2, v149
	s_cselect_b64 s[0:1], -1, 0
	s_lshl_b32 s5, s4, 7
	s_add_i32 s44, s5, 0xffffff00
	s_ashr_i32 s45, s44, 31
	s_mov_b64 s[50:51], -1
	s_and_b64 vcc, exec, s[48:49]
	s_waitcnt lgkmcnt(0)
	v_add_f32_e32 v151, v170, v171
	v_add_f32_e32 v153, v172, v173
	v_add_f32_e32 v151, v151, v153
	v_add_f32_e32 v153, v174, v175
	v_add_f32_e32 v155, v176, v177
	v_add_f32_e32 v153, v153, v155
	v_add_f32_e32 v157, v178, v179
	ds_bpermute_b32 v178, v147, v151
	v_add_f32_e32 v159, v180, v181
	v_add_f32_e32 v160, v182, v183
	v_add_f32_e32 v163, v184, v185
	v_add_f32_e32 v170, v186, v187
	v_add_f32_e32 v171, v188, v189
	v_add_f32_e32 v172, v190, v191
	v_add_f32_e32 v173, v192, v193
	v_add_f32_e32 v155, v157, v159
	v_add_f32_e32 v157, v160, v163
	v_add_f32_e32 v174, v194, v195
	v_add_f32_e32 v175, v196, v197
	v_add_f32_e32 v159, v170, v171
	v_add_f32_e32 v160, v172, v173
	v_add_f32_e32 v163, v174, v175
	v_add_f32_e32 v176, v198, v199
	v_add_f32_e32 v177, v200, v201
	v_add_f32_e32 v170, v176, v177
	s_waitcnt lgkmcnt(0)
	v_add_f32_e32 v178, v151, v178
	ds_bpermute_b32 v171, v147, v153
	ds_bpermute_b32 v172, v147, v155
	ds_bpermute_b32 v174, v147, v157
	ds_bpermute_b32 v176, v147, v159
	ds_bpermute_b32 v177, v147, v160
	ds_bpermute_b32 v179, v147, v163
	ds_bpermute_b32 v147, v147, v170
	ds_bpermute_b32 v180, v149, v178
	s_waitcnt lgkmcnt(7)
	v_add_f32_e32 v175, v153, v171
	s_waitcnt lgkmcnt(6)
	v_add_f32_e32 v173, v155, v172
	s_waitcnt lgkmcnt(5)
	v_add_f32_e32 v171, v157, v174
	s_waitcnt lgkmcnt(4)
	v_add_f32_e32 v159, v159, v176
	s_waitcnt lgkmcnt(3)
	v_add_f32_e32 v155, v160, v177
	s_waitcnt lgkmcnt(2)
	v_add_f32_e32 v151, v163, v179
	s_waitcnt lgkmcnt(1)
	v_add_f32_e32 v147, v170, v147
	s_waitcnt lgkmcnt(0)
	v_add_f32_e32 v160, v178, v180
	ds_bpermute_b32 v176, v149, v175
	ds_bpermute_b32 v174, v149, v173
	ds_bpermute_b32 v172, v149, v171
	ds_bpermute_b32 v170, v149, v159
	ds_bpermute_b32 v157, v149, v155
	ds_bpermute_b32 v153, v149, v151
	v_fmamk_f32 v160, v160, 0x3a800000, v169
	ds_bpermute_b32 v149, v149, v147
	v_rsq_f32_e32 v160, v160
	v_mad_i64_i32 v[162:163], s[46:47], v162, s58, v[138:139]
	s_cbranch_vccz .LBB0_665
	v_mul_f32_e32 v177, v116, v160
	v_mul_f32_e32 v179, v117, v160
	v_mul_f32_e32 v178, 0xbfb8aa3b, v177
	v_mul_f32_e32 v180, 0xbfb8aa3b, v179
	v_exp_f32_e32 v178, v178
	v_exp_f32_e32 v180, v180
	v_mul_f32_e32 v181, v124, v160
	v_mul_f32_e32 v183, v126, v160
	v_add_f32_e32 v178, 1.0, v178
	v_add_f32_e32 v180, 1.0, v180
	v_rcp_f32_e32 v178, v178
	v_rcp_f32_e32 v180, v180
	v_mul_f32_e32 v185, v120, v160
	v_mul_f32_e32 v187, v122, v160
	v_cndmask_b32_e64 v177, v177, v178, s[0:1]
	v_mul_f32_e32 v178, v125, v160
	v_cndmask_b32_e64 v179, v179, v180, s[0:1]
	v_mul_f32_e32 v177, v181, v177
	v_mul_f32_e32 v178, v178, v179
	v_mul_f32_e32 v179, v118, v160
	v_mul_f32_e32 v181, v119, v160
	v_mul_f32_e32 v180, 0xbfb8aa3b, v179
	v_mul_f32_e32 v182, 0xbfb8aa3b, v181
	v_exp_f32_e32 v180, v180
	v_exp_f32_e32 v182, v182
	v_cvt_pk_bf16_f32 v178, v177, v178
	s_mov_b64 s[50:51], 0
	v_add_f32_e32 v180, 1.0, v180
	v_add_f32_e32 v182, 1.0, v182
	v_rcp_f32_e32 v180, v180
	v_rcp_f32_e32 v182, v182
	v_cndmask_b32_e64 v179, v179, v180, s[0:1]
	v_mul_f32_e32 v180, v127, v160
	v_cndmask_b32_e64 v181, v181, v182, s[0:1]
	v_mul_f32_e32 v179, v183, v179
	v_mul_f32_e32 v180, v180, v181
	v_mul_f32_e32 v181, v112, v160
	v_mul_f32_e32 v183, v113, v160
	v_mul_f32_e32 v182, 0xbfb8aa3b, v181
	v_mul_f32_e32 v184, 0xbfb8aa3b, v183
	v_exp_f32_e32 v182, v182
	v_exp_f32_e32 v184, v184
	v_cvt_pk_bf16_f32 v179, v179, v180
	v_add_f32_e32 v182, 1.0, v182
	v_add_f32_e32 v184, 1.0, v184
	v_rcp_f32_e32 v182, v182
	v_rcp_f32_e32 v184, v184
	v_cndmask_b32_e64 v181, v181, v182, s[0:1]
	v_mul_f32_e32 v182, v121, v160
	v_cndmask_b32_e64 v183, v183, v184, s[0:1]
	v_mul_f32_e32 v182, v182, v183
	v_mul_f32_e32 v183, v114, v160
	v_mul_f32_e32 v181, v185, v181
	v_mul_f32_e32 v184, 0xbfb8aa3b, v183
	v_mul_f32_e32 v185, v115, v160
	v_exp_f32_e32 v184, v184
	v_mul_f32_e32 v186, 0xbfb8aa3b, v185
	v_exp_f32_e32 v186, v186
	v_cvt_pk_bf16_f32 v180, v181, v182
	v_add_f32_e32 v184, 1.0, v184
	v_rcp_f32_e32 v184, v184
	v_add_f32_e32 v186, 1.0, v186
	v_rcp_f32_e32 v186, v186
	v_cndmask_b32_e64 v183, v183, v184, s[0:1]
	v_mul_f32_e32 v183, v187, v183
	v_mul_f32_e32 v184, v123, v160
	v_cndmask_b32_e64 v185, v185, v186, s[0:1]
	v_mul_f32_e32 v184, v184, v185
	v_cvt_pk_bf16_f32 v181, v183, v184
	v_lshl_add_u64 v[182:183], s[44:45], 1, v[162:163]
	global_store_dwordx4 v[182:183], v[178:181], off offset:1024

; __device__ __forceinline__ unsigned cvt_pk_bf16(float lo, float hi) { unsigned r; asm volatile("v_cvt_pk_bf16_f32 %0, %1, %2" : "=v"(r) : "v"(lo), "v"(hi)); return r; }
; __device__ __forceinline__ float bf_lo(unsigned w) { return __uint_as_float(w << 16); }
; __device__ __forceinline__ float bf_hi(unsigned w) { return __uint_as_float(w & 0xffff0000u); }
; __device__ __forceinline__ void conv_unit(CLAS unsigned char* lds, const bf16_t* __restrict__ PC, bf16_t* __restrict__ YC, const float* __restrict__ w3, const float* __restrict__ w31, ...
;     ...
; #pragma unroll
;         for (int i = 0; i < 18; ++i) { const int tok = tb - 1 + i; pw[i] = 0u; if (tok >= 0 && tok < S) pw[i] = *(const unsigned*)(PC + (size_t)(seq_base + tok) * 1536 + 512 + 2 * cp); }
; #pragma unroll
;         for (int i = 0; i < 16; ++i) gw[i] = *(const unsigned*)(PC + (size_t)(seq_base + tb + i) * 1536 + 2 * cp);
; #pragma unroll
;         for (int i = 0; i < 16; ++i) {
;             const float ya = bf_lo(gw[i]) * (wa0 * bf_lo(pw[i]) + wa1 * bf_lo(pw[i + 1]) + wa2 * bf_lo(pw[i + 2]));
;             const float yb = bf_hi(gw[i]) * (wb0 * bf_hi(pw[i]) + wb1 * bf_hi(pw[i + 1]) + wb2 * bf_hi(pw[i + 2]));
;             *(unsigned*)(YC + (size_t)(seq_base + tb + i) * 1024 + 2 * cp) = cvt_pk_bf16(ya, yb);
.LBB0_756:
	s_or_b64 exec, exec, s[16:17]
	v_mad_i64_i32 v[10:11], s[4:5], v6, s18, v[36:37]
	global_load_dword v121, v[10:11], off
	v_or_b32_e32 v124, 2, v6
	v_or_b32_e32 v128, 4, v6
	v_or_b32_e32 v122, 1, v6
	v_mad_i64_i32 v[134:135], s[4:5], v124, s18, v[36:37]
	v_mad_i64_i32 v[138:139], s[4:5], v128, s18, v[36:37]
	global_load_dword v194, v[134:135], off
	global_load_dword v196, v[138:139], off
	v_mad_i64_i32 v[10:11], s[4:5], v122, s18, v[36:37]
	global_load_dword v177, v[10:11], off
	v_or_b32_e32 v126, 3, v6
	v_mad_i64_i32 v[136:137], s[4:5], v126, s18, v[36:37]
	global_load_dword v195, v[136:137], off
	v_or_b32_e32 v130, 5, v6
	v_or_b32_e32 v132, 6, v6
	v_or_b32_e32 v24, 7, v6
	v_or_b32_e32 v22, 8, v6
	v_or_b32_e32 v18, 10, v6
	v_or_b32_e32 v8, 15, v6
	v_or_b32_e32 v20, 9, v6
	v_or_b32_e32 v16, 11, v6
	v_or_b32_e32 v14, 12, v6
	v_or_b32_e32 v12, 13, v6
	v_or_b32_e32 v10, 14, v6
	v_mad_i64_i32 v[134:135], s[4:5], v130, s18, v[36:37]
	v_mad_i64_i32 v[140:141], s[4:5], v132, s18, v[36:37]
	v_mad_i64_i32 v[178:179], s[4:5], v24, s18, v[36:37]
	v_mad_i64_i32 v[180:181], s[4:5], v22, s18, v[36:37]
	v_mad_i64_i32 v[136:137], s[4:5], v18, s18, v[36:37]
	v_mad_i64_i32 v[138:139], s[4:5], v8, s18, v[36:37]
	v_mad_i64_i32 v[182:183], s[4:5], v20, s18, v[36:37]
	v_mad_i64_i32 v[184:185], s[4:5], v16, s18, v[36:37]
	v_mad_i64_i32 v[186:187], s[4:5], v14, s18, v[36:37]
	v_mad_i64_i32 v[188:189], s[4:5], v12, s18, v[36:37]
	v_mad_i64_i32 v[190:191], s[4:5], v10, s18, v[36:37]
	global_load_dword v134, v[134:135], off
	s_nop 0
	global_load_dword v135, v[140:141], off
	s_nop 0
	global_load_dword v140, v[178:179], off
	global_load_dword v141, v[180:181], off
	s_nop 0
	global_load_dword v178, v[182:183], off
	s_nop 0
	global_load_dword v136, v[136:137], off
	s_nop 0
	global_load_dword v137, v[184:185], off
	global_load_dword v179, v[186:187], off
	global_load_dword v180, v[188:189], off
	global_load_dword v181, v[190:191], off
	s_nop 0
	global_load_dword v138, v[138:139], off
	s_waitcnt vmcnt(16)
	v_lshlrev_b32_e32 v193, 16, v112
	v_and_b32_e32 v112, 0xffff0000, v112
	v_lshlrev_b32_e32 v192, 16, v115
	v_and_b32_e32 v115, 0xffff0000, v115
	v_mul_f32_e32 v183, v5, v112
	v_ashrrev_i32_e32 v7, 31, v6
	v_mul_f32_e32 v197, v4, v193
	v_fmac_f32_e32 v183, v3, v115
	v_and_b32_e32 v115, 0xffff0000, v120
	v_fmac_f32_e32 v197, v2, v192
	v_lshlrev_b32_e32 v182, 16, v120
	v_fmac_f32_e32 v183, v1, v115
	v_lshlrev_b64 v[6:7], 11, v[6:7]
	v_fmac_f32_e32 v197, v0, v182
	v_lshl_add_u64 v[6:7], v[38:39], 0, v[6:7]
	v_ashrrev_i32_e32 v123, 31, v122
	v_ashrrev_i32_e32 v125, 31, v124
	v_ashrrev_i32_e32 v127, 31, v126
	v_ashrrev_i32_e32 v129, 31, v128
	v_ashrrev_i32_e32 v131, 31, v130
	v_ashrrev_i32_e32 v133, 31, v132
	v_ashrrev_i32_e32 v25, 31, v24
	v_ashrrev_i32_e32 v23, 31, v22
	v_ashrrev_i32_e32 v21, 31, v20
	v_ashrrev_i32_e32 v19, 31, v18
	v_ashrrev_i32_e32 v17, 31, v16
	v_ashrrev_i32_e32 v15, 31, v14
	v_ashrrev_i32_e32 v13, 31, v12
	v_ashrrev_i32_e32 v11, 31, v10
	s_waitcnt vmcnt(15)
	v_lshlrev_b32_e32 v139, 16, v121
	v_and_b32_e32 v121, 0xffff0000, v121
	v_mul_f32_e32 v120, v183, v121
	v_mul_f32_e32 v139, v197, v139
	v_cvt_pk_bf16_f32 v120, v139, v120
	global_store_dword v[6:7], v120, off
	v_mul_f32_e32 v7, v4, v182
	v_fmac_f32_e32 v7, v2, v193
	v_lshlrev_b32_e32 v120, 16, v116
	v_mul_f32_e32 v121, v5, v115
	v_fmac_f32_e32 v7, v0, v120
	v_fmac_f32_e32 v121, v3, v112
	s_waitcnt vmcnt(13)
	v_lshlrev_b32_e32 v6, 16, v177
	v_and_b32_e32 v112, 0xffff0000, v116
	v_mul_f32_e32 v6, v7, v6
	v_and_b32_e32 v7, 0xffff0000, v177
	v_fmac_f32_e32 v121, v1, v112
	v_mul_f32_e32 v7, v121, v7
	v_cvt_pk_bf16_f32 v116, v6, v7
	v_lshlrev_b64 v[6:7], 11, v[122:123]
	v_lshl_add_u64 v[6:7], v[38:39], 0, v[6:7]
	global_store_dword v[6:7], v116, off
	v_mul_f32_e32 v7, v4, v120
	v_fmac_f32_e32 v7, v2, v182
	v_lshlrev_b32_e32 v116, 16, v119
	v_mul_f32_e32 v121, v5, v112
	v_lshlrev_b32_e32 v6, 16, v194
	v_fmac_f32_e32 v7, v0, v116
	v_fmac_f32_e32 v121, v3, v115
	v_and_b32_e32 v115, 0xffff0000, v119
	v_mul_f32_e32 v6, v7, v6
	v_and_b32_e32 v7, 0xffff0000, v194
	v_fmac_f32_e32 v121, v1, v115
	v_mul_f32_e32 v7, v121, v7
	v_cvt_pk_bf16_f32 v119, v6, v7
	v_lshlrev_b64 v[6:7], 11, v[124:125]
	v_lshl_add_u64 v[6:7], v[38:39], 0, v[6:7]
	global_store_dword v[6:7], v119, off
	v_mul_f32_e32 v7, v4, v116
	v_fmac_f32_e32 v7, v2, v120
	v_lshlrev_b32_e32 v119, 16, v113
	v_mul_f32_e32 v120, v5, v115
	s_waitcnt vmcnt(14)
	v_lshlrev_b32_e32 v6, 16, v195
	v_fmac_f32_e32 v7, v0, v119
	v_fmac_f32_e32 v120, v3, v112
	v_and_b32_e32 v112, 0xffff0000, v113
	v_mul_f32_e32 v6, v7, v6
	v_and_b32_e32 v7, 0xffff0000, v195
	v_fmac_f32_e32 v120, v1, v112
	v_mul_f32_e32 v7, v120, v7
	v_cvt_pk_bf16_f32 v113, v6, v7
	v_lshlrev_b64 v[6:7], 11, v[126:127]
	v_lshl_add_u64 v[6:7], v[38:39], 0, v[6:7]
	global_store_dword v[6:7], v113, off
	v_mul_f32_e32 v7, v4, v119
	v_fmac_f32_e32 v7, v2, v116
	v_lshlrev_b32_e32 v113, 16, v118
	v_mul_f32_e32 v116, v5, v112
	v_lshlrev_b32_e32 v6, 16, v196
	v_fmac_f32_e32 v7, v0, v113
	v_fmac_f32_e32 v116, v3, v115
	v_and_b32_e32 v115, 0xffff0000, v118
	v_mul_f32_e32 v6, v7, v6
	v_and_b32_e32 v7, 0xffff0000, v196
	v_fmac_f32_e32 v116, v1, v115
	v_mul_f32_e32 v7, v116, v7
	v_cvt_pk_bf16_f32 v116, v6, v7
	v_lshlrev_b64 v[6:7], 11, v[128:129]
	v_lshl_add_u64 v[6:7], v[38:39], 0, v[6:7]
	global_store_dword v[6:7], v116, off
	v_mul_f32_e32 v7, v4, v113
	v_fmac_f32_e32 v7, v2, v119
	v_lshlrev_b32_e32 v116, 16, v110
	v_mul_f32_e32 v118, v5, v115
	s_waitcnt vmcnt(15)
; __device__ __forceinline__ unsigned cvt_pk_bf16(float lo, float hi) { unsigned r; asm volatile("v_cvt_pk_bf16_f32 %0, %1, %2" : "=v"(r) : "v"(lo), "v"(hi)); return r; }
; __device__ __forceinline__ float bf_lo(unsigned w) { return __uint_as_float(w << 16); }
; __device__ __forceinline__ float bf_hi(unsigned w) { return __uint_as_float(w & 0xffff0000u); }
; __device__ __forceinline__ void conv_unit(CLAS unsigned char* lds, const bf16_t* __restrict__ PC, bf16_t* __restrict__ YC, const float* __restrict__ w3, const float* __restrict__ w31, ...
;     ...
; #pragma unroll
;         for (int i = 0; i < 16; ++i) {
;             const float ya = bf_lo(gw[i]) * (wa0 * bf_lo(pw[i]) + wa1 * bf_lo(pw[i + 1]) + wa2 * bf_lo(pw[i + 2]));
;             const float yb = bf_hi(gw[i]) * (wb0 * bf_hi(pw[i]) + wb1 * bf_hi(pw[i + 1]) + wb2 * bf_hi(pw[i + 2]));
;             *(unsigned*)(YC + (size_t)(seq_base + tb + i) * 1024 + 2 * cp) = cvt_pk_bf16(ya, yb);
	v_lshlrev_b32_e32 v6, 16, v134
	v_fmac_f32_e32 v7, v0, v116
	v_fmac_f32_e32 v118, v3, v112
	v_and_b32_e32 v110, 0xffff0000, v110
	v_mul_f32_e32 v6, v7, v6
	v_and_b32_e32 v7, 0xffff0000, v134
	v_fmac_f32_e32 v118, v1, v110
	v_mul_f32_e32 v7, v118, v7
	v_cvt_pk_bf16_f32 v112, v6, v7
	v_lshlrev_b64 v[6:7], 11, v[130:131]
	v_lshl_add_u64 v[6:7], v[38:39], 0, v[6:7]
	global_store_dword v[6:7], v112, off
	v_mul_f32_e32 v7, v4, v116
	v_fmac_f32_e32 v7, v2, v113
	v_lshlrev_b32_e32 v112, 16, v117
	v_mul_f32_e32 v113, v5, v110
	s_waitcnt vmcnt(15)
	v_lshlrev_b32_e32 v6, 16, v135
	v_fmac_f32_e32 v7, v0, v112
	v_fmac_f32_e32 v113, v3, v115
	v_and_b32_e32 v115, 0xffff0000, v117
	v_mul_f32_e32 v6, v7, v6
	v_and_b32_e32 v7, 0xffff0000, v135
	v_fmac_f32_e32 v113, v1, v115
	v_mul_f32_e32 v7, v113, v7
	v_cvt_pk_bf16_f32 v113, v6, v7
	v_lshlrev_b64 v[6:7], 11, v[132:133]
	v_lshl_add_u64 v[6:7], v[38:39], 0, v[6:7]
	global_store_dword v[6:7], v113, off
	v_mul_f32_e32 v7, v4, v112
	v_fmac_f32_e32 v7, v2, v116
	v_lshlrev_b32_e32 v113, 16, v30
	v_mul_f32_e32 v116, v5, v115
	s_waitcnt vmcnt(15)
	v_lshlrev_b32_e32 v6, 16, v140
	v_fmac_f32_e32 v7, v0, v113
	v_fmac_f32_e32 v116, v3, v110
	v_and_b32_e32 v30, 0xffff0000, v30
	v_mul_f32_e32 v6, v7, v6
	v_and_b32_e32 v7, 0xffff0000, v140
	v_fmac_f32_e32 v116, v1, v30
	v_mul_f32_e32 v7, v116, v7
	v_cvt_pk_bf16_f32 v110, v6, v7
	v_lshlrev_b64 v[6:7], 11, v[24:25]
	v_lshl_add_u64 v[6:7], v[38:39], 0, v[6:7]
	global_store_dword v[6:7], v110, off
	v_mul_f32_e32 v7, v4, v113
	v_fmac_f32_e32 v7, v2, v112
	v_lshlrev_b32_e32 v24, 16, v114
	v_mul_f32_e32 v25, v5, v30
	s_waitcnt vmcnt(15)
	v_lshlrev_b32_e32 v6, 16, v141
	v_fmac_f32_e32 v7, v0, v24
	v_fmac_f32_e32 v25, v3, v115
	v_and_b32_e32 v110, 0xffff0000, v114
	v_mul_f32_e32 v6, v7, v6
	v_and_b32_e32 v7, 0xffff0000, v141
	v_fmac_f32_e32 v25, v1, v110
	v_mul_f32_e32 v7, v25, v7
	v_cvt_pk_bf16_f32 v25, v6, v7
	v_lshlrev_b64 v[6:7], 11, v[22:23]
	v_lshl_add_u64 v[6:7], v[38:39], 0, v[6:7]
	global_store_dword v[6:7], v25, off
	v_mul_f32_e32 v7, v4, v24
	v_fmac_f32_e32 v7, v2, v113
	v_lshlrev_b32_e32 v22, 16, v28
	v_mul_f32_e32 v23, v5, v110
	s_waitcnt vmcnt(15)
	v_lshlrev_b32_e32 v6, 16, v178
	v_fmac_f32_e32 v7, v0, v22
	v_fmac_f32_e32 v23, v3, v30
	v_and_b32_e32 v25, 0xffff0000, v28
	v_mul_f32_e32 v6, v7, v6
	v_and_b32_e32 v7, 0xffff0000, v178
	v_fmac_f32_e32 v23, v1, v25
	v_mul_f32_e32 v7, v23, v7
	v_cvt_pk_bf16_f32 v23, v6, v7
	v_lshlrev_b64 v[6:7], 11, v[20:21]
	v_lshl_add_u64 v[6:7], v[38:39], 0, v[6:7]
	global_store_dword v[6:7], v23, off
	v_mul_f32_e32 v7, v4, v22
	v_fmac_f32_e32 v7, v2, v24
	v_lshlrev_b32_e32 v20, 16, v111
	v_mul_f32_e32 v21, v5, v25
	s_waitcnt vmcnt(15)
	v_lshlrev_b32_e32 v6, 16, v136
	v_fmac_f32_e32 v7, v0, v20
	v_fmac_f32_e32 v21, v3, v110
	v_and_b32_e32 v23, 0xffff0000, v111
	v_mul_f32_e32 v6, v7, v6
	v_and_b32_e32 v7, 0xffff0000, v136
	v_fmac_f32_e32 v21, v1, v23
	v_mul_f32_e32 v7, v21, v7
	v_cvt_pk_bf16_f32 v21, v6, v7
	v_lshlrev_b64 v[6:7], 11, v[18:19]
	v_lshl_add_u64 v[6:7], v[38:39], 0, v[6:7]
	global_store_dword v[6:7], v21, off
	v_mul_f32_e32 v7, v4, v20
	v_fmac_f32_e32 v7, v2, v22
	v_lshlrev_b32_e32 v18, 16, v27
	v_mul_f32_e32 v19, v5, v23
	s_waitcnt vmcnt(15)
	v_lshlrev_b32_e32 v6, 16, v137
	v_fmac_f32_e32 v7, v0, v18
	v_fmac_f32_e32 v19, v3, v25
	v_and_b32_e32 v21, 0xffff0000, v27
	v_mul_f32_e32 v6, v7, v6
	v_and_b32_e32 v7, 0xffff0000, v137
	v_fmac_f32_e32 v19, v1, v21
	v_mul_f32_e32 v7, v19, v7
	v_cvt_pk_bf16_f32 v19, v6, v7
	v_lshlrev_b64 v[6:7], 11, v[16:17]
	v_lshl_add_u64 v[6:7], v[38:39], 0, v[6:7]
	global_store_dword v[6:7], v19, off
	v_mul_f32_e32 v7, v4, v18
	v_fmac_f32_e32 v7, v2, v20
	v_lshlrev_b32_e32 v16, 16, v31
	v_mul_f32_e32 v17, v5, v21
	s_waitcnt vmcnt(15)
	v_lshlrev_b32_e32 v6, 16, v179
	v_fmac_f32_e32 v7, v0, v16
	v_fmac_f32_e32 v17, v3, v23
	v_and_b32_e32 v19, 0xffff0000, v31
	v_mul_f32_e32 v6, v7, v6
	v_and_b32_e32 v7, 0xffff0000, v179
	v_fmac_f32_e32 v17, v1, v19
	v_mul_f32_e32 v7, v17, v7
	v_cvt_pk_bf16_f32 v17, v6, v7
	v_lshlrev_b64 v[6:7], 11, v[14:15]
	v_lshl_add_u64 v[6:7], v[38:39], 0, v[6:7]
	global_store_dword v[6:7], v17, off
	v_mul_f32_e32 v7, v4, v16
	v_fmac_f32_e32 v7, v2, v18
	v_lshlrev_b32_e32 v14, 16, v26
	v_mul_f32_e32 v15, v5, v19
	s_waitcnt vmcnt(15)
	v_lshlrev_b32_e32 v6, 16, v180
	v_fmac_f32_e32 v7, v0, v14
	v_fmac_f32_e32 v15, v3, v21
	v_and_b32_e32 v17, 0xffff0000, v26
	v_mul_f32_e32 v6, v7, v6
	v_and_b32_e32 v7, 0xffff0000, v180
	v_fmac_f32_e32 v15, v1, v17
	v_mul_f32_e32 v7, v15, v7
	v_cvt_pk_bf16_f32 v15, v6, v7
	v_lshlrev_b64 v[6:7], 11, v[12:13]
	v_lshl_add_u64 v[6:7], v[38:39], 0, v[6:7]
	global_store_dword v[6:7], v15, off
	v_mul_f32_e32 v7, v4, v14
	v_fmac_f32_e32 v7, v2, v16
	v_lshlrev_b32_e32 v12, 16, v29
	v_mul_f32_e32 v13, v5, v17
	s_waitcnt vmcnt(15)
	v_lshlrev_b32_e32 v6, 16, v181
	v_fmac_f32_e32 v7, v0, v12
	v_fmac_f32_e32 v13, v3, v19
	v_and_b32_e32 v15, 0xffff0000, v29
	v_mul_f32_e32 v6, v7, v6
	v_and_b32_e32 v7, 0xffff0000, v181
	v_fmac_f32_e32 v13, v1, v15
	v_mul_f32_e32 v7, v13, v7
	v_cvt_pk_bf16_f32 v13, v6, v7
	v_lshlrev_b64 v[6:7], 11, v[10:11]
	v_mul_f32_e32 v4, v4, v12
	v_lshl_add_u64 v[6:7], v[38:39], 0, v[6:7]
	v_fmac_f32_e32 v4, v2, v14
	v_lshlrev_b32_e32 v2, 16, v9
	global_store_dword v[6:7], v13, off
	s_waitcnt vmcnt(15)
; __device__ __forceinline__ unsigned cvt_pk_bf16(float lo, float hi) { unsigned r; asm volatile("v_cvt_pk_bf16_f32 %0, %1, %2" : "=v"(r) : "v"(lo), "v"(hi)); return r; }
; __device__ __forceinline__ float bf_lo(unsigned w) { return __uint_as_float(w << 16); }
; __device__ __forceinline__ float bf_hi(unsigned w) { return __uint_as_float(w & 0xffff0000u); }
; #define CLAS __attribute__((address_space(3)))
; __device__ __forceinline__ void conv_unit(CLAS unsigned char* lds, const bf16_t* __restrict__ PC, bf16_t* __restrict__ YC, const float* __restrict__ w3, const float* __restrict__ w31, ...
;     ...
;         for (int i = 0; i < 16; ++i) gw[i] = *(const unsigned*)(PC + (size_t)(seq_base + tb + i) * 1536 + 2 * cp);
; #pragma unroll
;         for (int i = 0; i < 16; ++i) {
;             const float ya = bf_lo(gw[i]) * (wa0 * bf_lo(pw[i]) + wa1 * bf_lo(pw[i + 1]) + wa2 * bf_lo(pw[i + 2]));
;             const float yb = bf_hi(gw[i]) * (wb0 * bf_hi(pw[i]) + wb1 * bf_hi(pw[i + 1]) + wb2 * bf_hi(pw[i + 2]));
;             *(unsigned*)(YC + (size_t)(seq_base + tb + i) * 1024 + 2 * cp) = cvt_pk_bf16(ya, yb);
;         }
;     }
;     {
;         float wa[31], wb[31];
; #pragma unroll
;         for (int j = 0; j < 31; ++j) { wa[j] = w31[j * 512 + 2 * cp]; wb[j] = w31[j * 512 + 2 * cp + 1]; }
;         const float ba = dwb[2 * cp], bb = dwb[2 * cp + 1];
;         for (int g4 = 0; g4 < 4; ++g4) {
;             const int tt = 16 * th + 4 * g4;
;             float aa[4], ab[4];
; #pragma unroll
;             for (int k = 0; k < 4; ++k) { aa[k] = ba; ab[k] = bb; }
;             const CLAS unsigned char* up = lds + OFF_U0 + tt * 1024 + cp * 4;
; #pragma unroll
;             for (int rr = 0; rr < 34; ++rr) {
;                 const unsigned w = *(const CLAS unsigned*)(up + rr * 1024);
;                 const float xa = bf_lo(w), xb = bf_hi(w);
; #pragma unroll
;                 for (int k = 0; k < 4; ++k) { const int j = rr - k; if (j >= 0 && j < 31) { aa[k] += wa[j] * xa; ab[k] += wb[j] * xb; } }
	v_lshlrev_b32_e32 v6, 16, v138
	v_fmac_f32_e32 v4, v0, v2
	v_mul_f32_e32 v0, v4, v6
	v_mul_f32_e32 v4, v5, v15
	v_fmac_f32_e32 v4, v3, v17
	v_and_b32_e32 v3, 0xffff0000, v9
	v_and_b32_e32 v2, 0xffff0000, v138
	v_fmac_f32_e32 v4, v1, v3
	v_mul_f32_e32 v1, v4, v2
	v_ashrrev_i32_e32 v9, 31, v8
	v_cvt_pk_bf16_f32 v2, v0, v1
	global_load_dwordx2 v[122:123], v[100:101], off
	global_load_dwordx2 v[140:141], v[40:41], off
	global_load_dwordx2 v[138:139], v[40:41], off offset:2048
	global_load_dwordx2 v[136:137], v[42:43], off
	global_load_dwordx2 v[134:135], v[44:45], off
	global_load_dwordx2 v[132:133], v[46:47], off
	global_load_dwordx2 v[130:131], v[48:49], off
	global_load_dwordx2 v[128:129], v[50:51], off
	global_load_dwordx2 v[126:127], v[52:53], off
	global_load_dwordx2 v[124:125], v[54:55], off
	v_lshlrev_b64 v[0:1], 11, v[8:9]
	v_lshl_add_u64 v[0:1], v[38:39], 0, v[0:1]
	global_store_dword v[0:1], v2, off
	global_load_dwordx2 v[0:1], v[98:99], off
	s_nop 0
	global_load_dwordx2 v[2:3], v[96:97], off
	global_load_dwordx2 v[4:5], v[94:95], off
	global_load_dwordx2 v[6:7], v[92:93], off
	global_load_dwordx2 v[8:9], v[90:91], off
	global_load_dwordx2 v[10:11], v[88:89], off
	global_load_dwordx2 v[12:13], v[86:87], off
	global_load_dwordx2 v[14:15], v[84:85], off
	global_load_dwordx2 v[16:17], v[82:83], off
	global_load_dwordx2 v[18:19], v[80:81], off
	global_load_dwordx2 v[20:21], v[78:79], off
	global_load_dwordx2 v[22:23], v[76:77], off
	global_load_dwordx2 v[24:25], v[74:75], off
	global_load_dwordx2 v[26:27], v[72:73], off
	global_load_dwordx2 v[28:29], v[70:71], off
	global_load_dwordx2 v[110:111], v[60:61], off
	global_load_dwordx2 v[114:115], v[58:59], off
	global_load_dwordx2 v[118:119], v[56:57], off
	ds_read2st64_b32 v[178:179], v163 offset1:4
	global_load_dwordx2 v[30:31], v[68:69], off
	global_load_dwordx2 v[112:113], v[66:67], off
	global_load_dwordx2 v[116:117], v[64:65], off
	global_load_dwordx2 v[120:121], v[62:63], off
	ds_read2st64_b32 v[182:183], v163 offset0:8 offset1:12
	ds_read2st64_b32 v[184:185], v163 offset0:16 offset1:20
	ds_read2st64_b32 v[190:191], v163 offset0:24 offset1:28
	s_waitcnt lgkmcnt(3)
	v_and_b32_e32 v181, 0xffff0000, v178
	v_lshlrev_b32_e32 v180, 16, v178
	v_lshlrev_b32_e32 v178, 16, v179
	v_and_b32_e32 v179, 0xffff0000, v179
	s_waitcnt lgkmcnt(2)
	v_lshlrev_b32_e32 v186, 16, v182
	v_and_b32_e32 v187, 0xffff0000, v182
	v_lshlrev_b32_e32 v182, 16, v183
	v_and_b32_e32 v183, 0xffff0000, v183
	ds_read2st64_b32 v[192:193], v163 offset0:32 offset1:36
	s_waitcnt lgkmcnt(2)
	v_lshlrev_b32_e32 v188, 16, v184
	v_and_b32_e32 v189, 0xffff0000, v184
	v_lshlrev_b32_e32 v184, 16, v185
	v_and_b32_e32 v185, 0xffff0000, v185
	ds_read2st64_b32 v[198:199], v163 offset0:40 offset1:44
	s_waitcnt lgkmcnt(2)
	v_lshlrev_b32_e32 v194, 16, v190
	v_and_b32_e32 v195, 0xffff0000, v190
	v_lshlrev_b32_e32 v190, 16, v191
	v_and_b32_e32 v191, 0xffff0000, v191
	ds_read2st64_b32 v[202:203], v163 offset0:48 offset1:52
	s_waitcnt lgkmcnt(2)
	v_lshlrev_b32_e32 v196, 16, v192
	v_and_b32_e32 v197, 0xffff0000, v192
	v_lshlrev_b32_e32 v192, 16, v193
	v_and_b32_e32 v193, 0xffff0000, v193
	ds_read2st64_b32 v[204:205], v163 offset0:56 offset1:60
	s_waitcnt lgkmcnt(2)
	v_lshlrev_b32_e32 v200, 16, v198
	v_and_b32_e32 v201, 0xffff0000, v198
	v_lshlrev_b32_e32 v198, 16, v199
	v_and_b32_e32 v199, 0xffff0000, v199
	ds_read2st64_b32 v[210:211], v163 offset0:64 offset1:68
	s_waitcnt lgkmcnt(2)
	v_lshlrev_b32_e32 v206, 16, v202
	v_and_b32_e32 v207, 0xffff0000, v202
	v_lshlrev_b32_e32 v202, 16, v203
	v_and_b32_e32 v203, 0xffff0000, v203
	ds_read2st64_b32 v[212:213], v163 offset0:72 offset1:76
	s_waitcnt lgkmcnt(2)
	v_lshlrev_b32_e32 v208, 16, v204
	v_and_b32_e32 v209, 0xffff0000, v204
	v_lshlrev_b32_e32 v204, 16, v205
	v_and_b32_e32 v205, 0xffff0000, v205
	s_waitcnt lgkmcnt(1)
	v_lshlrev_b32_e32 v214, 16, v210
	v_and_b32_e32 v215, 0xffff0000, v210
	v_lshlrev_b32_e32 v210, 16, v211
	v_and_b32_e32 v211, 0xffff0000, v211
	s_waitcnt lgkmcnt(0)
	v_lshlrev_b32_e32 v216, 16, v212
	v_and_b32_e32 v217, 0xffff0000, v212
	v_lshlrev_b32_e32 v212, 16, v213
	v_and_b32_e32 v213, 0xffff0000, v213
	ds_read2st64_b32 v[218:219], v163 offset0:112 offset1:116
	ds_read2st64_b32 v[220:221], v163 offset0:120 offset1:124
	s_add_i32 s22, s22, s74
	s_sub_i32 s19, s19, s74
	s_cmpk_lt_i32 s22, 0x1000
	s_waitcnt lgkmcnt(1)
	v_lshlrev_b32_e32 v222, 16, v218
	v_and_b32_e32 v223, 0xffff0000, v218
	v_lshlrev_b32_e32 v218, 16, v219
	v_and_b32_e32 v219, 0xffff0000, v219
	s_waitcnt lgkmcnt(0)
	v_lshlrev_b32_e32 v224, 16, v220
	v_and_b32_e32 v225, 0xffff0000, v220
	s_waitcnt vmcnt(31)
	v_pk_fma_f32 v[180:181], v[140:141], v[180:181], v[122:123]
	s_waitcnt vmcnt(30)
	v_pk_fma_f32 v[180:181], v[138:139], v[178:179], v[180:181]
	v_pk_fma_f32 v[178:179], v[140:141], v[178:179], v[122:123]
	s_waitcnt vmcnt(29)
	v_pk_fma_f32 v[180:181], v[136:137], v[186:187], v[180:181]
	v_pk_fma_f32 v[178:179], v[138:139], v[186:187], v[178:179]
	v_pk_fma_f32 v[186:187], v[140:141], v[186:187], v[122:123]
	s_waitcnt vmcnt(28)
	v_pk_fma_f32 v[180:181], v[134:135], v[182:183], v[180:181]
	v_pk_fma_f32 v[178:179], v[136:137], v[182:183], v[178:179]
	v_pk_fma_f32 v[186:187], v[138:139], v[182:183], v[186:187]
	v_pk_fma_f32 v[182:183], v[140:141], v[182:183], v[122:123]
	v_pk_fma_f32 v[178:179], v[134:135], v[188:189], v[178:179]
	v_pk_fma_f32 v[182:183], v[138:139], v[188:189], v[182:183]
	v_pk_fma_f32 v[186:187], v[136:137], v[188:189], v[186:187]
	v_pk_fma_f32 v[182:183], v[136:137], v[184:185], v[182:183]
	s_waitcnt vmcnt(27)
; __device__ __forceinline__ float bf_lo(unsigned w) { return __uint_as_float(w << 16); }
; __device__ __forceinline__ float bf_hi(unsigned w) { return __uint_as_float(w & 0xffff0000u); }
; #define CLAS __attribute__((address_space(3)))
; __device__ __forceinline__ void conv_unit(CLAS unsigned char* lds, const bf16_t* __restrict__ PC, bf16_t* __restrict__ YC, const float* __restrict__ w3, const float* __restrict__ w31, ...
;     ...
;             const CLAS unsigned char* up = lds + OFF_U0 + tt * 1024 + cp * 4;
; #pragma unroll
;             for (int rr = 0; rr < 34; ++rr) {
;                 const unsigned w = *(const CLAS unsigned*)(up + rr * 1024);
;                 const float xa = bf_lo(w), xb = bf_hi(w);
; #pragma unroll
;                 for (int k = 0; k < 4; ++k) { const int j = rr - k; if (j >= 0 && j < 31) { aa[k] += wa[j] * xa; ab[k] += wb[j] * xb; } }
;             }
	v_pk_fma_f32 v[180:181], v[132:133], v[188:189], v[180:181]
	v_pk_fma_f32 v[178:179], v[132:133], v[184:185], v[178:179]
	v_pk_fma_f32 v[186:187], v[134:135], v[184:185], v[186:187]
	v_pk_fma_f32 v[182:183], v[134:135], v[194:195], v[182:183]
	s_waitcnt vmcnt(26)
	v_pk_fma_f32 v[180:181], v[130:131], v[184:185], v[180:181]
	v_pk_fma_f32 v[178:179], v[130:131], v[194:195], v[178:179]
	v_pk_fma_f32 v[186:187], v[132:133], v[194:195], v[186:187]
	v_pk_fma_f32 v[182:183], v[132:133], v[190:191], v[182:183]
	s_waitcnt vmcnt(25)
	v_pk_fma_f32 v[180:181], v[128:129], v[194:195], v[180:181]
	v_pk_fma_f32 v[178:179], v[128:129], v[190:191], v[178:179]
	v_pk_fma_f32 v[186:187], v[130:131], v[190:191], v[186:187]
	v_pk_fma_f32 v[182:183], v[130:131], v[196:197], v[182:183]
	s_waitcnt vmcnt(24)
	v_pk_fma_f32 v[180:181], v[126:127], v[190:191], v[180:181]
	v_pk_fma_f32 v[178:179], v[126:127], v[196:197], v[178:179]
	v_pk_fma_f32 v[186:187], v[128:129], v[196:197], v[186:187]
	v_pk_fma_f32 v[182:183], v[128:129], v[192:193], v[182:183]
	s_waitcnt vmcnt(23)
	v_pk_fma_f32 v[180:181], v[124:125], v[196:197], v[180:181]
	v_pk_fma_f32 v[178:179], v[124:125], v[192:193], v[178:179]
	v_pk_fma_f32 v[186:187], v[126:127], v[192:193], v[186:187]
	v_pk_fma_f32 v[182:183], v[126:127], v[200:201], v[182:183]
	v_pk_fma_f32 v[186:187], v[124:125], v[200:201], v[186:187]
	s_waitcnt vmcnt(4)
	v_pk_fma_f32 v[180:181], v[118:119], v[192:193], v[180:181]
	v_pk_fma_f32 v[182:183], v[124:125], v[198:199], v[182:183]
	v_pk_fma_f32 v[178:179], v[118:119], v[200:201], v[178:179]
	v_pk_fma_f32 v[180:181], v[114:115], v[200:201], v[180:181]
	v_pk_fma_f32 v[178:179], v[114:115], v[198:199], v[178:179]
	v_pk_fma_f32 v[186:187], v[118:119], v[198:199], v[186:187]
	v_pk_fma_f32 v[182:183], v[118:119], v[206:207], v[182:183]
	v_pk_fma_f32 v[180:181], v[110:111], v[198:199], v[180:181]
	v_pk_fma_f32 v[178:179], v[110:111], v[206:207], v[178:179]
	v_pk_fma_f32 v[186:187], v[114:115], v[206:207], v[186:187]
	v_pk_fma_f32 v[182:183], v[114:115], v[202:203], v[182:183]
	s_waitcnt vmcnt(0)
	v_pk_fma_f32 v[180:181], v[120:121], v[206:207], v[180:181]
	ds_read2st64_b32 v[184:185], v163 offset0:80 offset1:84
	v_pk_fma_f32 v[178:179], v[120:121], v[202:203], v[178:179]
	v_pk_fma_f32 v[186:187], v[110:111], v[202:203], v[186:187]
	v_pk_fma_f32 v[182:183], v[110:111], v[208:209], v[182:183]
	v_pk_fma_f32 v[180:181], v[116:117], v[202:203], v[180:181]
	v_pk_fma_f32 v[178:179], v[116:117], v[208:209], v[178:179]
	v_pk_fma_f32 v[186:187], v[120:121], v[208:209], v[186:187]
	v_pk_fma_f32 v[182:183], v[120:121], v[204:205], v[182:183]
	v_pk_fma_f32 v[180:181], v[112:113], v[208:209], v[180:181]
	v_pk_fma_f32 v[178:179], v[112:113], v[204:205], v[178:179]
	v_pk_fma_f32 v[186:187], v[116:117], v[204:205], v[186:187]
	ds_read2st64_b32 v[190:191], v163 offset0:88 offset1:92
	v_pk_fma_f32 v[182:183], v[116:117], v[214:215], v[182:183]
	v_pk_fma_f32 v[180:181], v[30:31], v[204:205], v[180:181]
	v_pk_fma_f32 v[178:179], v[30:31], v[214:215], v[178:179]
	v_pk_fma_f32 v[186:187], v[112:113], v[214:215], v[186:187]
	v_pk_fma_f32 v[182:183], v[112:113], v[210:211], v[182:183]
	v_pk_fma_f32 v[180:181], v[28:29], v[214:215], v[180:181]
	v_pk_fma_f32 v[178:179], v[28:29], v[210:211], v[178:179]
	v_pk_fma_f32 v[186:187], v[30:31], v[210:211], v[186:187]
	ds_read2st64_b32 v[194:195], v163 offset0:96 offset1:100
	v_pk_fma_f32 v[182:183], v[30:31], v[216:217], v[182:183]
	v_pk_fma_f32 v[180:181], v[26:27], v[210:211], v[180:181]
	s_waitcnt lgkmcnt(2)
	v_lshlrev_b32_e32 v188, 16, v184
	v_and_b32_e32 v189, 0xffff0000, v184
	v_pk_fma_f32 v[178:179], v[26:27], v[216:217], v[178:179]
	v_pk_fma_f32 v[186:187], v[28:29], v[216:217], v[186:187]
	v_pk_fma_f32 v[182:183], v[28:29], v[212:213], v[182:183]
	v_pk_fma_f32 v[180:181], v[24:25], v[216:217], v[180:181]
	v_pk_fma_f32 v[178:179], v[24:25], v[212:213], v[178:179]
	v_lshlrev_b32_e32 v184, 16, v185
	v_and_b32_e32 v185, 0xffff0000, v185
	v_pk_fma_f32 v[186:187], v[26:27], v[212:213], v[186:187]
	ds_read2st64_b32 v[196:197], v163 offset0:104 offset1:108
	v_pk_fma_f32 v[182:183], v[26:27], v[188:189], v[182:183]
	v_pk_fma_f32 v[180:181], v[22:23], v[212:213], v[180:181]
	v_pk_fma_f32 v[178:179], v[22:23], v[188:189], v[178:179]
	v_pk_fma_f32 v[186:187], v[24:25], v[188:189], v[186:187]
	s_waitcnt lgkmcnt(2)
	v_lshlrev_b32_e32 v192, 16, v190
	v_and_b32_e32 v193, 0xffff0000, v190
	v_pk_fma_f32 v[182:183], v[24:25], v[184:185], v[182:183]
	v_pk_fma_f32 v[186:187], v[22:23], v[184:185], v[186:187]
	v_lshlrev_b32_e32 v190, 16, v191
	v_and_b32_e32 v191, 0xffff0000, v191
	v_pk_fma_f32 v[180:181], v[20:21], v[188:189], v[180:181]
	v_pk_fma_f32 v[182:183], v[22:23], v[192:193], v[182:183]
	v_pk_fma_f32 v[178:179], v[20:21], v[184:185], v[178:179]
	s_waitcnt lgkmcnt(1)
	v_lshlrev_b32_e32 v198, 16, v194
	v_and_b32_e32 v199, 0xffff0000, v194
	v_pk_fma_f32 v[180:181], v[18:19], v[184:185], v[180:181]
	v_pk_fma_f32 v[178:179], v[18:19], v[192:193], v[178:179]
	v_pk_fma_f32 v[186:187], v[20:21], v[192:193], v[186:187]
	v_pk_fma_f32 v[182:183], v[20:21], v[190:191], v[182:183]
	v_lshlrev_b32_e32 v194, 16, v195
	v_and_b32_e32 v195, 0xffff0000, v195
	v_pk_fma_f32 v[180:181], v[16:17], v[192:193], v[180:181]
	v_pk_fma_f32 v[178:179], v[16:17], v[190:191], v[178:179]
	v_pk_fma_f32 v[186:187], v[18:19], v[190:191], v[186:187]
	v_pk_fma_f32 v[182:183], v[18:19], v[198:199], v[182:183]
	s_waitcnt lgkmcnt(0)
; __device__ __forceinline__ float bf_lo(unsigned w) { return __uint_as_float(w << 16); }
; __device__ __forceinline__ float bf_hi(unsigned w) { return __uint_as_float(w & 0xffff0000u); }
; #define CLAS __attribute__((address_space(3)))
; __device__ __forceinline__ void conv_unit(CLAS unsigned char* lds, const bf16_t* __restrict__ PC, bf16_t* __restrict__ YC, const float* __restrict__ w3, const float* __restrict__ w31, ...
;     ...
;             const CLAS unsigned char* up = lds + OFF_U0 + tt * 1024 + cp * 4;
; #pragma unroll
;             for (int rr = 0; rr < 34; ++rr) {
;                 const unsigned w = *(const CLAS unsigned*)(up + rr * 1024);
;                 const float xa = bf_lo(w), xb = bf_hi(w);
; #pragma unroll
;                 for (int k = 0; k < 4; ++k) { const int j = rr - k; if (j >= 0 && j < 31) { aa[k] += wa[j] * xa; ab[k] += wb[j] * xb; } }
;             }
; #pragma unroll
;             for (int k = 0; k < 4; ++k) { typedef float f32x2 __attribute__((ext_vector_type(2))); *(CLAS f32x2*)(lds + OFF_U1 + (tt + k) * 2048 + cp * 8) = (f32x2){aa[k], ab[k]}; }
	v_lshlrev_b32_e32 v200, 16, v196
	v_and_b32_e32 v201, 0xffff0000, v196
	v_pk_fma_f32 v[180:181], v[14:15], v[190:191], v[180:181]
	v_pk_fma_f32 v[178:179], v[14:15], v[198:199], v[178:179]
	v_pk_fma_f32 v[186:187], v[16:17], v[198:199], v[186:187]
	v_pk_fma_f32 v[182:183], v[16:17], v[194:195], v[182:183]
	v_lshlrev_b32_e32 v196, 16, v197
	v_and_b32_e32 v197, 0xffff0000, v197
	v_pk_fma_f32 v[180:181], v[12:13], v[198:199], v[180:181]
	v_pk_fma_f32 v[178:179], v[12:13], v[194:195], v[178:179]
	ds_read2st64_b32 v[184:185], v163 offset0:128 offset1:132
	v_pk_fma_f32 v[186:187], v[14:15], v[194:195], v[186:187]
	v_pk_fma_f32 v[182:183], v[14:15], v[200:201], v[182:183]
	v_pk_fma_f32 v[180:181], v[10:11], v[194:195], v[180:181]
	v_pk_fma_f32 v[178:179], v[10:11], v[200:201], v[178:179]
	v_pk_fma_f32 v[186:187], v[12:13], v[200:201], v[186:187]
	v_pk_fma_f32 v[182:183], v[12:13], v[196:197], v[182:183]
	v_pk_fma_f32 v[180:181], v[8:9], v[200:201], v[180:181]
	v_pk_fma_f32 v[178:179], v[8:9], v[196:197], v[178:179]
	v_pk_fma_f32 v[186:187], v[10:11], v[196:197], v[186:187]
	v_pk_fma_f32 v[182:183], v[10:11], v[222:223], v[182:183]
	v_pk_fma_f32 v[180:181], v[6:7], v[196:197], v[180:181]
	v_pk_fma_f32 v[178:179], v[6:7], v[222:223], v[178:179]
	v_pk_fma_f32 v[186:187], v[8:9], v[222:223], v[186:187]
	v_pk_fma_f32 v[182:183], v[8:9], v[218:219], v[182:183]
	v_pk_fma_f32 v[180:181], v[4:5], v[222:223], v[180:181]
	v_lshlrev_b32_e32 v188, 16, v221
	v_and_b32_e32 v189, 0xffff0000, v221
	v_pk_fma_f32 v[178:179], v[4:5], v[218:219], v[178:179]
	v_pk_fma_f32 v[186:187], v[6:7], v[218:219], v[186:187]
	v_pk_fma_f32 v[182:183], v[6:7], v[224:225], v[182:183]
	v_pk_fma_f32 v[180:181], v[2:3], v[218:219], v[180:181]
	v_pk_fma_f32 v[178:179], v[2:3], v[224:225], v[178:179]
	s_waitcnt lgkmcnt(0)
	v_lshlrev_b32_e32 v202, 16, v184
	v_and_b32_e32 v203, 0xffff0000, v184
	v_pk_fma_f32 v[186:187], v[4:5], v[224:225], v[186:187]
	v_pk_fma_f32 v[182:183], v[4:5], v[188:189], v[182:183]
	v_pk_fma_f32 v[180:181], v[0:1], v[224:225], v[180:181]
	v_pk_fma_f32 v[178:179], v[0:1], v[188:189], v[178:179]
	v_pk_fma_f32 v[186:187], v[2:3], v[188:189], v[186:187]
	v_lshlrev_b32_e32 v184, 16, v185
	v_and_b32_e32 v185, 0xffff0000, v185
	ds_read2st64_b32 v[188:189], v165 offset1:4
	v_pk_fma_f32 v[182:183], v[2:3], v[202:203], v[182:183]
	v_pk_fma_f32 v[186:187], v[0:1], v[202:203], v[186:187]
	v_pk_fma_f32 v[182:183], v[0:1], v[184:185], v[182:183]
	ds_write2st64_b64 v164, v[180:181], v[178:179] offset1:4
	ds_write2st64_b64 v164, v[186:187], v[182:183] offset0:8 offset1:12
	ds_read2st64_b32 v[180:181], v165 offset0:8 offset1:12
	ds_read2st64_b32 v[184:185], v165 offset0:16 offset1:20
	s_waitcnt lgkmcnt(4)
	v_and_b32_e32 v179, 0xffff0000, v188
	v_lshlrev_b32_e32 v178, 16, v188
	v_lshlrev_b32_e32 v182, 16, v189
	v_and_b32_e32 v183, 0xffff0000, v189
	ds_read2st64_b32 v[190:191], v165 offset0:24 offset1:28
	v_pk_fma_f32 v[178:179], v[140:141], v[178:179], v[122:123]
	s_waitcnt lgkmcnt(2)
	v_lshlrev_b32_e32 v186, 16, v180
	v_and_b32_e32 v187, 0xffff0000, v180
	v_pk_fma_f32 v[178:179], v[138:139], v[182:183], v[178:179]
	v_pk_fma_f32 v[182:183], v[140:141], v[182:183], v[122:123]
	v_lshlrev_b32_e32 v180, 16, v181
	v_and_b32_e32 v181, 0xffff0000, v181
	ds_read2st64_b32 v[192:193], v165 offset0:32 offset1:36
	v_pk_fma_f32 v[178:179], v[136:137], v[186:187], v[178:179]
	v_pk_fma_f32 v[182:183], v[138:139], v[186:187], v[182:183]
	v_pk_fma_f32 v[186:187], v[140:141], v[186:187], v[122:123]
	s_waitcnt lgkmcnt(2)
	v_lshlrev_b32_e32 v188, 16, v184
	v_and_b32_e32 v189, 0xffff0000, v184
	v_pk_fma_f32 v[178:179], v[134:135], v[180:181], v[178:179]
	v_pk_fma_f32 v[182:183], v[136:137], v[180:181], v[182:183]
	v_pk_fma_f32 v[186:187], v[138:139], v[180:181], v[186:187]
	v_pk_fma_f32 v[180:181], v[140:141], v[180:181], v[122:123]
	v_lshlrev_b32_e32 v184, 16, v185
	v_and_b32_e32 v185, 0xffff0000, v185
	ds_read2st64_b32 v[198:199], v165 offset0:40 offset1:44
	v_pk_fma_f32 v[180:181], v[138:139], v[188:189], v[180:181]
	s_waitcnt lgkmcnt(2)
	v_lshlrev_b32_e32 v194, 16, v190
	v_and_b32_e32 v195, 0xffff0000, v190
	v_pk_fma_f32 v[182:183], v[134:135], v[188:189], v[182:183]
	v_pk_fma_f32 v[186:187], v[136:137], v[188:189], v[186:187]
	v_pk_fma_f32 v[180:181], v[136:137], v[184:185], v[180:181]
	v_lshlrev_b32_e32 v190, 16, v191
	v_and_b32_e32 v191, 0xffff0000, v191
	v_pk_fma_f32 v[178:179], v[132:133], v[188:189], v[178:179]
	v_pk_fma_f32 v[182:183], v[132:133], v[184:185], v[182:183]
	v_pk_fma_f32 v[186:187], v[134:135], v[184:185], v[186:187]
	ds_read2st64_b32 v[202:203], v165 offset0:48 offset1:52
	v_pk_fma_f32 v[180:181], v[134:135], v[194:195], v[180:181]
	s_waitcnt lgkmcnt(2)
	v_lshlrev_b32_e32 v196, 16, v192
	v_and_b32_e32 v197, 0xffff0000, v192
	v_pk_fma_f32 v[178:179], v[130:131], v[184:185], v[178:179]
	v_pk_fma_f32 v[182:183], v[130:131], v[194:195], v[182:183]
	v_pk_fma_f32 v[186:187], v[132:133], v[194:195], v[186:187]
	v_pk_fma_f32 v[180:181], v[132:133], v[190:191], v[180:181]
	v_pk_fma_f32 v[178:179], v[128:129], v[194:195], v[178:179]
	v_lshlrev_b32_e32 v192, 16, v193
	v_and_b32_e32 v193, 0xffff0000, v193
	v_pk_fma_f32 v[182:183], v[128:129], v[190:191], v[182:183]
	v_pk_fma_f32 v[186:187], v[130:131], v[190:191], v[186:187]
	ds_read2st64_b32 v[204:205], v165 offset0:56 offset1:60
	v_pk_fma_f32 v[180:181], v[130:131], v[196:197], v[180:181]
	v_pk_fma_f32 v[178:179], v[126:127], v[190:191], v[178:179]
	v_pk_fma_f32 v[182:183], v[126:127], v[196:197], v[182:183]
	s_waitcnt lgkmcnt(2)
; __device__ __forceinline__ float bf_lo(unsigned w) { return __uint_as_float(w << 16); }
; __device__ __forceinline__ float bf_hi(unsigned w) { return __uint_as_float(w & 0xffff0000u); }
; #define CLAS __attribute__((address_space(3)))
; __device__ __forceinline__ void conv_unit(CLAS unsigned char* lds, const bf16_t* __restrict__ PC, bf16_t* __restrict__ YC, const float* __restrict__ w3, const float* __restrict__ w31, ...
;     ...
;             const CLAS unsigned char* up = lds + OFF_U0 + tt * 1024 + cp * 4;
; #pragma unroll
;             for (int rr = 0; rr < 34; ++rr) {
;                 const unsigned w = *(const CLAS unsigned*)(up + rr * 1024);
;                 const float xa = bf_lo(w), xb = bf_hi(w);
; #pragma unroll
;                 for (int k = 0; k < 4; ++k) { const int j = rr - k; if (j >= 0 && j < 31) { aa[k] += wa[j] * xa; ab[k] += wb[j] * xb; } }
;             }
	v_lshlrev_b32_e32 v200, 16, v198
	v_and_b32_e32 v201, 0xffff0000, v198
	v_pk_fma_f32 v[186:187], v[128:129], v[196:197], v[186:187]
	v_pk_fma_f32 v[180:181], v[128:129], v[192:193], v[180:181]
	v_pk_fma_f32 v[178:179], v[124:125], v[196:197], v[178:179]
	v_pk_fma_f32 v[182:183], v[124:125], v[192:193], v[182:183]
	v_pk_fma_f32 v[186:187], v[126:127], v[192:193], v[186:187]
	v_lshlrev_b32_e32 v198, 16, v199
	v_and_b32_e32 v199, 0xffff0000, v199
	ds_read2st64_b32 v[210:211], v165 offset0:64 offset1:68
	v_pk_fma_f32 v[180:181], v[126:127], v[200:201], v[180:181]
	v_pk_fma_f32 v[186:187], v[124:125], v[200:201], v[186:187]
	s_waitcnt lgkmcnt(2)
	v_lshlrev_b32_e32 v206, 16, v202
	v_and_b32_e32 v207, 0xffff0000, v202
	v_pk_fma_f32 v[178:179], v[118:119], v[192:193], v[178:179]
	v_pk_fma_f32 v[180:181], v[124:125], v[198:199], v[180:181]
	v_pk_fma_f32 v[182:183], v[118:119], v[200:201], v[182:183]
	v_lshlrev_b32_e32 v202, 16, v203
	v_and_b32_e32 v203, 0xffff0000, v203
	ds_read2st64_b32 v[212:213], v165 offset0:72 offset1:76
	v_pk_fma_f32 v[178:179], v[114:115], v[200:201], v[178:179]
	v_pk_fma_f32 v[182:183], v[114:115], v[198:199], v[182:183]
	v_pk_fma_f32 v[186:187], v[118:119], v[198:199], v[186:187]
	v_pk_fma_f32 v[180:181], v[118:119], v[206:207], v[180:181]
	s_waitcnt lgkmcnt(2)
	v_lshlrev_b32_e32 v208, 16, v204
	v_and_b32_e32 v209, 0xffff0000, v204
	v_pk_fma_f32 v[178:179], v[110:111], v[198:199], v[178:179]
	v_pk_fma_f32 v[182:183], v[110:111], v[206:207], v[182:183]
	v_pk_fma_f32 v[186:187], v[114:115], v[206:207], v[186:187]
	v_pk_fma_f32 v[180:181], v[114:115], v[202:203], v[180:181]
	v_lshlrev_b32_e32 v204, 16, v205
	v_and_b32_e32 v205, 0xffff0000, v205
	v_pk_fma_f32 v[178:179], v[120:121], v[206:207], v[178:179]
	ds_read2st64_b32 v[184:185], v165 offset0:80 offset1:84
	v_pk_fma_f32 v[182:183], v[120:121], v[202:203], v[182:183]
	v_pk_fma_f32 v[186:187], v[110:111], v[202:203], v[186:187]
	v_pk_fma_f32 v[180:181], v[110:111], v[208:209], v[180:181]
	s_waitcnt lgkmcnt(2)
	v_lshlrev_b32_e32 v214, 16, v210
	v_and_b32_e32 v215, 0xffff0000, v210
	v_pk_fma_f32 v[178:179], v[116:117], v[202:203], v[178:179]
	v_pk_fma_f32 v[182:183], v[116:117], v[208:209], v[182:183]
	v_pk_fma_f32 v[186:187], v[120:121], v[208:209], v[186:187]
	v_pk_fma_f32 v[180:181], v[120:121], v[204:205], v[180:181]
	v_lshlrev_b32_e32 v210, 16, v211
	v_and_b32_e32 v211, 0xffff0000, v211
	v_pk_fma_f32 v[178:179], v[112:113], v[208:209], v[178:179]
	v_pk_fma_f32 v[182:183], v[112:113], v[204:205], v[182:183]
	v_pk_fma_f32 v[186:187], v[116:117], v[204:205], v[186:187]
	ds_read2st64_b32 v[190:191], v165 offset0:88 offset1:92
	v_pk_fma_f32 v[180:181], v[116:117], v[214:215], v[180:181]
	s_waitcnt lgkmcnt(2)
	v_lshlrev_b32_e32 v216, 16, v212
	v_and_b32_e32 v217, 0xffff0000, v212
	v_pk_fma_f32 v[178:179], v[30:31], v[204:205], v[178:179]
	v_pk_fma_f32 v[182:183], v[30:31], v[214:215], v[182:183]
	v_pk_fma_f32 v[186:187], v[112:113], v[214:215], v[186:187]
	v_pk_fma_f32 v[180:181], v[112:113], v[210:211], v[180:181]
	v_lshlrev_b32_e32 v212, 16, v213
	v_and_b32_e32 v213, 0xffff0000, v213
	v_pk_fma_f32 v[178:179], v[28:29], v[214:215], v[178:179]
	v_pk_fma_f32 v[182:183], v[28:29], v[210:211], v[182:183]
	v_pk_fma_f32 v[186:187], v[30:31], v[210:211], v[186:187]
	ds_read2st64_b32 v[194:195], v165 offset0:96 offset1:100
	v_pk_fma_f32 v[180:181], v[30:31], v[216:217], v[180:181]
	v_pk_fma_f32 v[178:179], v[26:27], v[210:211], v[178:179]
	s_waitcnt lgkmcnt(2)
	v_lshlrev_b32_e32 v188, 16, v184
	v_and_b32_e32 v189, 0xffff0000, v184
	v_pk_fma_f32 v[182:183], v[26:27], v[216:217], v[182:183]
	v_pk_fma_f32 v[186:187], v[28:29], v[216:217], v[186:187]
	v_pk_fma_f32 v[180:181], v[28:29], v[212:213], v[180:181]
	v_pk_fma_f32 v[178:179], v[24:25], v[216:217], v[178:179]
	v_pk_fma_f32 v[182:183], v[24:25], v[212:213], v[182:183]
	v_lshlrev_b32_e32 v184, 16, v185
	v_and_b32_e32 v185, 0xffff0000, v185
	v_pk_fma_f32 v[186:187], v[26:27], v[212:213], v[186:187]
	ds_read2st64_b32 v[196:197], v165 offset0:104 offset1:108
	v_pk_fma_f32 v[180:181], v[26:27], v[188:189], v[180:181]
	v_pk_fma_f32 v[178:179], v[22:23], v[212:213], v[178:179]
	v_pk_fma_f32 v[182:183], v[22:23], v[188:189], v[182:183]
	v_pk_fma_f32 v[186:187], v[24:25], v[188:189], v[186:187]
	s_waitcnt lgkmcnt(2)
	v_lshlrev_b32_e32 v192, 16, v190
	v_and_b32_e32 v193, 0xffff0000, v190
	v_pk_fma_f32 v[180:181], v[24:25], v[184:185], v[180:181]
	v_pk_fma_f32 v[186:187], v[22:23], v[184:185], v[186:187]
	v_lshlrev_b32_e32 v190, 16, v191
	v_and_b32_e32 v191, 0xffff0000, v191
	ds_read2st64_b32 v[218:219], v165 offset0:112 offset1:116
	v_pk_fma_f32 v[178:179], v[20:21], v[188:189], v[178:179]
	v_pk_fma_f32 v[180:181], v[22:23], v[192:193], v[180:181]
	v_pk_fma_f32 v[182:183], v[20:21], v[184:185], v[182:183]
	s_waitcnt lgkmcnt(2)
	v_lshlrev_b32_e32 v198, 16, v194
	v_and_b32_e32 v199, 0xffff0000, v194
	v_pk_fma_f32 v[178:179], v[18:19], v[184:185], v[178:179]
	v_pk_fma_f32 v[182:183], v[18:19], v[192:193], v[182:183]
	v_pk_fma_f32 v[186:187], v[20:21], v[192:193], v[186:187]
	v_pk_fma_f32 v[180:181], v[20:21], v[190:191], v[180:181]
	v_lshlrev_b32_e32 v194, 16, v195
	v_and_b32_e32 v195, 0xffff0000, v195
	ds_read2st64_b32 v[220:221], v165 offset0:120 offset1:124
	v_pk_fma_f32 v[178:179], v[16:17], v[192:193], v[178:179]
	v_pk_fma_f32 v[182:183], v[16:17], v[190:191], v[182:183]
	v_pk_fma_f32 v[186:187], v[18:19], v[190:191], v[186:187]
	v_pk_fma_f32 v[180:181], v[18:19], v[198:199], v[180:181]
	s_waitcnt lgkmcnt(2)
; __device__ __forceinline__ float bf_lo(unsigned w) { return __uint_as_float(w << 16); }
; __device__ __forceinline__ float bf_hi(unsigned w) { return __uint_as_float(w & 0xffff0000u); }
; #define CLAS __attribute__((address_space(3)))
; __device__ __forceinline__ void conv_unit(CLAS unsigned char* lds, const bf16_t* __restrict__ PC, bf16_t* __restrict__ YC, const float* __restrict__ w3, const float* __restrict__ w31, ...
;     ...
;             const CLAS unsigned char* up = lds + OFF_U0 + tt * 1024 + cp * 4;
; #pragma unroll
;             for (int rr = 0; rr < 34; ++rr) {
;                 const unsigned w = *(const CLAS unsigned*)(up + rr * 1024);
;                 const float xa = bf_lo(w), xb = bf_hi(w);
; #pragma unroll
;                 for (int k = 0; k < 4; ++k) { const int j = rr - k; if (j >= 0 && j < 31) { aa[k] += wa[j] * xa; ab[k] += wb[j] * xb; } }
;             }
; #pragma unroll
;             for (int k = 0; k < 4; ++k) { typedef float f32x2 __attribute__((ext_vector_type(2))); *(CLAS f32x2*)(lds + OFF_U1 + (tt + k) * 2048 + cp * 8) = (f32x2){aa[k], ab[k]}; }
	v_lshlrev_b32_e32 v200, 16, v196
	v_and_b32_e32 v201, 0xffff0000, v196
	v_pk_fma_f32 v[178:179], v[14:15], v[190:191], v[178:179]
	v_pk_fma_f32 v[182:183], v[14:15], v[198:199], v[182:183]
	v_pk_fma_f32 v[186:187], v[16:17], v[198:199], v[186:187]
	v_pk_fma_f32 v[180:181], v[16:17], v[194:195], v[180:181]
	v_lshlrev_b32_e32 v196, 16, v197
	v_and_b32_e32 v197, 0xffff0000, v197
	v_pk_fma_f32 v[178:179], v[12:13], v[198:199], v[178:179]
	v_pk_fma_f32 v[182:183], v[12:13], v[194:195], v[182:183]
	ds_read2st64_b32 v[184:185], v165 offset0:128 offset1:132
	v_pk_fma_f32 v[186:187], v[14:15], v[194:195], v[186:187]
	v_pk_fma_f32 v[180:181], v[14:15], v[200:201], v[180:181]
	s_waitcnt lgkmcnt(2)
	v_lshlrev_b32_e32 v222, 16, v218
	v_and_b32_e32 v223, 0xffff0000, v218
	v_pk_fma_f32 v[178:179], v[10:11], v[194:195], v[178:179]
	v_pk_fma_f32 v[182:183], v[10:11], v[200:201], v[182:183]
	v_pk_fma_f32 v[186:187], v[12:13], v[200:201], v[186:187]
	v_pk_fma_f32 v[180:181], v[12:13], v[196:197], v[180:181]
	v_lshlrev_b32_e32 v218, 16, v219
	v_and_b32_e32 v219, 0xffff0000, v219
	v_pk_fma_f32 v[178:179], v[8:9], v[200:201], v[178:179]
	v_pk_fma_f32 v[182:183], v[8:9], v[196:197], v[182:183]
	v_pk_fma_f32 v[186:187], v[10:11], v[196:197], v[186:187]
	v_pk_fma_f32 v[180:181], v[10:11], v[222:223], v[180:181]
	s_waitcnt lgkmcnt(1)
	v_lshlrev_b32_e32 v224, 16, v220
	v_and_b32_e32 v225, 0xffff0000, v220
	v_pk_fma_f32 v[178:179], v[6:7], v[196:197], v[178:179]
	v_pk_fma_f32 v[182:183], v[6:7], v[222:223], v[182:183]
	v_pk_fma_f32 v[186:187], v[8:9], v[222:223], v[186:187]
	v_pk_fma_f32 v[180:181], v[8:9], v[218:219], v[180:181]
	v_pk_fma_f32 v[178:179], v[4:5], v[222:223], v[178:179]
	v_lshlrev_b32_e32 v188, 16, v221
	v_and_b32_e32 v189, 0xffff0000, v221
	v_pk_fma_f32 v[182:183], v[4:5], v[218:219], v[182:183]
	v_pk_fma_f32 v[186:187], v[6:7], v[218:219], v[186:187]
	v_pk_fma_f32 v[180:181], v[6:7], v[224:225], v[180:181]
	v_pk_fma_f32 v[178:179], v[2:3], v[218:219], v[178:179]
	v_pk_fma_f32 v[182:183], v[2:3], v[224:225], v[182:183]
	s_waitcnt lgkmcnt(0)
	v_lshlrev_b32_e32 v202, 16, v184
	v_and_b32_e32 v203, 0xffff0000, v184
	v_pk_fma_f32 v[186:187], v[4:5], v[224:225], v[186:187]
	v_pk_fma_f32 v[180:181], v[4:5], v[188:189], v[180:181]
	v_pk_fma_f32 v[178:179], v[0:1], v[224:225], v[178:179]
	v_pk_fma_f32 v[182:183], v[0:1], v[188:189], v[182:183]
	v_pk_fma_f32 v[186:187], v[2:3], v[188:189], v[186:187]
	v_lshlrev_b32_e32 v184, 16, v185
	v_and_b32_e32 v185, 0xffff0000, v185
	ds_read2st64_b32 v[188:189], v167 offset1:4
	v_pk_fma_f32 v[180:181], v[2:3], v[202:203], v[180:181]
	v_pk_fma_f32 v[186:187], v[0:1], v[202:203], v[186:187]
	v_pk_fma_f32 v[180:181], v[0:1], v[184:185], v[180:181]
	ds_write2st64_b64 v166, v[178:179], v[182:183] offset1:4
	ds_write2st64_b64 v166, v[186:187], v[180:181] offset0:8 offset1:12
	ds_read2st64_b32 v[180:181], v167 offset0:8 offset1:12
	ds_read2st64_b32 v[184:185], v167 offset0:16 offset1:20
	s_waitcnt lgkmcnt(4)
	v_and_b32_e32 v179, 0xffff0000, v188
	v_lshlrev_b32_e32 v178, 16, v188
	v_lshlrev_b32_e32 v182, 16, v189
	v_and_b32_e32 v183, 0xffff0000, v189
	ds_read2st64_b32 v[190:191], v167 offset0:24 offset1:28
	v_pk_fma_f32 v[178:179], v[140:141], v[178:179], v[122:123]
	s_waitcnt lgkmcnt(2)
	v_lshlrev_b32_e32 v186, 16, v180
	v_and_b32_e32 v187, 0xffff0000, v180
	v_pk_fma_f32 v[178:179], v[138:139], v[182:183], v[178:179]
	v_pk_fma_f32 v[182:183], v[140:141], v[182:183], v[122:123]
	v_lshlrev_b32_e32 v180, 16, v181
	v_and_b32_e32 v181, 0xffff0000, v181
	ds_read2st64_b32 v[192:193], v167 offset0:32 offset1:36
	v_pk_fma_f32 v[178:179], v[136:137], v[186:187], v[178:179]
	v_pk_fma_f32 v[182:183], v[138:139], v[186:187], v[182:183]
	v_pk_fma_f32 v[186:187], v[140:141], v[186:187], v[122:123]
	s_waitcnt lgkmcnt(2)
	v_lshlrev_b32_e32 v188, 16, v184
	v_and_b32_e32 v189, 0xffff0000, v184
	v_pk_fma_f32 v[178:179], v[134:135], v[180:181], v[178:179]
	v_pk_fma_f32 v[182:183], v[136:137], v[180:181], v[182:183]
	v_pk_fma_f32 v[186:187], v[138:139], v[180:181], v[186:187]
	v_pk_fma_f32 v[180:181], v[140:141], v[180:181], v[122:123]
	v_lshlrev_b32_e32 v184, 16, v185
	v_and_b32_e32 v185, 0xffff0000, v185
	ds_read2st64_b32 v[198:199], v167 offset0:40 offset1:44
	v_pk_fma_f32 v[180:181], v[138:139], v[188:189], v[180:181]
	s_waitcnt lgkmcnt(2)
	v_lshlrev_b32_e32 v194, 16, v190
	v_and_b32_e32 v195, 0xffff0000, v190
	v_pk_fma_f32 v[182:183], v[134:135], v[188:189], v[182:183]
	v_pk_fma_f32 v[186:187], v[136:137], v[188:189], v[186:187]
	v_pk_fma_f32 v[180:181], v[136:137], v[184:185], v[180:181]
	v_lshlrev_b32_e32 v190, 16, v191
	v_and_b32_e32 v191, 0xffff0000, v191
	v_pk_fma_f32 v[178:179], v[132:133], v[188:189], v[178:179]
	v_pk_fma_f32 v[182:183], v[132:133], v[184:185], v[182:183]
	v_pk_fma_f32 v[186:187], v[134:135], v[184:185], v[186:187]
	ds_read2st64_b32 v[202:203], v167 offset0:48 offset1:52
	v_pk_fma_f32 v[180:181], v[134:135], v[194:195], v[180:181]
	s_waitcnt lgkmcnt(2)
	v_lshlrev_b32_e32 v196, 16, v192
	v_and_b32_e32 v197, 0xffff0000, v192
	v_pk_fma_f32 v[178:179], v[130:131], v[184:185], v[178:179]
	v_pk_fma_f32 v[182:183], v[130:131], v[194:195], v[182:183]
	v_pk_fma_f32 v[186:187], v[132:133], v[194:195], v[186:187]
	v_pk_fma_f32 v[180:181], v[132:133], v[190:191], v[180:181]
	v_pk_fma_f32 v[178:179], v[128:129], v[194:195], v[178:179]
	v_lshlrev_b32_e32 v192, 16, v193
	v_and_b32_e32 v193, 0xffff0000, v193
	v_pk_fma_f32 v[182:183], v[128:129], v[190:191], v[182:183]
	v_pk_fma_f32 v[186:187], v[130:131], v[190:191], v[186:187]
	ds_read2st64_b32 v[204:205], v167 offset0:56 offset1:60
	v_pk_fma_f32 v[180:181], v[130:131], v[196:197], v[180:181]
	v_pk_fma_f32 v[178:179], v[126:127], v[190:191], v[178:179]
	v_pk_fma_f32 v[182:183], v[126:127], v[196:197], v[182:183]
	s_waitcnt lgkmcnt(2)
; __device__ __forceinline__ float bf_lo(unsigned w) { return __uint_as_float(w << 16); }
; __device__ __forceinline__ float bf_hi(unsigned w) { return __uint_as_float(w & 0xffff0000u); }
; #define CLAS __attribute__((address_space(3)))
; __device__ __forceinline__ void conv_unit(CLAS unsigned char* lds, const bf16_t* __restrict__ PC, bf16_t* __restrict__ YC, const float* __restrict__ w3, const float* __restrict__ w31, ...
;     ...
;             const CLAS unsigned char* up = lds + OFF_U0 + tt * 1024 + cp * 4;
; #pragma unroll
;             for (int rr = 0; rr < 34; ++rr) {
;                 const unsigned w = *(const CLAS unsigned*)(up + rr * 1024);
;                 const float xa = bf_lo(w), xb = bf_hi(w);
; #pragma unroll
;                 for (int k = 0; k < 4; ++k) { const int j = rr - k; if (j >= 0 && j < 31) { aa[k] += wa[j] * xa; ab[k] += wb[j] * xb; } }
;             }
	v_lshlrev_b32_e32 v200, 16, v198
	v_and_b32_e32 v201, 0xffff0000, v198
	v_pk_fma_f32 v[186:187], v[128:129], v[196:197], v[186:187]
	v_pk_fma_f32 v[180:181], v[128:129], v[192:193], v[180:181]
	v_pk_fma_f32 v[178:179], v[124:125], v[196:197], v[178:179]
	v_pk_fma_f32 v[182:183], v[124:125], v[192:193], v[182:183]
	v_pk_fma_f32 v[186:187], v[126:127], v[192:193], v[186:187]
	v_lshlrev_b32_e32 v198, 16, v199
	v_and_b32_e32 v199, 0xffff0000, v199
	ds_read2st64_b32 v[210:211], v167 offset0:64 offset1:68
	v_pk_fma_f32 v[180:181], v[126:127], v[200:201], v[180:181]
	v_pk_fma_f32 v[186:187], v[124:125], v[200:201], v[186:187]
	s_waitcnt lgkmcnt(2)
	v_lshlrev_b32_e32 v206, 16, v202
	v_and_b32_e32 v207, 0xffff0000, v202
	v_pk_fma_f32 v[178:179], v[118:119], v[192:193], v[178:179]
	v_pk_fma_f32 v[180:181], v[124:125], v[198:199], v[180:181]
	v_pk_fma_f32 v[182:183], v[118:119], v[200:201], v[182:183]
	v_lshlrev_b32_e32 v202, 16, v203
	v_and_b32_e32 v203, 0xffff0000, v203
	ds_read2st64_b32 v[212:213], v167 offset0:72 offset1:76
	v_pk_fma_f32 v[178:179], v[114:115], v[200:201], v[178:179]
	v_pk_fma_f32 v[182:183], v[114:115], v[198:199], v[182:183]
	v_pk_fma_f32 v[186:187], v[118:119], v[198:199], v[186:187]
	v_pk_fma_f32 v[180:181], v[118:119], v[206:207], v[180:181]
	s_waitcnt lgkmcnt(2)
	v_lshlrev_b32_e32 v208, 16, v204
	v_and_b32_e32 v209, 0xffff0000, v204
	v_pk_fma_f32 v[178:179], v[110:111], v[198:199], v[178:179]
	v_pk_fma_f32 v[182:183], v[110:111], v[206:207], v[182:183]
	v_pk_fma_f32 v[186:187], v[114:115], v[206:207], v[186:187]
	v_pk_fma_f32 v[180:181], v[114:115], v[202:203], v[180:181]
	v_lshlrev_b32_e32 v204, 16, v205
	v_and_b32_e32 v205, 0xffff0000, v205
	v_pk_fma_f32 v[178:179], v[120:121], v[206:207], v[178:179]
	ds_read2st64_b32 v[184:185], v167 offset0:80 offset1:84
	v_pk_fma_f32 v[182:183], v[120:121], v[202:203], v[182:183]
	v_pk_fma_f32 v[186:187], v[110:111], v[202:203], v[186:187]
	v_pk_fma_f32 v[180:181], v[110:111], v[208:209], v[180:181]
	s_waitcnt lgkmcnt(2)
	v_lshlrev_b32_e32 v214, 16, v210
	v_and_b32_e32 v215, 0xffff0000, v210
	v_pk_fma_f32 v[178:179], v[116:117], v[202:203], v[178:179]
	v_pk_fma_f32 v[182:183], v[116:117], v[208:209], v[182:183]
	v_pk_fma_f32 v[186:187], v[120:121], v[208:209], v[186:187]
	v_pk_fma_f32 v[180:181], v[120:121], v[204:205], v[180:181]
	v_lshlrev_b32_e32 v210, 16, v211
	v_and_b32_e32 v211, 0xffff0000, v211
	v_pk_fma_f32 v[178:179], v[112:113], v[208:209], v[178:179]
	v_pk_fma_f32 v[182:183], v[112:113], v[204:205], v[182:183]
	v_pk_fma_f32 v[186:187], v[116:117], v[204:205], v[186:187]
	ds_read2st64_b32 v[190:191], v167 offset0:88 offset1:92
	v_pk_fma_f32 v[180:181], v[116:117], v[214:215], v[180:181]
	s_waitcnt lgkmcnt(2)
	v_lshlrev_b32_e32 v216, 16, v212
	v_and_b32_e32 v217, 0xffff0000, v212
	v_pk_fma_f32 v[178:179], v[30:31], v[204:205], v[178:179]
	v_pk_fma_f32 v[182:183], v[30:31], v[214:215], v[182:183]
	v_pk_fma_f32 v[186:187], v[112:113], v[214:215], v[186:187]
	v_pk_fma_f32 v[180:181], v[112:113], v[210:211], v[180:181]
	v_lshlrev_b32_e32 v212, 16, v213
	v_and_b32_e32 v213, 0xffff0000, v213
	v_pk_fma_f32 v[178:179], v[28:29], v[214:215], v[178:179]
	v_pk_fma_f32 v[182:183], v[28:29], v[210:211], v[182:183]
	v_pk_fma_f32 v[186:187], v[30:31], v[210:211], v[186:187]
	ds_read2st64_b32 v[194:195], v167 offset0:96 offset1:100
	v_pk_fma_f32 v[180:181], v[30:31], v[216:217], v[180:181]
	v_pk_fma_f32 v[178:179], v[26:27], v[210:211], v[178:179]
	s_waitcnt lgkmcnt(2)
	v_lshlrev_b32_e32 v188, 16, v184
	v_and_b32_e32 v189, 0xffff0000, v184
	v_pk_fma_f32 v[182:183], v[26:27], v[216:217], v[182:183]
	v_pk_fma_f32 v[186:187], v[28:29], v[216:217], v[186:187]
	v_pk_fma_f32 v[180:181], v[28:29], v[212:213], v[180:181]
	v_pk_fma_f32 v[178:179], v[24:25], v[216:217], v[178:179]
	v_pk_fma_f32 v[182:183], v[24:25], v[212:213], v[182:183]
	v_lshlrev_b32_e32 v184, 16, v185
	v_and_b32_e32 v185, 0xffff0000, v185
	v_pk_fma_f32 v[186:187], v[26:27], v[212:213], v[186:187]
	ds_read2st64_b32 v[196:197], v167 offset0:104 offset1:108
	v_pk_fma_f32 v[180:181], v[26:27], v[188:189], v[180:181]
	v_pk_fma_f32 v[178:179], v[22:23], v[212:213], v[178:179]
	v_pk_fma_f32 v[182:183], v[22:23], v[188:189], v[182:183]
	v_pk_fma_f32 v[186:187], v[24:25], v[188:189], v[186:187]
	s_waitcnt lgkmcnt(2)
	v_lshlrev_b32_e32 v192, 16, v190
	v_and_b32_e32 v193, 0xffff0000, v190
	v_pk_fma_f32 v[180:181], v[24:25], v[184:185], v[180:181]
	v_pk_fma_f32 v[186:187], v[22:23], v[184:185], v[186:187]
	v_lshlrev_b32_e32 v190, 16, v191
	v_and_b32_e32 v191, 0xffff0000, v191
	ds_read2st64_b32 v[218:219], v167 offset0:112 offset1:116
	v_pk_fma_f32 v[178:179], v[20:21], v[188:189], v[178:179]
	v_pk_fma_f32 v[180:181], v[22:23], v[192:193], v[180:181]
	v_pk_fma_f32 v[182:183], v[20:21], v[184:185], v[182:183]
	s_waitcnt lgkmcnt(2)
	v_lshlrev_b32_e32 v198, 16, v194
	v_and_b32_e32 v199, 0xffff0000, v194
	v_pk_fma_f32 v[178:179], v[18:19], v[184:185], v[178:179]
	v_pk_fma_f32 v[182:183], v[18:19], v[192:193], v[182:183]
	v_pk_fma_f32 v[186:187], v[20:21], v[192:193], v[186:187]
	v_pk_fma_f32 v[180:181], v[20:21], v[190:191], v[180:181]
	v_lshlrev_b32_e32 v194, 16, v195
	v_and_b32_e32 v195, 0xffff0000, v195
	ds_read2st64_b32 v[220:221], v167 offset0:120 offset1:124
	v_pk_fma_f32 v[178:179], v[16:17], v[192:193], v[178:179]
	v_pk_fma_f32 v[182:183], v[16:17], v[190:191], v[182:183]
	v_pk_fma_f32 v[186:187], v[18:19], v[190:191], v[186:187]
	v_pk_fma_f32 v[180:181], v[18:19], v[198:199], v[180:181]
	s_waitcnt lgkmcnt(2)
; __device__ __forceinline__ float bf_lo(unsigned w) { return __uint_as_float(w << 16); }
; __device__ __forceinline__ float bf_hi(unsigned w) { return __uint_as_float(w & 0xffff0000u); }
; #define CLAS __attribute__((address_space(3)))
; __device__ __forceinline__ void conv_unit(CLAS unsigned char* lds, const bf16_t* __restrict__ PC, bf16_t* __restrict__ YC, const float* __restrict__ w3, const float* __restrict__ w31, ...
;     ...
;             const CLAS unsigned char* up = lds + OFF_U0 + tt * 1024 + cp * 4;
; #pragma unroll
;             for (int rr = 0; rr < 34; ++rr) {
;                 const unsigned w = *(const CLAS unsigned*)(up + rr * 1024);
;                 const float xa = bf_lo(w), xb = bf_hi(w);
; #pragma unroll
;                 for (int k = 0; k < 4; ++k) { const int j = rr - k; if (j >= 0 && j < 31) { aa[k] += wa[j] * xa; ab[k] += wb[j] * xb; } }
;             }
; #pragma unroll
;             for (int k = 0; k < 4; ++k) { typedef float f32x2 __attribute__((ext_vector_type(2))); *(CLAS f32x2*)(lds + OFF_U1 + (tt + k) * 2048 + cp * 8) = (f32x2){aa[k], ab[k]}; }
	v_lshlrev_b32_e32 v200, 16, v196
	v_and_b32_e32 v201, 0xffff0000, v196
	v_pk_fma_f32 v[178:179], v[14:15], v[190:191], v[178:179]
	v_pk_fma_f32 v[182:183], v[14:15], v[198:199], v[182:183]
	v_pk_fma_f32 v[186:187], v[16:17], v[198:199], v[186:187]
	v_pk_fma_f32 v[180:181], v[16:17], v[194:195], v[180:181]
	v_lshlrev_b32_e32 v196, 16, v197
	v_and_b32_e32 v197, 0xffff0000, v197
	v_pk_fma_f32 v[178:179], v[12:13], v[198:199], v[178:179]
	v_pk_fma_f32 v[182:183], v[12:13], v[194:195], v[182:183]
	ds_read2st64_b32 v[184:185], v167 offset0:128 offset1:132
	v_pk_fma_f32 v[186:187], v[14:15], v[194:195], v[186:187]
	v_pk_fma_f32 v[180:181], v[14:15], v[200:201], v[180:181]
	s_waitcnt lgkmcnt(2)
	v_lshlrev_b32_e32 v222, 16, v218
	v_and_b32_e32 v223, 0xffff0000, v218
	v_pk_fma_f32 v[178:179], v[10:11], v[194:195], v[178:179]
	v_pk_fma_f32 v[182:183], v[10:11], v[200:201], v[182:183]
	v_pk_fma_f32 v[186:187], v[12:13], v[200:201], v[186:187]
	v_pk_fma_f32 v[180:181], v[12:13], v[196:197], v[180:181]
	v_lshlrev_b32_e32 v218, 16, v219
	v_and_b32_e32 v219, 0xffff0000, v219
	v_pk_fma_f32 v[178:179], v[8:9], v[200:201], v[178:179]
	v_pk_fma_f32 v[182:183], v[8:9], v[196:197], v[182:183]
	v_pk_fma_f32 v[186:187], v[10:11], v[196:197], v[186:187]
	v_pk_fma_f32 v[180:181], v[10:11], v[222:223], v[180:181]
	s_waitcnt lgkmcnt(1)
	v_lshlrev_b32_e32 v224, 16, v220
	v_and_b32_e32 v225, 0xffff0000, v220
	v_pk_fma_f32 v[178:179], v[6:7], v[196:197], v[178:179]
	v_pk_fma_f32 v[182:183], v[6:7], v[222:223], v[182:183]
	v_pk_fma_f32 v[186:187], v[8:9], v[222:223], v[186:187]
	v_pk_fma_f32 v[180:181], v[8:9], v[218:219], v[180:181]
	v_pk_fma_f32 v[178:179], v[4:5], v[222:223], v[178:179]
	v_lshlrev_b32_e32 v188, 16, v221
	v_and_b32_e32 v189, 0xffff0000, v221
	v_pk_fma_f32 v[182:183], v[4:5], v[218:219], v[182:183]
	v_pk_fma_f32 v[186:187], v[6:7], v[218:219], v[186:187]
	v_pk_fma_f32 v[180:181], v[6:7], v[224:225], v[180:181]
	v_pk_fma_f32 v[178:179], v[2:3], v[218:219], v[178:179]
	v_pk_fma_f32 v[182:183], v[2:3], v[224:225], v[182:183]
	s_waitcnt lgkmcnt(0)
	v_lshlrev_b32_e32 v202, 16, v184
	v_and_b32_e32 v203, 0xffff0000, v184
	v_pk_fma_f32 v[186:187], v[4:5], v[224:225], v[186:187]
	v_pk_fma_f32 v[180:181], v[4:5], v[188:189], v[180:181]
	v_pk_fma_f32 v[178:179], v[0:1], v[224:225], v[178:179]
	v_pk_fma_f32 v[182:183], v[0:1], v[188:189], v[182:183]
	v_pk_fma_f32 v[186:187], v[2:3], v[188:189], v[186:187]
	v_lshlrev_b32_e32 v184, 16, v185
	v_and_b32_e32 v185, 0xffff0000, v185
	ds_read2st64_b32 v[188:189], v169 offset1:4
	v_pk_fma_f32 v[180:181], v[2:3], v[202:203], v[180:181]
	v_pk_fma_f32 v[186:187], v[0:1], v[202:203], v[186:187]
	v_pk_fma_f32 v[180:181], v[0:1], v[184:185], v[180:181]
	ds_write2st64_b64 v168, v[178:179], v[182:183] offset1:4
	ds_write2st64_b64 v168, v[186:187], v[180:181] offset0:8 offset1:12
	ds_read2st64_b32 v[180:181], v169 offset0:8 offset1:12
	ds_read2st64_b32 v[184:185], v169 offset0:16 offset1:20
	s_waitcnt lgkmcnt(4)
	v_and_b32_e32 v179, 0xffff0000, v188
	v_lshlrev_b32_e32 v178, 16, v188
	ds_read2st64_b32 v[190:191], v169 offset0:24 offset1:28
	v_lshlrev_b32_e32 v182, 16, v189
	v_and_b32_e32 v183, 0xffff0000, v189
	v_pk_fma_f32 v[178:179], v[140:141], v[178:179], v[122:123]
	s_waitcnt lgkmcnt(2)
	v_lshlrev_b32_e32 v186, 16, v180
	v_and_b32_e32 v187, 0xffff0000, v180
	v_lshlrev_b32_e32 v180, 16, v181
	v_and_b32_e32 v181, 0xffff0000, v181
	ds_read2st64_b32 v[192:193], v169 offset0:32 offset1:36
	v_pk_fma_f32 v[178:179], v[138:139], v[182:183], v[178:179]
	v_pk_fma_f32 v[182:183], v[140:141], v[182:183], v[122:123]
	s_waitcnt lgkmcnt(2)
	v_lshlrev_b32_e32 v188, 16, v184
	v_and_b32_e32 v189, 0xffff0000, v184
	v_pk_fma_f32 v[178:179], v[136:137], v[186:187], v[178:179]
	v_pk_fma_f32 v[182:183], v[138:139], v[186:187], v[182:183]
	v_pk_fma_f32 v[186:187], v[140:141], v[186:187], v[122:123]
	v_pk_fma_f32 v[122:123], v[140:141], v[180:181], v[122:123]
	v_lshlrev_b32_e32 v184, 16, v185
	v_and_b32_e32 v185, 0xffff0000, v185
	v_pk_fma_f32 v[182:183], v[136:137], v[180:181], v[182:183]
	ds_read2st64_b32 v[198:199], v169 offset0:40 offset1:44
	v_pk_fma_f32 v[186:187], v[138:139], v[180:181], v[186:187]
	v_pk_fma_f32 v[122:123], v[138:139], v[188:189], v[122:123]
	s_waitcnt lgkmcnt(2)
	v_lshlrev_b32_e32 v194, 16, v190
	v_and_b32_e32 v195, 0xffff0000, v190
	v_pk_fma_f32 v[178:179], v[134:135], v[180:181], v[178:179]
	v_pk_fma_f32 v[182:183], v[134:135], v[188:189], v[182:183]
	v_pk_fma_f32 v[186:187], v[136:137], v[188:189], v[186:187]
	v_pk_fma_f32 v[122:123], v[136:137], v[184:185], v[122:123]
	v_lshlrev_b32_e32 v190, 16, v191
	v_and_b32_e32 v191, 0xffff0000, v191
	v_pk_fma_f32 v[178:179], v[132:133], v[188:189], v[178:179]
	v_pk_fma_f32 v[182:183], v[132:133], v[184:185], v[182:183]
	v_pk_fma_f32 v[186:187], v[134:135], v[184:185], v[186:187]
	ds_read2st64_b32 v[202:203], v169 offset0:48 offset1:52
	v_pk_fma_f32 v[122:123], v[134:135], v[194:195], v[122:123]
	s_waitcnt lgkmcnt(2)
	v_lshlrev_b32_e32 v196, 16, v192
	v_and_b32_e32 v197, 0xffff0000, v192
	v_pk_fma_f32 v[178:179], v[130:131], v[184:185], v[178:179]
	v_pk_fma_f32 v[182:183], v[130:131], v[194:195], v[182:183]
	v_pk_fma_f32 v[186:187], v[132:133], v[194:195], v[186:187]
	v_pk_fma_f32 v[122:123], v[132:133], v[190:191], v[122:123]
	v_pk_fma_f32 v[178:179], v[128:129], v[194:195], v[178:179]
	v_lshlrev_b32_e32 v192, 16, v193
	v_and_b32_e32 v193, 0xffff0000, v193
	v_pk_fma_f32 v[182:183], v[128:129], v[190:191], v[182:183]
	v_pk_fma_f32 v[186:187], v[130:131], v[190:191], v[186:187]
	ds_read2st64_b32 v[204:205], v169 offset0:56 offset1:60
	v_pk_fma_f32 v[122:123], v[130:131], v[196:197], v[122:123]
	v_pk_fma_f32 v[178:179], v[126:127], v[190:191], v[178:179]
	v_pk_fma_f32 v[182:183], v[126:127], v[196:197], v[182:183]
	s_waitcnt lgkmcnt(2)
; __device__ __forceinline__ float bf_lo(unsigned w) { return __uint_as_float(w << 16); }
; __device__ __forceinline__ float bf_hi(unsigned w) { return __uint_as_float(w & 0xffff0000u); }
; #define CLAS __attribute__((address_space(3)))
; __device__ __forceinline__ void conv_unit(CLAS unsigned char* lds, const bf16_t* __restrict__ PC, bf16_t* __restrict__ YC, const float* __restrict__ w3, const float* __restrict__ w31, ...
;     ...
;             const CLAS unsigned char* up = lds + OFF_U0 + tt * 1024 + cp * 4;
; #pragma unroll
;             for (int rr = 0; rr < 34; ++rr) {
;                 const unsigned w = *(const CLAS unsigned*)(up + rr * 1024);
;                 const float xa = bf_lo(w), xb = bf_hi(w);
; #pragma unroll
;                 for (int k = 0; k < 4; ++k) { const int j = rr - k; if (j >= 0 && j < 31) { aa[k] += wa[j] * xa; ab[k] += wb[j] * xb; } }
;             }
	v_lshlrev_b32_e32 v200, 16, v198
	v_and_b32_e32 v201, 0xffff0000, v198
	v_pk_fma_f32 v[186:187], v[128:129], v[196:197], v[186:187]
	v_pk_fma_f32 v[122:123], v[128:129], v[192:193], v[122:123]
	v_pk_fma_f32 v[178:179], v[124:125], v[196:197], v[178:179]
	v_pk_fma_f32 v[182:183], v[124:125], v[192:193], v[182:183]
	v_pk_fma_f32 v[186:187], v[126:127], v[192:193], v[186:187]
	v_lshlrev_b32_e32 v198, 16, v199
	v_and_b32_e32 v199, 0xffff0000, v199
	ds_read2st64_b32 v[210:211], v169 offset0:64 offset1:68
	v_pk_fma_f32 v[122:123], v[126:127], v[200:201], v[122:123]
	v_pk_fma_f32 v[186:187], v[124:125], v[200:201], v[186:187]
	s_waitcnt lgkmcnt(2)
	v_lshlrev_b32_e32 v206, 16, v202
	v_and_b32_e32 v207, 0xffff0000, v202
	v_pk_fma_f32 v[178:179], v[118:119], v[192:193], v[178:179]
	v_pk_fma_f32 v[122:123], v[124:125], v[198:199], v[122:123]
	v_pk_fma_f32 v[130:131], v[118:119], v[200:201], v[182:183]
	v_lshlrev_b32_e32 v202, 16, v203
	v_and_b32_e32 v203, 0xffff0000, v203
	ds_read2st64_b32 v[212:213], v169 offset0:72 offset1:76
	v_pk_fma_f32 v[178:179], v[114:115], v[200:201], v[178:179]
	v_pk_fma_f32 v[130:131], v[114:115], v[198:199], v[130:131]
	v_pk_fma_f32 v[132:133], v[118:119], v[198:199], v[186:187]
	v_pk_fma_f32 v[118:119], v[118:119], v[206:207], v[122:123]
	s_waitcnt lgkmcnt(2)
	v_lshlrev_b32_e32 v208, 16, v204
	v_and_b32_e32 v209, 0xffff0000, v204
	v_pk_fma_f32 v[178:179], v[110:111], v[198:199], v[178:179]
	v_pk_fma_f32 v[130:131], v[110:111], v[206:207], v[130:131]
	v_pk_fma_f32 v[132:133], v[114:115], v[206:207], v[132:133]
	v_pk_fma_f32 v[114:115], v[114:115], v[202:203], v[118:119]
	v_lshlrev_b32_e32 v204, 16, v205
	v_and_b32_e32 v205, 0xffff0000, v205
	v_pk_fma_f32 v[124:125], v[120:121], v[206:207], v[178:179]
	ds_read2st64_b32 v[126:127], v169 offset0:80 offset1:84
	v_pk_fma_f32 v[130:131], v[120:121], v[202:203], v[130:131]
	v_pk_fma_f32 v[132:133], v[110:111], v[202:203], v[132:133]
	v_pk_fma_f32 v[110:111], v[110:111], v[208:209], v[114:115]
	s_waitcnt lgkmcnt(2)
	v_lshlrev_b32_e32 v214, 16, v210
	v_and_b32_e32 v215, 0xffff0000, v210
	v_pk_fma_f32 v[124:125], v[116:117], v[202:203], v[124:125]
	v_pk_fma_f32 v[130:131], v[116:117], v[208:209], v[130:131]
	v_pk_fma_f32 v[132:133], v[120:121], v[208:209], v[132:133]
	v_pk_fma_f32 v[110:111], v[120:121], v[204:205], v[110:111]
	v_lshlrev_b32_e32 v210, 16, v211
	v_and_b32_e32 v211, 0xffff0000, v211
	v_pk_fma_f32 v[124:125], v[112:113], v[208:209], v[124:125]
	v_pk_fma_f32 v[130:131], v[112:113], v[204:205], v[130:131]
	v_pk_fma_f32 v[132:133], v[116:117], v[204:205], v[132:133]
	ds_read2st64_b32 v[134:135], v169 offset0:88 offset1:92
	v_pk_fma_f32 v[110:111], v[116:117], v[214:215], v[110:111]
	s_waitcnt lgkmcnt(2)
	v_lshlrev_b32_e32 v216, 16, v212
	v_and_b32_e32 v217, 0xffff0000, v212
	v_pk_fma_f32 v[124:125], v[30:31], v[204:205], v[124:125]
	v_pk_fma_f32 v[130:131], v[30:31], v[214:215], v[130:131]
	v_pk_fma_f32 v[132:133], v[112:113], v[214:215], v[132:133]
	v_pk_fma_f32 v[110:111], v[112:113], v[210:211], v[110:111]
	v_lshlrev_b32_e32 v212, 16, v213
	v_and_b32_e32 v213, 0xffff0000, v213
	v_pk_fma_f32 v[124:125], v[28:29], v[214:215], v[124:125]
	v_pk_fma_f32 v[130:131], v[28:29], v[210:211], v[130:131]
	v_pk_fma_f32 v[132:133], v[30:31], v[210:211], v[132:133]
	ds_read2st64_b32 v[138:139], v169 offset0:96 offset1:100
	v_pk_fma_f32 v[30:31], v[30:31], v[216:217], v[110:111]
	v_pk_fma_f32 v[124:125], v[26:27], v[210:211], v[124:125]
	s_waitcnt lgkmcnt(2)
	v_lshlrev_b32_e32 v128, 16, v126
	v_and_b32_e32 v129, 0xffff0000, v126
	v_pk_fma_f32 v[130:131], v[26:27], v[216:217], v[130:131]
	v_pk_fma_f32 v[132:133], v[28:29], v[216:217], v[132:133]
	v_pk_fma_f32 v[28:29], v[28:29], v[212:213], v[30:31]
	v_pk_fma_f32 v[124:125], v[24:25], v[216:217], v[124:125]
	v_pk_fma_f32 v[130:131], v[24:25], v[212:213], v[130:131]
	v_lshlrev_b32_e32 v126, 16, v127
	v_and_b32_e32 v127, 0xffff0000, v127
	v_pk_fma_f32 v[132:133], v[26:27], v[212:213], v[132:133]
	ds_read2st64_b32 v[140:141], v169 offset0:104 offset1:108
	v_pk_fma_f32 v[26:27], v[26:27], v[128:129], v[28:29]
	v_pk_fma_f32 v[124:125], v[22:23], v[212:213], v[124:125]
	v_pk_fma_f32 v[130:131], v[22:23], v[128:129], v[130:131]
	v_pk_fma_f32 v[132:133], v[24:25], v[128:129], v[132:133]
	s_waitcnt lgkmcnt(2)
	v_lshlrev_b32_e32 v136, 16, v134
	v_and_b32_e32 v137, 0xffff0000, v134
	v_pk_fma_f32 v[24:25], v[24:25], v[126:127], v[26:27]
	v_pk_fma_f32 v[132:133], v[22:23], v[126:127], v[132:133]
	v_lshlrev_b32_e32 v134, 16, v135
	v_and_b32_e32 v135, 0xffff0000, v135
	ds_read2st64_b32 v[182:183], v169 offset0:112 offset1:116
	v_pk_fma_f32 v[124:125], v[20:21], v[128:129], v[124:125]
	v_pk_fma_f32 v[22:23], v[22:23], v[136:137], v[24:25]
	v_pk_fma_f32 v[28:29], v[20:21], v[126:127], v[130:131]
	s_waitcnt lgkmcnt(2)
	v_lshlrev_b32_e32 v178, 16, v138
	v_and_b32_e32 v179, 0xffff0000, v138
	v_pk_fma_f32 v[124:125], v[18:19], v[126:127], v[124:125]
	v_pk_fma_f32 v[28:29], v[18:19], v[136:137], v[28:29]
	v_pk_fma_f32 v[112:113], v[20:21], v[136:137], v[132:133]
	v_pk_fma_f32 v[20:21], v[20:21], v[134:135], v[22:23]
	v_lshlrev_b32_e32 v138, 16, v139
	v_and_b32_e32 v139, 0xffff0000, v139
	ds_read2st64_b32 v[184:185], v169 offset0:120 offset1:124
	v_pk_fma_f32 v[124:125], v[16:17], v[136:137], v[124:125]
	v_pk_fma_f32 v[28:29], v[16:17], v[134:135], v[28:29]
	v_pk_fma_f32 v[112:113], v[18:19], v[134:135], v[112:113]
	v_pk_fma_f32 v[18:19], v[18:19], v[178:179], v[20:21]
	s_waitcnt lgkmcnt(2)
; __device__ __forceinline__ float bf_lo(unsigned w) { return __uint_as_float(w << 16); }
; __device__ __forceinline__ float bf_hi(unsigned w) { return __uint_as_float(w & 0xffff0000u); }
; #define CLAS __attribute__((address_space(3)))
; __device__ __forceinline__ void conv_unit(CLAS unsigned char* lds, const bf16_t* __restrict__ PC, bf16_t* __restrict__ YC, const float* __restrict__ w3, const float* __restrict__ w31, ...
;     ...
; #pragma unroll
;             for (int rr = 0; rr < 34; ++rr) {
;                 const unsigned w = *(const CLAS unsigned*)(up + rr * 1024);
;                 const float xa = bf_lo(w), xb = bf_hi(w);
; #pragma unroll
;                 for (int k = 0; k < 4; ++k) { const int j = rr - k; if (j >= 0 && j < 31) { aa[k] += wa[j] * xa; ab[k] += wb[j] * xb; } }
;             }
; #pragma unroll
;             for (int k = 0; k < 4; ++k) { typedef float f32x2 __attribute__((ext_vector_type(2))); *(CLAS f32x2*)(lds + OFF_U1 + (tt + k) * 2048 + cp * 8) = (f32x2){aa[k], ab[k]}; }
;         }
;     }
;     __syncthreads();
;     {
;         const int lane = tid & 63, wid = tid >> 6;
;         const f32x4 g0 = *(const f32x4*)(lng + 8 * lane), g1 = *(const f32x4*)(lng + 8 * lane + 4), b0 = *(const f32x4*)(lnb + 8 * lane), b1 = *(const f32x4*)(lnb + 8 * lane + 4);
;         for (int k = 0; k < 4; ++k) {
;             const int tt = 4 * wid + k;
;             const f32x4 x0 = *(const CLAS f32x4*)(lds + OFF_U1 + tt * 2048 + lane * 32), x1 = *(const CLAS f32x4*)(lds + OFF_U1 + tt * 2048 + lane * 32 + 16);
;             float s = ((x0[0] + x0[1]) + (x0[2] + x0[3])) + ((x1[0] + x1[1]) + (x1[2] + x1[3]));
; #pragma unroll
;             for (int o = 1; o < 64; o <<= 1) s += __shfl_xor(s, o);
;             const float mean = s * (1.0f / 512.0f);
;             const f32x4 d0 = x0 - mean, d1 = x1 - mean;
;             float q = ((d0[0] * d0[0] + d0[1] * d0[1]) + (d0[2] * d0[2] + d0[3] * d0[3])) + ((d1[0] * d1[0] + d1[1] * d1[1]) + (d1[2] * d1[2] + d1[3] * d1[3]));
; #pragma unroll
;             for (int o = 1; o < 64; o <<= 1) q += __shfl_xor(q, o);
	v_lshlrev_b32_e32 v180, 16, v140
	v_and_b32_e32 v181, 0xffff0000, v140
	v_pk_fma_f32 v[24:25], v[14:15], v[134:135], v[124:125]
	v_pk_fma_f32 v[28:29], v[14:15], v[178:179], v[28:29]
	v_pk_fma_f32 v[112:113], v[16:17], v[178:179], v[112:113]
	v_pk_fma_f32 v[16:17], v[16:17], v[138:139], v[18:19]
	v_lshlrev_b32_e32 v140, 16, v141
	v_and_b32_e32 v141, 0xffff0000, v141
	v_pk_fma_f32 v[24:25], v[12:13], v[178:179], v[24:25]
	v_pk_fma_f32 v[28:29], v[12:13], v[138:139], v[28:29]
	ds_read2st64_b32 v[30:31], v169 offset0:128 offset1:132
	v_pk_fma_f32 v[112:113], v[14:15], v[138:139], v[112:113]
	v_pk_fma_f32 v[14:15], v[14:15], v[180:181], v[16:17]
	s_waitcnt lgkmcnt(2)
	v_lshlrev_b32_e32 v186, 16, v182
	v_and_b32_e32 v187, 0xffff0000, v182
	v_pk_fma_f32 v[24:25], v[10:11], v[138:139], v[24:25]
	v_pk_fma_f32 v[28:29], v[10:11], v[180:181], v[28:29]
	v_pk_fma_f32 v[112:113], v[12:13], v[180:181], v[112:113]
	v_pk_fma_f32 v[12:13], v[12:13], v[140:141], v[14:15]
	v_lshlrev_b32_e32 v182, 16, v183
	v_and_b32_e32 v183, 0xffff0000, v183
	v_pk_fma_f32 v[24:25], v[8:9], v[180:181], v[24:25]
	v_pk_fma_f32 v[28:29], v[8:9], v[140:141], v[28:29]
	v_pk_fma_f32 v[112:113], v[10:11], v[140:141], v[112:113]
	v_pk_fma_f32 v[10:11], v[10:11], v[186:187], v[12:13]
	s_waitcnt lgkmcnt(1)
	v_lshlrev_b32_e32 v188, 16, v184
	v_and_b32_e32 v189, 0xffff0000, v184
	v_pk_fma_f32 v[24:25], v[6:7], v[140:141], v[24:25]
	v_pk_fma_f32 v[28:29], v[6:7], v[186:187], v[28:29]
	v_pk_fma_f32 v[112:113], v[8:9], v[186:187], v[112:113]
	v_pk_fma_f32 v[8:9], v[8:9], v[182:183], v[10:11]
	v_pk_fma_f32 v[24:25], v[4:5], v[186:187], v[24:25]
	v_lshlrev_b32_e32 v26, 16, v185
	v_and_b32_e32 v27, 0xffff0000, v185
	v_pk_fma_f32 v[28:29], v[4:5], v[182:183], v[28:29]
	v_pk_fma_f32 v[112:113], v[6:7], v[182:183], v[112:113]
	v_pk_fma_f32 v[6:7], v[6:7], v[188:189], v[8:9]
	v_pk_fma_f32 v[24:25], v[2:3], v[182:183], v[24:25]
	v_pk_fma_f32 v[28:29], v[2:3], v[188:189], v[28:29]
	s_waitcnt lgkmcnt(0)
	v_lshlrev_b32_e32 v110, 16, v30
	v_and_b32_e32 v111, 0xffff0000, v30
	v_pk_fma_f32 v[112:113], v[4:5], v[188:189], v[112:113]
	v_pk_fma_f32 v[4:5], v[4:5], v[26:27], v[6:7]
	v_pk_fma_f32 v[24:25], v[0:1], v[188:189], v[24:25]
	v_pk_fma_f32 v[28:29], v[0:1], v[26:27], v[28:29]
	v_pk_fma_f32 v[112:113], v[2:3], v[26:27], v[112:113]
	v_lshlrev_b32_e32 v30, 16, v31
	v_and_b32_e32 v31, 0xffff0000, v31
	v_pk_fma_f32 v[2:3], v[2:3], v[110:111], v[4:5]
	v_pk_fma_f32 v[112:113], v[0:1], v[110:111], v[112:113]
	v_pk_fma_f32 v[0:1], v[0:1], v[30:31], v[2:3]
	ds_write2st64_b64 v170, v[24:25], v[28:29] offset1:4
	ds_write2st64_b64 v170, v[112:113], v[0:1] offset0:8 offset1:12
	s_waitcnt lgkmcnt(0)
	s_barrier
	ds_read_b128 v[22:25], v172
	ds_read_b128 v[26:29], v172 offset:16
	v_and_b32_e32 v0, 64, v171
	v_add_u32_e32 v21, 64, v0
	global_load_dwordx4 v[8:11], v[104:105], off
	s_waitcnt lgkmcnt(1)
	v_mov_b32_e32 v0, v22
	s_waitcnt lgkmcnt(0)
	v_mov_b32_e32 v1, v26
	v_mov_b32_e32 v2, v23
	v_mov_b32_e32 v3, v27
	v_pk_add_f32 v[0:1], v[0:1], v[2:3]
	v_mov_b32_e32 v2, v24
	v_mov_b32_e32 v3, v28
	v_mov_b32_e32 v4, v25
	v_mov_b32_e32 v5, v29
	v_pk_add_f32 v[2:3], v[2:3], v[4:5]
	s_nop 0
	v_pk_add_f32 v[0:1], v[0:1], v[2:3]
	s_nop 0
	v_add_f32_e32 v0, v0, v1
	v_xor_b32_e32 v1, 1, v171
	v_cmp_lt_i32_e64 s[4:5], v1, v21
	s_nop 1
	v_cndmask_b32_e64 v1, v171, v1, s[4:5]
	v_lshlrev_b32_e32 v16, 2, v1
	s_nop 1
	v_add_f32_dpp v0, v0, v0 quad_perm:[1,0,3,2] row_mask:0xf bank_mask:0xf
	v_xor_b32_e32 v1, 2, v171
	v_cmp_lt_i32_e64 s[4:5], v1, v21
	s_nop 1
	v_cndmask_b32_e64 v1, v171, v1, s[4:5]
	v_lshlrev_b32_e32 v17, 2, v1
	s_nop 1
	v_add_f32_dpp v0, v0, v0 quad_perm:[2,3,0,1] row_mask:0xf bank_mask:0xf
	v_xor_b32_e32 v1, 4, v171
	v_cmp_lt_i32_e64 s[4:5], v1, v21
	s_nop 1
	v_cndmask_b32_e64 v1, v171, v1, s[4:5]
	v_lshlrev_b32_e32 v18, 2, v1
	s_nop 1
	v_add_f32_dpp v0, v0, v0 row_half_mirror row_mask:0xf bank_mask:0xf
	v_xor_b32_e32 v1, 8, v171
	v_cmp_lt_i32_e64 s[4:5], v1, v21
	s_nop 1
	v_cndmask_b32_e64 v1, v171, v1, s[4:5]
	v_lshlrev_b32_e32 v19, 2, v1
	s_nop 1
	v_add_f32_dpp v30, v0, v0 row_mirror row_mask:0xf bank_mask:0xf
	v_xor_b32_e32 v0, 16, v171
	v_cmp_lt_i32_e64 s[4:5], v0, v21
	s_nop 1
	v_cndmask_b32_e64 v0, v171, v0, s[4:5]
	v_lshlrev_b32_e32 v20, 2, v0
	global_load_dwordx4 v[12:15], v[102:103], off
	global_load_dwordx4 v[0:3], v[102:103], off offset:16
	global_load_dwordx4 v[4:7], v[104:105], off offset:16
	v_mov_b32_e32 v31, v30
	s_nop 1
	v_permlane16_swap_b32_e32 v30, v31
	v_add_f32_e32 v30, v30, v31
	v_xor_b32_e32 v31, 32, v171
	v_cmp_lt_i32_e64 s[4:5], v31, v21
	s_nop 1
	v_cndmask_b32_e64 v21, v171, v31, s[4:5]
	v_lshlrev_b32_e32 v21, 2, v21
	v_mov_b32_e32 v31, v30
	s_nop 1
	v_permlane32_swap_b32_e32 v30, v31
	v_add_f32_e32 v30, v30, v31
	v_fmamk_f32 v23, v30, 0xbb000000, v23
	v_fmamk_f32 v27, v30, 0xbb000000, v27
	v_fmamk_f32 v25, v30, 0xbb000000, v25
	v_fmac_f32_e32 v22, 0xbb000000, v30
	v_fmamk_f32 v29, v30, 0xbb000000, v29
	v_fmac_f32_e32 v26, 0xbb000000, v30
	v_mov_b32_e32 v110, v23
	v_mov_b32_e32 v111, v27
	v_fmamk_f32 v24, v30, 0xbb000000, v24
	v_fmamk_f32 v28, v30, 0xbb000000, v28
	v_mov_b32_e32 v30, v22
	v_mov_b32_e32 v31, v26
	v_pk_mul_f32 v[110:111], v[110:111], v[110:111]
	v_mov_b32_e32 v112, v25
	v_mov_b32_e32 v113, v29
	v_pk_fma_f32 v[30:31], v[30:31], v[30:31], v[110:111]
	v_mov_b32_e32 v110, v24
	v_mov_b32_e32 v111, v28
	v_pk_mul_f32 v[112:113], v[112:113], v[112:113]
	s_nop 0
	v_pk_fma_f32 v[110:111], v[110:111], v[110:111], v[112:113]
	s_nop 0
	v_pk_add_f32 v[30:31], v[30:31], v[110:111]
	s_nop 0
	v_add_f32_e32 v30, v30, v31
	s_nop 1
	v_add_f32_dpp v30, v30, v30 quad_perm:[1,0,3,2] row_mask:0xf bank_mask:0xf
	s_nop 1
	v_add_f32_dpp v30, v30, v30 quad_perm:[2,3,0,1] row_mask:0xf bank_mask:0xf
	s_nop 1
	v_add_f32_dpp v30, v30, v30 row_half_mirror row_mask:0xf bank_mask:0xf
	s_nop 1
	v_add_f32_dpp v30, v30, v30 row_mirror row_mask:0xf bank_mask:0xf
	v_mov_b32_e32 v31, v30
	s_nop 1
	v_permlane16_swap_b32_e32 v30, v31
	v_add_f32_e32 v30, v30, v31
	v_mov_b32_e32 v31, v30
	s_nop 1
	v_permlane32_swap_b32_e32 v30, v31
	v_add_f32_e32 v30, v30, v31
	v_fmamk_f32 v30, v30, 0x3b000000, v173
	v_rsq_f32_e32 v30, v30
	s_nop 0
	v_pk_mul_f32 v[22:23], v[22:23], v[30:31] op_sel_hi:[1,0]
	s_waitcnt vmcnt(2)
; __device__ __forceinline__ unsigned cvt_pk_bf16(float lo, float hi) { unsigned r; asm volatile("v_cvt_pk_bf16_f32 %0, %1, %2" : "=v"(r) : "v"(lo), "v"(hi)); return r; }
; __device__ __forceinline__ float fast_sigmoid(float x) { return __builtin_amdgcn_rcpf(1.0f + __expf(-x)); }
; #define CLAS __attribute__((address_space(3)))
; __device__ __forceinline__ void conv_unit(CLAS unsigned char* lds, const bf16_t* __restrict__ PC, bf16_t* __restrict__ YC, const float* __restrict__ w3, const float* __restrict__ w31, ...
;     ...
;         for (int k = 0; k < 4; ++k) {
;             const int tt = 4 * wid + k;
;             const f32x4 x0 = *(const CLAS f32x4*)(lds + OFF_U1 + tt * 2048 + lane * 32), x1 = *(const CLAS f32x4*)(lds + OFF_U1 + tt * 2048 + lane * 32 + 16);
;             float s = ((x0[0] + x0[1]) + (x0[2] + x0[3])) + ((x1[0] + x1[1]) + (x1[2] + x1[3]));
; #pragma unroll
;             for (int o = 1; o < 64; o <<= 1) s += __shfl_xor(s, o);
;             const float mean = s * (1.0f / 512.0f);
;             const f32x4 d0 = x0 - mean, d1 = x1 - mean;
;             float q = ((d0[0] * d0[0] + d0[1] * d0[1]) + (d0[2] * d0[2] + d0[3] * d0[3])) + ((d1[0] * d1[0] + d1[1] * d1[1]) + (d1[2] * d1[2] + d1[3] * d1[3]));
; #pragma unroll
;             for (int o = 1; o < 64; o <<= 1) q += __shfl_xor(q, o);
;             const float rstd = __builtin_amdgcn_rsqf(q * (1.0f / 512.0f) + 1e-6f);
;             f32x4 y0 = d0 * rstd * g0 + b0, y1 = d1 * rstd * g1 + b1;
; #pragma unroll
;             for (int i = 0; i < 4; ++i) { y0[i] = y0[i] * fast_sigmoid(y0[i]); y1[i] = y1[i] * fast_sigmoid(y1[i]); }
;             u32x4 w; w.x = cvt_pk_bf16(y0[0], y0[1]); w.y = cvt_pk_bf16(y0[2], y0[3]); w.z = cvt_pk_bf16(y1[0], y1[1]); w.w = cvt_pk_bf16(y1[2], y1[3]);
;             *(u32x4*)(YC + (size_t)(seq_base + t0 + tt) * 1024 + 512 + 8 * lane) = w;
	v_pk_fma_f32 v[22:23], v[12:13], v[22:23], v[8:9]
	v_pk_mul_f32 v[24:25], v[24:25], v[30:31] op_sel_hi:[1,0]
	v_pk_mul_f32 v[26:27], v[26:27], v[30:31] op_sel_hi:[1,0]
	v_mul_f32_e32 v31, 0xbfb8aa3b, v22
	v_exp_f32_e32 v31, v31
	s_waitcnt vmcnt(0)
	v_pk_fma_f32 v[26:27], v[0:1], v[26:27], v[4:5]
	v_mul_f32_e32 v110, 0xbfb8aa3b, v23
	v_exp_f32_e32 v110, v110
	v_pk_mul_f32 v[28:29], v[28:29], v[30:31] op_sel_hi:[1,0]
	v_add_f32_e32 v30, 1.0, v31
	v_mul_f32_e32 v31, 0xbfb8aa3b, v26
	v_exp_f32_e32 v31, v31
	v_add_f32_e32 v110, 1.0, v110
	v_mul_f32_e32 v111, 0xbfb8aa3b, v27
	v_rcp_f32_e32 v30, v30
	v_add_f32_e32 v31, 1.0, v31
	v_rcp_f32_e32 v31, v31
	v_rcp_f32_e32 v110, v110
	v_exp_f32_e32 v111, v111
	v_pk_fma_f32 v[24:25], v[14:15], v[24:25], v[10:11]
	v_pk_fma_f32 v[28:29], v[2:3], v[28:29], v[6:7]
	v_mul_f32_e32 v22, v22, v30
	v_mul_f32_e32 v26, v26, v31
	v_mul_f32_e32 v23, v23, v110
	v_add_f32_e32 v30, 1.0, v111
	v_mul_f32_e32 v31, 0xbfb8aa3b, v24
	v_mul_f32_e32 v110, 0xbfb8aa3b, v28
	v_rcp_f32_e32 v30, v30
	v_exp_f32_e32 v31, v31
	v_exp_f32_e32 v110, v110
	v_mul_f32_e32 v111, 0xbfb8aa3b, v29
	v_mul_f32_e32 v27, v27, v30
	v_add_f32_e32 v30, 1.0, v31
	v_add_f32_e32 v31, 1.0, v110
	v_mul_f32_e32 v110, 0xbfb8aa3b, v25
	v_exp_f32_e32 v110, v110
	v_exp_f32_e32 v111, v111
	v_rcp_f32_e32 v30, v30
	v_rcp_f32_e32 v31, v31
	v_add_f32_e32 v110, 1.0, v110
	v_add_f32_e32 v111, 1.0, v111
	v_rcp_f32_e32 v110, v110
	v_rcp_f32_e32 v111, v111
	v_mul_f32_e32 v24, v24, v30
	v_mul_f32_e32 v28, v28, v31
	v_mul_f32_e32 v25, v25, v110
	v_mul_f32_e32 v29, v29, v111
	v_cvt_pk_bf16_f32 v22, v22, v23
	v_cvt_pk_bf16_f32 v23, v24, v25
	v_cvt_pk_bf16_f32 v24, v26, v27
	v_cvt_pk_bf16_f32 v25, v28, v29
	ds_read_b128 v[26:29], v174
	ds_read_b128 v[110:113], v174 offset:16
	s_waitcnt lgkmcnt(1)
	v_mov_b32_e32 v30, v26
	s_waitcnt lgkmcnt(0)
	v_mov_b32_e32 v31, v110
	v_mov_b32_e32 v114, v27
	v_mov_b32_e32 v115, v111
	v_pk_add_f32 v[30:31], v[30:31], v[114:115]
	v_mov_b32_e32 v114, v28
	v_mov_b32_e32 v115, v112
	v_mov_b32_e32 v116, v29
	v_mov_b32_e32 v117, v113
	v_pk_add_f32 v[114:115], v[114:115], v[116:117]
	s_nop 0
	v_pk_add_f32 v[30:31], v[30:31], v[114:115]
	s_nop 0
	v_add_f32_e32 v30, v30, v31
	s_nop 1
	v_add_f32_dpp v30, v30, v30 quad_perm:[1,0,3,2] row_mask:0xf bank_mask:0xf
	s_nop 1
	v_add_f32_dpp v30, v30, v30 quad_perm:[2,3,0,1] row_mask:0xf bank_mask:0xf
	s_nop 1
	v_add_f32_dpp v30, v30, v30 row_half_mirror row_mask:0xf bank_mask:0xf
	s_nop 1
	v_add_f32_dpp v30, v30, v30 row_mirror row_mask:0xf bank_mask:0xf
	v_mov_b32_e32 v31, v30
	s_nop 1
	v_permlane16_swap_b32_e32 v30, v31
	v_add_f32_e32 v30, v30, v31
	v_mov_b32_e32 v31, v30
	s_nop 1
	v_permlane32_swap_b32_e32 v30, v31
	v_add_f32_e32 v114, v30, v31
	v_fmamk_f32 v27, v114, 0xbb000000, v27
	v_fmamk_f32 v111, v114, 0xbb000000, v111
	v_fmamk_f32 v29, v114, 0xbb000000, v29
	v_fmamk_f32 v28, v114, 0xbb000000, v28
	v_fmac_f32_e32 v26, 0xbb000000, v114
	v_fmamk_f32 v31, v114, 0xbb000000, v113
	v_fmamk_f32 v30, v114, 0xbb000000, v112
	v_fmac_f32_e32 v110, 0xbb000000, v114
	v_mov_b32_e32 v114, v27
	v_mov_b32_e32 v115, v111
	v_mov_b32_e32 v112, v26
	v_mov_b32_e32 v113, v110
	v_pk_mul_f32 v[114:115], v[114:115], v[114:115]
	v_mov_b32_e32 v116, v29
	v_mov_b32_e32 v117, v31
	v_pk_fma_f32 v[112:113], v[112:113], v[112:113], v[114:115]
	v_mov_b32_e32 v114, v28
	v_mov_b32_e32 v115, v30
	v_pk_mul_f32 v[116:117], v[116:117], v[116:117]
	s_nop 0
	v_pk_fma_f32 v[114:115], v[114:115], v[114:115], v[116:117]
	s_nop 0
	v_pk_add_f32 v[112:113], v[112:113], v[114:115]
	s_nop 0
	v_add_f32_e32 v112, v112, v113
	s_nop 1
	v_add_f32_dpp v112, v112, v112 quad_perm:[1,0,3,2] row_mask:0xf bank_mask:0xf
	s_nop 1
	v_add_f32_dpp v112, v112, v112 quad_perm:[2,3,0,1] row_mask:0xf bank_mask:0xf
	s_nop 1
	v_add_f32_dpp v112, v112, v112 row_half_mirror row_mask:0xf bank_mask:0xf
	s_nop 1
	v_add_f32_dpp v112, v112, v112 row_mirror row_mask:0xf bank_mask:0xf
	v_mov_b32_e32 v113, v112
	s_nop 1
	v_permlane16_swap_b32_e32 v112, v113
	v_add_f32_e32 v114, v112, v113
	v_mov_b32_e32 v115, v114
	s_nop 1
	v_permlane32_swap_b32_e32 v114, v115
	v_add_u32_e32 v112, s23, v151
	v_ashrrev_i32_e32 v113, 31, v112
	v_lshlrev_b64 v[112:113], 11, v[112:113]
	v_lshl_add_u64 v[112:113], v[108:109], 0, v[112:113]
	v_add_f32_e32 v114, v114, v115
	v_fmamk_f32 v114, v114, 0x3b000000, v173
	v_rsq_f32_e32 v114, v114
	global_store_dwordx4 v[112:113], v[22:25], off offset:1024
	s_nop 1
	v_pk_mul_f32 v[22:23], v[26:27], v[114:115] op_sel_hi:[1,0]
	v_pk_mul_f32 v[24:25], v[28:29], v[114:115] op_sel_hi:[1,0]
	v_pk_fma_f32 v[22:23], v[12:13], v[22:23], v[8:9]
	v_pk_mul_f32 v[26:27], v[110:111], v[114:115] op_sel_hi:[1,0]
	v_mul_f32_e32 v28, 0xbfb8aa3b, v22
	v_exp_f32_e32 v110, v28
	v_pk_fma_f32 v[26:27], v[0:1], v[26:27], v[4:5]
	v_pk_mul_f32 v[28:29], v[30:31], v[114:115] op_sel_hi:[1,0]
	v_mul_f32_e32 v31, 0xbfb8aa3b, v26
	v_add_f32_e32 v30, 1.0, v110
	v_mul_f32_e32 v110, 0xbfb8aa3b, v23
	v_exp_f32_e32 v31, v31
	v_exp_f32_e32 v110, v110
	v_mul_f32_e32 v111, 0xbfb8aa3b, v27
	v_rcp_f32_e32 v30, v30
	v_add_f32_e32 v31, 1.0, v31
	v_add_f32_e32 v110, 1.0, v110
	v_rcp_f32_e32 v31, v31
	v_rcp_f32_e32 v110, v110
	v_exp_f32_e32 v111, v111
	v_pk_fma_f32 v[24:25], v[14:15], v[24:25], v[10:11]
	v_pk_fma_f32 v[28:29], v[2:3], v[28:29], v[6:7]
	v_mul_f32_e32 v22, v22, v30
	v_mul_f32_e32 v26, v26, v31
	v_mul_f32_e32 v23, v23, v110
	v_add_f32_e32 v30, 1.0, v111
	v_mul_f32_e32 v31, 0xbfb8aa3b, v24
	v_mul_f32_e32 v110, 0xbfb8aa3b, v28
	v_rcp_f32_e32 v30, v30
	v_exp_f32_e32 v31, v31
	v_exp_f32_e32 v110, v110
	v_mul_f32_e32 v111, 0xbfb8aa3b, v29
	v_mul_f32_e32 v27, v27, v30
	v_add_f32_e32 v30, 1.0, v31
	v_add_f32_e32 v31, 1.0, v110
	v_mul_f32_e32 v110, 0xbfb8aa3b, v25
	v_exp_f32_e32 v110, v110
	v_exp_f32_e32 v111, v111
	v_rcp_f32_e32 v30, v30
	v_rcp_f32_e32 v31, v31
	v_add_f32_e32 v110, 1.0, v110
	v_add_f32_e32 v111, 1.0, v111
	v_rcp_f32_e32 v110, v110
	v_rcp_f32_e32 v111, v111
	v_mul_f32_e32 v24, v24, v30
	v_mul_f32_e32 v28, v28, v31
	v_mul_f32_e32 v25, v25, v110
	v_mul_f32_e32 v29, v29, v111
	v_cvt_pk_bf16_f32 v22, v22, v23
	v_cvt_pk_bf16_f32 v23, v24, v25
	v_cvt_pk_bf16_f32 v24, v26, v27
	v_cvt_pk_bf16_f32 v25, v28, v29
	ds_read_b128 v[26:29], v175
	ds_read_b128 v[110:113], v175 offset:16
	s_waitcnt lgkmcnt(1)
; __device__ __forceinline__ unsigned cvt_pk_bf16(float lo, float hi) { unsigned r; asm volatile("v_cvt_pk_bf16_f32 %0, %1, %2" : "=v"(r) : "v"(lo), "v"(hi)); return r; }
; __device__ __forceinline__ float fast_sigmoid(float x) { return __builtin_amdgcn_rcpf(1.0f + __expf(-x)); }
; #define CLAS __attribute__((address_space(3)))
; __device__ __forceinline__ void conv_unit(CLAS unsigned char* lds, const bf16_t* __restrict__ PC, bf16_t* __restrict__ YC, const float* __restrict__ w3, const float* __restrict__ w31, ...
;     ...
;         for (int k = 0; k < 4; ++k) {
;             const int tt = 4 * wid + k;
;             const f32x4 x0 = *(const CLAS f32x4*)(lds + OFF_U1 + tt * 2048 + lane * 32), x1 = *(const CLAS f32x4*)(lds + OFF_U1 + tt * 2048 + lane * 32 + 16);
;             float s = ((x0[0] + x0[1]) + (x0[2] + x0[3])) + ((x1[0] + x1[1]) + (x1[2] + x1[3]));
; #pragma unroll
;             for (int o = 1; o < 64; o <<= 1) s += __shfl_xor(s, o);
;             const float mean = s * (1.0f / 512.0f);
;             const f32x4 d0 = x0 - mean, d1 = x1 - mean;
;             float q = ((d0[0] * d0[0] + d0[1] * d0[1]) + (d0[2] * d0[2] + d0[3] * d0[3])) + ((d1[0] * d1[0] + d1[1] * d1[1]) + (d1[2] * d1[2] + d1[3] * d1[3]));
; #pragma unroll
;             for (int o = 1; o < 64; o <<= 1) q += __shfl_xor(q, o);
;             const float rstd = __builtin_amdgcn_rsqf(q * (1.0f / 512.0f) + 1e-6f);
;             f32x4 y0 = d0 * rstd * g0 + b0, y1 = d1 * rstd * g1 + b1;
; #pragma unroll
;             for (int i = 0; i < 4; ++i) { y0[i] = y0[i] * fast_sigmoid(y0[i]); y1[i] = y1[i] * fast_sigmoid(y1[i]); }
;             u32x4 w; w.x = cvt_pk_bf16(y0[0], y0[1]); w.y = cvt_pk_bf16(y0[2], y0[3]); w.z = cvt_pk_bf16(y1[0], y1[1]); w.w = cvt_pk_bf16(y1[2], y1[3]);
;             *(u32x4*)(YC + (size_t)(seq_base + t0 + tt) * 1024 + 512 + 8 * lane) = w;
	v_mov_b32_e32 v30, v26
	s_waitcnt lgkmcnt(0)
	v_mov_b32_e32 v31, v110
	v_mov_b32_e32 v114, v27
	v_mov_b32_e32 v115, v111
	v_pk_add_f32 v[30:31], v[30:31], v[114:115]
	v_mov_b32_e32 v114, v28
	v_mov_b32_e32 v115, v112
	v_mov_b32_e32 v116, v29
	v_mov_b32_e32 v117, v113
	v_pk_add_f32 v[114:115], v[114:115], v[116:117]
	s_nop 0
	v_pk_add_f32 v[30:31], v[30:31], v[114:115]
	s_nop 0
	v_add_f32_e32 v30, v30, v31
	s_nop 1
	v_add_f32_dpp v30, v30, v30 quad_perm:[1,0,3,2] row_mask:0xf bank_mask:0xf
	s_nop 1
	v_add_f32_dpp v30, v30, v30 quad_perm:[2,3,0,1] row_mask:0xf bank_mask:0xf
	s_nop 1
	v_add_f32_dpp v30, v30, v30 row_half_mirror row_mask:0xf bank_mask:0xf
	s_nop 1
	v_add_f32_dpp v30, v30, v30 row_mirror row_mask:0xf bank_mask:0xf
	v_mov_b32_e32 v31, v30
	s_nop 1
	v_permlane16_swap_b32_e32 v30, v31
	v_add_f32_e32 v30, v30, v31
	v_mov_b32_e32 v31, v30
	s_nop 1
	v_permlane32_swap_b32_e32 v30, v31
	v_add_f32_e32 v114, v30, v31
	v_fmamk_f32 v27, v114, 0xbb000000, v27
	v_fmamk_f32 v111, v114, 0xbb000000, v111
	v_fmamk_f32 v29, v114, 0xbb000000, v29
	v_fmamk_f32 v28, v114, 0xbb000000, v28
	v_fmac_f32_e32 v26, 0xbb000000, v114
	v_fmamk_f32 v31, v114, 0xbb000000, v113
	v_fmamk_f32 v30, v114, 0xbb000000, v112
	v_fmac_f32_e32 v110, 0xbb000000, v114
	v_mov_b32_e32 v114, v27
	v_mov_b32_e32 v115, v111
	v_mov_b32_e32 v112, v26
	v_mov_b32_e32 v113, v110
	v_pk_mul_f32 v[114:115], v[114:115], v[114:115]
	v_mov_b32_e32 v116, v29
	v_mov_b32_e32 v117, v31
	v_pk_fma_f32 v[112:113], v[112:113], v[112:113], v[114:115]
	v_mov_b32_e32 v114, v28
	v_mov_b32_e32 v115, v30
	v_pk_mul_f32 v[116:117], v[116:117], v[116:117]
	s_nop 0
	v_pk_fma_f32 v[114:115], v[114:115], v[114:115], v[116:117]
	s_nop 0
	v_pk_add_f32 v[112:113], v[112:113], v[114:115]
	s_nop 0
	v_add_f32_e32 v112, v112, v113
	s_nop 1
	v_add_f32_dpp v112, v112, v112 quad_perm:[1,0,3,2] row_mask:0xf bank_mask:0xf
	s_nop 1
	v_add_f32_dpp v112, v112, v112 quad_perm:[2,3,0,1] row_mask:0xf bank_mask:0xf
	s_nop 1
	v_add_f32_dpp v112, v112, v112 row_half_mirror row_mask:0xf bank_mask:0xf
	s_nop 1
	v_add_f32_dpp v112, v112, v112 row_mirror row_mask:0xf bank_mask:0xf
	v_mov_b32_e32 v113, v112
	s_nop 1
	v_permlane16_swap_b32_e32 v112, v113
	v_add_f32_e32 v114, v112, v113
	v_mov_b32_e32 v115, v114
	s_nop 1
	v_permlane32_swap_b32_e32 v114, v115
	v_add_u32_e32 v112, s23, v152
	v_ashrrev_i32_e32 v113, 31, v112
	v_lshlrev_b64 v[112:113], 11, v[112:113]
	v_lshl_add_u64 v[112:113], v[108:109], 0, v[112:113]
	v_add_f32_e32 v114, v114, v115
	v_fmamk_f32 v114, v114, 0x3b000000, v173
	v_rsq_f32_e32 v114, v114
	global_store_dwordx4 v[112:113], v[22:25], off offset:1024
	s_nop 1
	v_pk_mul_f32 v[22:23], v[26:27], v[114:115] op_sel_hi:[1,0]
	v_pk_mul_f32 v[24:25], v[28:29], v[114:115] op_sel_hi:[1,0]
	v_pk_fma_f32 v[22:23], v[12:13], v[22:23], v[8:9]
	v_pk_mul_f32 v[26:27], v[110:111], v[114:115] op_sel_hi:[1,0]
	v_mul_f32_e32 v28, 0xbfb8aa3b, v22
	v_exp_f32_e32 v110, v28
	v_pk_fma_f32 v[26:27], v[0:1], v[26:27], v[4:5]
	v_pk_mul_f32 v[28:29], v[30:31], v[114:115] op_sel_hi:[1,0]
	v_mul_f32_e32 v31, 0xbfb8aa3b, v26
	v_add_f32_e32 v30, 1.0, v110
	v_mul_f32_e32 v110, 0xbfb8aa3b, v23
	v_exp_f32_e32 v31, v31
	v_exp_f32_e32 v110, v110
	v_mul_f32_e32 v111, 0xbfb8aa3b, v27
	v_rcp_f32_e32 v30, v30
	v_add_f32_e32 v31, 1.0, v31
	v_add_f32_e32 v110, 1.0, v110
	v_rcp_f32_e32 v31, v31
	v_rcp_f32_e32 v110, v110
	v_exp_f32_e32 v111, v111
	v_pk_fma_f32 v[24:25], v[14:15], v[24:25], v[10:11]
	v_pk_fma_f32 v[28:29], v[2:3], v[28:29], v[6:7]
	v_mul_f32_e32 v22, v22, v30
	v_mul_f32_e32 v26, v26, v31
	v_mul_f32_e32 v23, v23, v110
	v_add_f32_e32 v30, 1.0, v111
	v_mul_f32_e32 v31, 0xbfb8aa3b, v24
	v_mul_f32_e32 v110, 0xbfb8aa3b, v28
	v_rcp_f32_e32 v30, v30
	v_exp_f32_e32 v31, v31
	v_exp_f32_e32 v110, v110
	v_mul_f32_e32 v111, 0xbfb8aa3b, v29
	v_mul_f32_e32 v27, v27, v30
	v_add_f32_e32 v30, 1.0, v31
	v_add_f32_e32 v31, 1.0, v110
	v_mul_f32_e32 v110, 0xbfb8aa3b, v25
	v_exp_f32_e32 v110, v110
	v_exp_f32_e32 v111, v111
	v_rcp_f32_e32 v30, v30
	v_rcp_f32_e32 v31, v31
	v_add_f32_e32 v110, 1.0, v110
	v_add_f32_e32 v111, 1.0, v111
	v_rcp_f32_e32 v110, v110
	v_rcp_f32_e32 v111, v111
	v_mul_f32_e32 v24, v24, v30
	v_mul_f32_e32 v28, v28, v31
	v_mul_f32_e32 v25, v25, v110
	v_mul_f32_e32 v29, v29, v111
	v_cvt_pk_bf16_f32 v22, v22, v23
	v_cvt_pk_bf16_f32 v23, v24, v25
	v_cvt_pk_bf16_f32 v24, v26, v27
	v_cvt_pk_bf16_f32 v25, v28, v29
	ds_read_b128 v[26:29], v176
	ds_read_b128 v[110:113], v176 offset:16
	s_waitcnt lgkmcnt(1)
; __device__ __forceinline__ unsigned cvt_pk_bf16(float lo, float hi) { unsigned r; asm volatile("v_cvt_pk_bf16_f32 %0, %1, %2" : "=v"(r) : "v"(lo), "v"(hi)); return r; }
; __device__ __forceinline__ float fast_sigmoid(float x) { return __builtin_amdgcn_rcpf(1.0f + __expf(-x)); }
; #define CLAS __attribute__((address_space(3)))
; __device__ __forceinline__ void conv_unit(CLAS unsigned char* lds, const bf16_t* __restrict__ PC, bf16_t* __restrict__ YC, const float* __restrict__ w3, const float* __restrict__ w31, ...
;     ...
;         for (int k = 0; k < 4; ++k) {
;             const int tt = 4 * wid + k;
;             const f32x4 x0 = *(const CLAS f32x4*)(lds + OFF_U1 + tt * 2048 + lane * 32), x1 = *(const CLAS f32x4*)(lds + OFF_U1 + tt * 2048 + lane * 32 + 16);
;             float s = ((x0[0] + x0[1]) + (x0[2] + x0[3])) + ((x1[0] + x1[1]) + (x1[2] + x1[3]));
; #pragma unroll
;             for (int o = 1; o < 64; o <<= 1) s += __shfl_xor(s, o);
;             const float mean = s * (1.0f / 512.0f);
;             const f32x4 d0 = x0 - mean, d1 = x1 - mean;
;             float q = ((d0[0] * d0[0] + d0[1] * d0[1]) + (d0[2] * d0[2] + d0[3] * d0[3])) + ((d1[0] * d1[0] + d1[1] * d1[1]) + (d1[2] * d1[2] + d1[3] * d1[3]));
; #pragma unroll
;             for (int o = 1; o < 64; o <<= 1) q += __shfl_xor(q, o);
;             const float rstd = __builtin_amdgcn_rsqf(q * (1.0f / 512.0f) + 1e-6f);
;             f32x4 y0 = d0 * rstd * g0 + b0, y1 = d1 * rstd * g1 + b1;
; #pragma unroll
;             for (int i = 0; i < 4; ++i) { y0[i] = y0[i] * fast_sigmoid(y0[i]); y1[i] = y1[i] * fast_sigmoid(y1[i]); }
;             u32x4 w; w.x = cvt_pk_bf16(y0[0], y0[1]); w.y = cvt_pk_bf16(y0[2], y0[3]); w.z = cvt_pk_bf16(y1[0], y1[1]); w.w = cvt_pk_bf16(y1[2], y1[3]);
;             *(u32x4*)(YC + (size_t)(seq_base + t0 + tt) * 1024 + 512 + 8 * lane) = w;
;         }
;     }
;     __syncthreads();
	v_mov_b32_e32 v30, v26
	s_waitcnt lgkmcnt(0)
	v_mov_b32_e32 v31, v110
	v_mov_b32_e32 v114, v27
	v_mov_b32_e32 v115, v111
	v_pk_add_f32 v[30:31], v[30:31], v[114:115]
	v_mov_b32_e32 v114, v28
	v_mov_b32_e32 v115, v112
	v_mov_b32_e32 v116, v29
	v_mov_b32_e32 v117, v113
	v_pk_add_f32 v[114:115], v[114:115], v[116:117]
	s_nop 0
	v_pk_add_f32 v[30:31], v[30:31], v[114:115]
	s_nop 0
	v_add_f32_e32 v30, v30, v31
	s_nop 1
	v_add_f32_dpp v30, v30, v30 quad_perm:[1,0,3,2] row_mask:0xf bank_mask:0xf
	s_nop 1
	v_add_f32_dpp v30, v30, v30 quad_perm:[2,3,0,1] row_mask:0xf bank_mask:0xf
	s_nop 1
	v_add_f32_dpp v30, v30, v30 row_half_mirror row_mask:0xf bank_mask:0xf
	s_nop 1
	v_add_f32_dpp v30, v30, v30 row_mirror row_mask:0xf bank_mask:0xf
	v_mov_b32_e32 v31, v30
	s_nop 1
	v_permlane16_swap_b32_e32 v30, v31
	v_add_f32_e32 v30, v30, v31
	v_mov_b32_e32 v31, v30
	s_nop 1
	v_permlane32_swap_b32_e32 v30, v31
	v_add_f32_e32 v114, v30, v31
	v_fmamk_f32 v27, v114, 0xbb000000, v27
	v_fmamk_f32 v111, v114, 0xbb000000, v111
	v_fmamk_f32 v29, v114, 0xbb000000, v29
	v_fmamk_f32 v28, v114, 0xbb000000, v28
	v_fmac_f32_e32 v26, 0xbb000000, v114
	v_fmamk_f32 v31, v114, 0xbb000000, v113
	v_fmamk_f32 v30, v114, 0xbb000000, v112
	v_fmac_f32_e32 v110, 0xbb000000, v114
	v_mov_b32_e32 v114, v27
	v_mov_b32_e32 v115, v111
	v_mov_b32_e32 v112, v26
	v_mov_b32_e32 v113, v110
	v_pk_mul_f32 v[114:115], v[114:115], v[114:115]
	v_mov_b32_e32 v116, v29
	v_mov_b32_e32 v117, v31
	v_pk_fma_f32 v[112:113], v[112:113], v[112:113], v[114:115]
	v_mov_b32_e32 v114, v28
	v_mov_b32_e32 v115, v30
	v_pk_mul_f32 v[116:117], v[116:117], v[116:117]
	s_nop 0
	v_pk_fma_f32 v[114:115], v[114:115], v[114:115], v[116:117]
	s_nop 0
	v_pk_add_f32 v[112:113], v[112:113], v[114:115]
	s_nop 0
	v_add_f32_e32 v112, v112, v113
	s_nop 1
	v_add_f32_dpp v16, v112, v112 quad_perm:[1,0,3,2] row_mask:0xf bank_mask:0xf
	s_nop 1
	v_add_f32_dpp v16, v16, v16 quad_perm:[2,3,0,1] row_mask:0xf bank_mask:0xf
	s_nop 1
	v_add_f32_dpp v16, v16, v16 row_half_mirror row_mask:0xf bank_mask:0xf
	s_nop 1
	v_add_f32_dpp v16, v16, v16 row_mirror row_mask:0xf bank_mask:0xf
	v_mov_b32_e32 v17, v16
	s_nop 1
	v_permlane16_swap_b32_e32 v16, v17
	v_add_f32_e32 v18, v16, v17
	v_mov_b32_e32 v19, v18
	s_nop 1
	v_permlane32_swap_b32_e32 v18, v19
	v_add_u32_e32 v16, s23, v153
	v_ashrrev_i32_e32 v17, 31, v16
	v_lshlrev_b64 v[16:17], 11, v[16:17]
	v_lshl_add_u64 v[16:17], v[108:109], 0, v[16:17]
	v_add_f32_e32 v18, v18, v19
	v_fmamk_f32 v18, v18, 0x3b000000, v173
	v_rsq_f32_e32 v18, v18
	global_store_dwordx4 v[16:17], v[22:25], off offset:1024
	v_pk_mul_f32 v[16:17], v[26:27], v[18:19] op_sel_hi:[1,0]
	v_pk_mul_f32 v[20:21], v[28:29], v[18:19] op_sel_hi:[1,0]
	v_pk_fma_f32 v[8:9], v[12:13], v[16:17], v[8:9]
	v_pk_fma_f32 v[10:11], v[14:15], v[20:21], v[10:11]
	v_pk_mul_f32 v[12:13], v[110:111], v[18:19] op_sel_hi:[1,0]
	v_mul_f32_e32 v14, 0xbfb8aa3b, v8
	v_exp_f32_e32 v16, v14
	v_pk_mul_f32 v[14:15], v[30:31], v[18:19] op_sel_hi:[1,0]
	v_pk_fma_f32 v[0:1], v[0:1], v[12:13], v[4:5]
	v_pk_fma_f32 v[2:3], v[2:3], v[14:15], v[6:7]
	v_mul_f32_e32 v5, 0xbfb8aa3b, v0
	v_mul_f32_e32 v6, 0xbfb8aa3b, v9
	v_exp_f32_e32 v5, v5
	v_exp_f32_e32 v6, v6
	v_add_f32_e32 v4, 1.0, v16
	v_mul_f32_e32 v7, 0xbfb8aa3b, v1
	v_add_f32_e32 v5, 1.0, v5
	v_add_f32_e32 v6, 1.0, v6
	v_rcp_f32_e32 v4, v4
	v_rcp_f32_e32 v5, v5
	v_rcp_f32_e32 v6, v6
	v_exp_f32_e32 v7, v7
	v_mul_f32_e32 v4, v8, v4
	v_mul_f32_e32 v5, v0, v5
	v_mul_f32_e32 v0, v9, v6
	v_add_f32_e32 v6, 1.0, v7
	v_mul_f32_e32 v7, 0xbfb8aa3b, v10
	v_mul_f32_e32 v8, 0xbfb8aa3b, v2
	v_rcp_f32_e32 v6, v6
	v_exp_f32_e32 v7, v7
	v_exp_f32_e32 v8, v8
	v_mul_f32_e32 v9, 0xbfb8aa3b, v3
	v_mul_f32_e32 v6, v1, v6
	v_add_f32_e32 v1, 1.0, v7
	v_add_f32_e32 v7, 1.0, v8
	v_mul_f32_e32 v8, 0xbfb8aa3b, v11
	v_exp_f32_e32 v8, v8
	v_exp_f32_e32 v9, v9
	v_rcp_f32_e32 v1, v1
	v_rcp_f32_e32 v7, v7
	v_add_f32_e32 v8, 1.0, v8
	v_rcp_f32_e32 v8, v8
	v_add_f32_e32 v9, 1.0, v9
	v_rcp_f32_e32 v9, v9
	v_mul_f32_e32 v1, v10, v1
	v_mul_f32_e32 v7, v2, v7
	v_mul_f32_e32 v2, v11, v8
	v_cvt_pk_bf16_f32 v0, v4, v0
	v_add_u32_e32 v4, s23, v154
	v_cvt_pk_bf16_f32 v1, v1, v2
	v_cvt_pk_bf16_f32 v2, v5, v6
	v_ashrrev_i32_e32 v5, 31, v4
	v_lshlrev_b64 v[4:5], 11, v[4:5]
	v_mul_f32_e32 v3, v3, v9
	v_lshl_add_u64 v[4:5], v[108:109], 0, v[4:5]
	v_cvt_pk_bf16_f32 v3, v7, v3
	global_store_dwordx4 v[4:5], v[0:3], off offset:1024
	s_barrier
	s_cbranch_scc0 .LBB0_813

; #define PG8_STAGE(bufoff, gbase, voff) do { _Pragma("unroll") for (int _i = 0; _i < 2; ++_i) \
;         __builtin_amdgcn_global_load_lds((const unsigned*)((const char*)(gbase) + (voff)[_i]), (PG8_LAS unsigned*)(lds + (bufoff) + ldsw + _i * 8192), 16, 0, 0); } while (0)
; #define PG8_LDA(dst, b, h) do { _Pragma("unroll") for (int m = 0; m < 4; ++m) _Pragma("unroll") for (int k = 0; k < 2; ++k) dst[m][k] = *(const PG8_LAS bf16x8*)(lds + PG8_SA(b, h) + aoff + m * 2048 + k * 1024); } while (0)
; #define PG8_LDB(dst, b, h) do { _Pragma("unroll") for (int n = 0; n < 2; ++n) _Pragma("unroll") for (int k = 0; k < 2; ++k) dst[n][k] = *(const PG8_LAS bf16x8*)(lds + PG8_SB(b, h) + boff + n * 2048 + k * 1024); } while (0)
; #define PG8_MMA(ai, bj, At, Bt) do { __builtin_amdgcn_s_setprio(1); _Pragma("unroll") for (int m = 0; m < 4; ++m) _Pragma("unroll") for (int n = 0; n < 2; ++n) _Pragma("unroll") for (int k = 0; k < 2; ++k) \
;         acc[ai][bj][m][n] = __builtin_amdgcn_mfma_f32_16x16x32_bf16(Bt[n][k], At[m][k], acc[ai][bj][m][n], 0, 0, 0); __builtin_amdgcn_s_setprio(0); } while (0)
; #define PG8_WAIT_V(n) asm volatile("s_waitcnt vmcnt(" #n ")" ::: "memory")
; #define PG8_WAIT_L(n) asm volatile("s_waitcnt lgkmcnt(" #n ")" ::: "memory")
; #define PG8_BAR __builtin_amdgcn_s_barrier()
; #define PG8_SCHED __builtin_amdgcn_sched_barrier(0)
; template <class Epi, class Sched, bool ALIGN_EPI = false, bool SP2 = false>
; __device__ __forceinline__ void gemm_phase(PG8_LAS unsigned char* lds, const Gemm g, const Sched& S, const Epi& E) {
;     ...
;             PG8_LDB(B0, 0, 0); PG8_LDB(B1, 0, 1); PG8_SCHED; PG8_LDA(At, 0, 0); PG8_STAGE(PG8_SA(1, 1), a1 + hstep, voffA);
;             PG8_WAIT_V(8); PG8_WAIT_L(0); PG8_BAR; PG8_MMA(0, 0, At, B0); PG8_MMA(0, 1, At, B1); PG8_BAR; PG8_SCHED;
;             PG8_LDA(At, 0, 1); PG8_STAGE(PG8_SB(0, 0), b2, voffB); PG8_STAGE(PG8_SB(0, 1), b2 + hstep, voffB); PG8_STAGE(PG8_SA(0, 0), a2, voffA);
.LBB0_977:
	ds_read_b128 v[144:147], v161
	ds_read_b128 v[170:173], v161 offset:1024
	ds_read_b128 v[178:181], v161 offset:2048
	ds_read_b128 v[182:185], v161 offset:3072
	ds_read_b128 v[186:189], v165
	ds_read_b128 v[190:193], v165 offset:1024
	ds_read_b128 v[194:197], v165 offset:2048
	ds_read_b128 v[198:201], v165 offset:3072
	s_add_u32 s36, s34, 0xfffc0080
	s_addc_u32 s37, s35, -1
	s_cmp_eq_u32 s58, 12
	s_cselect_b32 s39, s21, s37
	s_cselect_b32 s38, s54, s36
	s_cselect_b32 s37, s19, s57
	s_cselect_b32 s36, s55, s56
	v_lshl_add_u64 v[150:151], s[34:35], 0, v[138:139]
	s_add_i32 m0, s29, 0xc000
	ds_read_b128 v[202:205], v169
	ds_read_b128 v[206:209], v169 offset:1024
	ds_read_b128 v[210:213], v169 offset:2048
	ds_read_b128 v[214:217], v169 offset:3072
	ds_read_b128 v[218:221], v169 offset:4096
	ds_read_b128 v[222:225], v169 offset:5120
	ds_read_b128 v[226:229], v169 offset:6144
	ds_read_b128 v[232:235], v169 offset:7168
	global_load_lds_dwordx4 v[150:151], off
	v_lshl_add_u64 v[150:151], s[34:35], 0, v[140:141]
	s_add_i32 m0, s29, 0xe000
	s_nop 0
	global_load_lds_dwordx4 v[150:151], off
	s_waitcnt vmcnt(8)
	s_waitcnt lgkmcnt(0)
	s_barrier
	s_setprio 1
	s_waitcnt lgkmcnt(0)
	v_mfma_f32_16x16x32_bf16 v[124:127], v[144:147], v[202:205], v[124:127]
	v_mfma_f32_16x16x32_bf16 v[116:119], v[178:181], v[202:205], v[116:119]
	v_mfma_f32_16x16x32_bf16 v[108:111], v[144:147], v[210:213], v[108:111]
	v_mfma_f32_16x16x32_bf16 v[100:103], v[178:181], v[210:213], v[100:103]
	v_mfma_f32_16x16x32_bf16 v[92:95], v[144:147], v[218:221], v[92:95]
	v_mfma_f32_16x16x32_bf16 v[84:87], v[178:181], v[218:221], v[84:87]
	v_mfma_f32_16x16x32_bf16 v[76:79], v[144:147], v[226:229], v[76:79]
	v_mfma_f32_16x16x32_bf16 v[68:71], v[178:181], v[226:229], v[68:71]
	v_mfma_f32_16x16x32_bf16 v[124:127], v[170:173], v[206:209], v[124:127]
	v_mfma_f32_16x16x32_bf16 v[116:119], v[182:185], v[206:209], v[116:119]
	v_mfma_f32_16x16x32_bf16 v[108:111], v[170:173], v[214:217], v[108:111]
	v_mfma_f32_16x16x32_bf16 v[100:103], v[182:185], v[214:217], v[100:103]
	v_mfma_f32_16x16x32_bf16 v[92:95], v[170:173], v[222:225], v[92:95]
	v_mfma_f32_16x16x32_bf16 v[84:87], v[182:185], v[222:225], v[84:87]
	v_mfma_f32_16x16x32_bf16 v[76:79], v[170:173], v[232:235], v[76:79]
	v_mfma_f32_16x16x32_bf16 v[68:71], v[182:185], v[232:235], v[68:71]
	s_setprio 0
	s_setprio 1
	v_mfma_f32_16x16x32_bf16 v[120:123], v[186:189], v[202:205], v[120:123]
	v_mfma_f32_16x16x32_bf16 v[112:115], v[194:197], v[202:205], v[112:115]
	v_mfma_f32_16x16x32_bf16 v[104:107], v[186:189], v[210:213], v[104:107]
	v_mfma_f32_16x16x32_bf16 v[96:99], v[194:197], v[210:213], v[96:99]
	v_mfma_f32_16x16x32_bf16 v[88:91], v[186:189], v[218:221], v[88:91]
	v_mfma_f32_16x16x32_bf16 v[80:83], v[194:197], v[218:221], v[80:83]
	v_mfma_f32_16x16x32_bf16 v[72:75], v[186:189], v[226:229], v[72:75]
	v_mfma_f32_16x16x32_bf16 v[64:67], v[194:197], v[226:229], v[64:67]
	v_mfma_f32_16x16x32_bf16 v[120:123], v[190:193], v[206:209], v[120:123]
	v_mfma_f32_16x16x32_bf16 v[112:115], v[198:201], v[206:209], v[112:115]
	v_mfma_f32_16x16x32_bf16 v[104:107], v[190:193], v[214:217], v[104:107]
	v_mfma_f32_16x16x32_bf16 v[96:99], v[198:201], v[214:217], v[96:99]
	v_mfma_f32_16x16x32_bf16 v[88:91], v[190:193], v[222:225], v[88:91]
	v_mfma_f32_16x16x32_bf16 v[80:83], v[198:201], v[222:225], v[80:83]
	v_mfma_f32_16x16x32_bf16 v[72:75], v[190:193], v[232:235], v[72:75]
	v_mfma_f32_16x16x32_bf16 v[64:67], v[198:201], v[232:235], v[64:67]
	s_setprio 0
	s_barrier
	s_add_i32 s59, s50, s43
	v_lshl_add_u64 v[150:151], s[36:37], 0, v[130:131]
	s_mov_b32 m0, s59
	ds_read_b128 v[202:205], v169 offset:16384
	ds_read_b128 v[206:209], v169 offset:17408
	ds_read_b128 v[210:213], v169 offset:18432
	ds_read_b128 v[214:217], v169 offset:19456
	ds_read_b128 v[218:221], v169 offset:20480
	ds_read_b128 v[222:225], v169 offset:21504
	ds_read_b128 v[226:229], v169 offset:22528
	ds_read_b128 v[232:235], v169 offset:23552
	global_load_lds_dwordx4 v[150:151], off
	s_add_i32 m0, s59, 0x2000
	s_add_u32 s60, s36, 0x40000
	v_lshl_add_u64 v[154:155], s[36:37], 0, v[134:135]
	s_addc_u32 s61, s37, 0
	s_add_i32 s59, s51, s43
	global_load_lds_dwordx4 v[154:155], off
	v_lshl_add_u64 v[158:159], s[60:61], 0, v[130:131]
	s_mov_b32 m0, s59
	v_lshl_add_u64 v[162:163], s[38:39], 0, v[132:133]
	global_load_lds_dwordx4 v[158:159], off
	v_lshl_add_u64 v[158:159], s[60:61], 0, v[134:135]
	s_add_i32 m0, s59, 0x2000
	s_nop 0
	global_load_lds_dwordx4 v[158:159], off
	v_lshl_add_u64 v[158:159], s[38:39], 0, v[128:129]
	s_mov_b32 m0, s29
	s_nop 0
	global_load_lds_dwordx4 v[158:159], off
	s_mov_b32 m0, s31
	s_nop 0
	global_load_lds_dwordx4 v[162:163], off
	s_cmp_lg_i32 s58, -2
	s_cbranch_scc1 .Lrsb_a
	v_lshrrev_b32_e32 v250, 6, v230
	v_lshlrev_b32_e32 v250, 11, v250
	v_and_b32_e32 v251, 63, v230
	v_lshl_or_b32 v250, v251, 4, v250
	v_lshl_add_u32 v250, s30, 14, v250
	v_readfirstlane_b32 s98, v230
	s_lshr_b32 s98, s98, 6
	s_lshl_b32 s98, s98, 11
	s_add_i32 m0, s98, 0x20000
	s_add_u32 s100, s70, 0x3f000000
	s_addc_u32 s101, s71, 0
	global_load_lds_dwordx4 v250, s[100:101]
	global_load_lds_dwordx4 v250, s[100:101] offset:1024
	s_waitcnt vmcnt(10)
	s_branch .Lrsb_b

; #define PG8_STAGE(bufoff, gbase, voff) do { _Pragma("unroll") for (int _i = 0; _i < 2; ++_i) \
;         __builtin_amdgcn_global_load_lds((const unsigned*)((const char*)(gbase) + (voff)[_i]), (PG8_LAS unsigned*)(lds + (bufoff) + ldsw + _i * 8192), 16, 0, 0); } while (0)
; #define PG8_LDA(dst, b, h) do { _Pragma("unroll") for (int m = 0; m < 4; ++m) _Pragma("unroll") for (int k = 0; k < 2; ++k) dst[m][k] = *(const PG8_LAS bf16x8*)(lds + PG8_SA(b, h) + aoff + m * 2048 + k * 1024); } while (0)
; #define PG8_LDB(dst, b, h) do { _Pragma("unroll") for (int n = 0; n < 2; ++n) _Pragma("unroll") for (int k = 0; k < 2; ++k) dst[n][k] = *(const PG8_LAS bf16x8*)(lds + PG8_SB(b, h) + boff + n * 2048 + k * 1024); } while (0)
; #define PG8_MMA(ai, bj, At, Bt) do { __builtin_amdgcn_s_setprio(1); _Pragma("unroll") for (int m = 0; m < 4; ++m) _Pragma("unroll") for (int n = 0; n < 2; ++n) _Pragma("unroll") for (int k = 0; k < 2; ++k) \
;         acc[ai][bj][m][n] = __builtin_amdgcn_mfma_f32_16x16x32_bf16(Bt[n][k], At[m][k], acc[ai][bj][m][n], 0, 0, 0); __builtin_amdgcn_s_setprio(0); } while (0)
; #define PG8_WAIT_V(n) asm volatile("s_waitcnt vmcnt(" #n ")" ::: "memory")
; #define PG8_WAIT_L(n) asm volatile("s_waitcnt lgkmcnt(" #n ")" ::: "memory")
; #define PG8_BAR __builtin_amdgcn_s_barrier()
; #define PG8_SCHED __builtin_amdgcn_sched_barrier(0)
; template <class Epi, class Sched, bool ALIGN_EPI = false, bool SP2 = false>
; __device__ __forceinline__ void gemm_phase(PG8_LAS unsigned char* lds, const Gemm g, const Sched& S, const Epi& E) {
;     ...
;             PG8_WAIT_V(8); PG8_WAIT_L(0); PG8_BAR; PG8_MMA(1, 0, At, B0); PG8_MMA(1, 1, At, B1); PG8_BAR; PG8_SCHED;
;             PG8_LDB(B0, 1, 0); PG8_LDB(B1, 1, 1); PG8_SCHED; PG8_LDA(At, 1, 0); PG8_STAGE(PG8_SA(0, 1), a2 + hstep, voffA);
.Lrsb_b:
	s_waitcnt lgkmcnt(0)
	s_barrier
	s_setprio 1
	s_waitcnt lgkmcnt(0)
	v_mfma_f32_16x16x32_bf16 v[60:63], v[144:147], v[202:205], v[60:63]
	v_mfma_f32_16x16x32_bf16 v[52:55], v[178:181], v[202:205], v[52:55]
	v_mfma_f32_16x16x32_bf16 v[44:47], v[144:147], v[210:213], v[44:47]
	v_mfma_f32_16x16x32_bf16 v[36:39], v[178:181], v[210:213], v[36:39]
	v_mfma_f32_16x16x32_bf16 v[28:31], v[144:147], v[218:221], v[28:31]
	v_mfma_f32_16x16x32_bf16 v[20:23], v[178:181], v[218:221], v[20:23]
	v_mfma_f32_16x16x32_bf16 v[12:15], v[144:147], v[226:229], v[12:15]
	v_mfma_f32_16x16x32_bf16 v[4:7], v[178:181], v[226:229], v[4:7]
	v_mfma_f32_16x16x32_bf16 v[60:63], v[170:173], v[206:209], v[60:63]
	v_mfma_f32_16x16x32_bf16 v[52:55], v[182:185], v[206:209], v[52:55]
	v_mfma_f32_16x16x32_bf16 v[44:47], v[170:173], v[214:217], v[44:47]
	v_mfma_f32_16x16x32_bf16 v[36:39], v[182:185], v[214:217], v[36:39]
	v_mfma_f32_16x16x32_bf16 v[28:31], v[170:173], v[222:225], v[28:31]
	v_mfma_f32_16x16x32_bf16 v[20:23], v[182:185], v[222:225], v[20:23]
	v_mfma_f32_16x16x32_bf16 v[12:15], v[170:173], v[232:235], v[12:15]
	v_mfma_f32_16x16x32_bf16 v[4:7], v[182:185], v[232:235], v[4:7]
	s_setprio 0
	s_setprio 1
	v_mfma_f32_16x16x32_bf16 v[56:59], v[186:189], v[202:205], v[56:59]
	v_mfma_f32_16x16x32_bf16 v[48:51], v[194:197], v[202:205], v[48:51]
	v_mfma_f32_16x16x32_bf16 v[40:43], v[186:189], v[210:213], v[40:43]
	v_mfma_f32_16x16x32_bf16 v[32:35], v[194:197], v[210:213], v[32:35]
	v_mfma_f32_16x16x32_bf16 v[24:27], v[186:189], v[218:221], v[24:27]
	v_mfma_f32_16x16x32_bf16 v[16:19], v[194:197], v[218:221], v[16:19]
	v_mfma_f32_16x16x32_bf16 v[8:11], v[186:189], v[226:229], v[8:11]
	v_mfma_f32_16x16x32_bf16 v[0:3], v[194:197], v[226:229], v[0:3]
	v_mfma_f32_16x16x32_bf16 v[56:59], v[190:193], v[206:209], v[56:59]
	v_mfma_f32_16x16x32_bf16 v[48:51], v[198:201], v[206:209], v[48:51]
	v_mfma_f32_16x16x32_bf16 v[40:43], v[190:193], v[214:217], v[40:43]
	v_mfma_f32_16x16x32_bf16 v[32:35], v[198:201], v[214:217], v[32:35]
	v_mfma_f32_16x16x32_bf16 v[24:27], v[190:193], v[222:225], v[24:27]
	v_mfma_f32_16x16x32_bf16 v[16:19], v[198:201], v[222:225], v[16:19]
	v_mfma_f32_16x16x32_bf16 v[8:11], v[190:193], v[232:235], v[8:11]
	v_mfma_f32_16x16x32_bf16 v[0:3], v[198:201], v[232:235], v[0:3]
	s_setprio 0
	s_barrier
	s_add_i32 s59, 0, 0x18000
	v_add_u32_e32 v148, s59, v153
	s_add_i32 s60, 0, 0x1c000
	ds_read_b128 v[144:147], v148
	ds_read_b128 v[170:173], v148 offset:1024
	ds_read_b128 v[178:181], v148 offset:2048
	ds_read_b128 v[182:185], v148 offset:3072
	v_add_u32_e32 v148, s60, v153
	ds_read_b128 v[186:189], v148
	ds_read_b128 v[190:193], v148 offset:1024
	ds_read_b128 v[194:197], v148 offset:2048
	ds_read_b128 v[198:201], v148 offset:3072
	s_add_u32 s38, s38, 0x40000
	s_addc_u32 s39, s39, 0
	s_mov_b32 m0, s45
	v_lshl_add_u64 v[166:167], s[38:39], 0, v[128:129]
	ds_read_b128 v[202:205], v169 offset:32768
	ds_read_b128 v[206:209], v169 offset:33792
	ds_read_b128 v[210:213], v169 offset:34816
	ds_read_b128 v[214:217], v169 offset:35840
	ds_read_b128 v[218:221], v169 offset:36864
	ds_read_b128 v[222:225], v169 offset:37888
	ds_read_b128 v[226:229], v169 offset:38912
	ds_read_b128 v[232:235], v169 offset:39936
	global_load_lds_dwordx4 v[166:167], off
	v_lshl_add_u64 v[166:167], s[38:39], 0, v[132:133]
	s_mov_b32 m0, s46
	s_nop 0
	global_load_lds_dwordx4 v[166:167], off
	s_cmp_lg_i32 s58, -2
	s_cbranch_scc1 .Lrsb_c
	s_waitcnt vmcnt(10)
	s_branch .Lrsb_d

; #define PG8_STAGE(bufoff, gbase, voff) do { _Pragma("unroll") for (int _i = 0; _i < 2; ++_i) \
;         __builtin_amdgcn_global_load_lds((const unsigned*)((const char*)(gbase) + (voff)[_i]), (PG8_LAS unsigned*)(lds + (bufoff) + ldsw + _i * 8192), 16, 0, 0); } while (0)
; #define PG8_LDA(dst, b, h) do { _Pragma("unroll") for (int m = 0; m < 4; ++m) _Pragma("unroll") for (int k = 0; k < 2; ++k) dst[m][k] = *(const PG8_LAS bf16x8*)(lds + PG8_SA(b, h) + aoff + m * 2048 + k * 1024); } while (0)
; #define PG8_MMA(ai, bj, At, Bt) do { __builtin_amdgcn_s_setprio(1); _Pragma("unroll") for (int m = 0; m < 4; ++m) _Pragma("unroll") for (int n = 0; n < 2; ++n) _Pragma("unroll") for (int k = 0; k < 2; ++k) \
;         acc[ai][bj][m][n] = __builtin_amdgcn_mfma_f32_16x16x32_bf16(Bt[n][k], At[m][k], acc[ai][bj][m][n], 0, 0, 0); __builtin_amdgcn_s_setprio(0); } while (0)
; #define PG8_WAIT_V(n) asm volatile("s_waitcnt vmcnt(" #n ")" ::: "memory")
; #define PG8_WAIT_L(n) asm volatile("s_waitcnt lgkmcnt(" #n ")" ::: "memory")
; #define PG8_BAR __builtin_amdgcn_s_barrier()
; #define PG8_SCHED __builtin_amdgcn_sched_barrier(0)
; template <class Epi, class Sched, bool ALIGN_EPI = false, bool SP2 = false>
; __device__ __forceinline__ void gemm_phase(PG8_LAS unsigned char* lds, const Gemm g, const Sched& S, const Epi& E) {
;     ...
;         for (int t = 0; t < nt; t += 2) {
;     ...
;             PG8_WAIT_V(8); PG8_WAIT_L(0); PG8_BAR; PG8_MMA(0, 0, At, B0); PG8_MMA(0, 1, At, B1); PG8_BAR; PG8_SCHED;
;             PG8_LDA(At, 1, 1); PG8_STAGE(PG8_SB(1, 0), b3, voffB); PG8_STAGE(PG8_SB(1, 1), b3 + hstep, voffB); PG8_STAGE(PG8_SA(1, 0), a3, voffA);
;             PG8_WAIT_V(8); PG8_WAIT_L(0); PG8_BAR; PG8_MMA(1, 0, At, B0); PG8_MMA(1, 1, At, B1); PG8_BAR; PG8_SCHED;
.Lrsb_d:
	s_waitcnt lgkmcnt(0)
	s_barrier
	s_setprio 1
	s_waitcnt lgkmcnt(0)
	v_mfma_f32_16x16x32_bf16 v[124:127], v[144:147], v[202:205], v[124:127]
	v_mfma_f32_16x16x32_bf16 v[116:119], v[178:181], v[202:205], v[116:119]
	v_mfma_f32_16x16x32_bf16 v[108:111], v[144:147], v[210:213], v[108:111]
	v_mfma_f32_16x16x32_bf16 v[100:103], v[178:181], v[210:213], v[100:103]
	v_mfma_f32_16x16x32_bf16 v[92:95], v[144:147], v[218:221], v[92:95]
	v_mfma_f32_16x16x32_bf16 v[84:87], v[178:181], v[218:221], v[84:87]
	v_mfma_f32_16x16x32_bf16 v[76:79], v[144:147], v[226:229], v[76:79]
	v_mfma_f32_16x16x32_bf16 v[68:71], v[178:181], v[226:229], v[68:71]
	v_mfma_f32_16x16x32_bf16 v[124:127], v[170:173], v[206:209], v[124:127]
	v_mfma_f32_16x16x32_bf16 v[116:119], v[182:185], v[206:209], v[116:119]
	v_mfma_f32_16x16x32_bf16 v[108:111], v[170:173], v[214:217], v[108:111]
	v_mfma_f32_16x16x32_bf16 v[100:103], v[182:185], v[214:217], v[100:103]
	v_mfma_f32_16x16x32_bf16 v[92:95], v[170:173], v[222:225], v[92:95]
	v_mfma_f32_16x16x32_bf16 v[84:87], v[182:185], v[222:225], v[84:87]
	v_mfma_f32_16x16x32_bf16 v[76:79], v[170:173], v[232:235], v[76:79]
	v_mfma_f32_16x16x32_bf16 v[68:71], v[182:185], v[232:235], v[68:71]
	s_setprio 0
	s_setprio 1
	v_mfma_f32_16x16x32_bf16 v[120:123], v[186:189], v[202:205], v[120:123]
	v_mfma_f32_16x16x32_bf16 v[112:115], v[194:197], v[202:205], v[112:115]
	v_mfma_f32_16x16x32_bf16 v[104:107], v[186:189], v[210:213], v[104:107]
	v_mfma_f32_16x16x32_bf16 v[96:99], v[194:197], v[210:213], v[96:99]
	v_mfma_f32_16x16x32_bf16 v[88:91], v[186:189], v[218:221], v[88:91]
	v_mfma_f32_16x16x32_bf16 v[80:83], v[194:197], v[218:221], v[80:83]
	v_mfma_f32_16x16x32_bf16 v[72:75], v[186:189], v[226:229], v[72:75]
	v_mfma_f32_16x16x32_bf16 v[64:67], v[194:197], v[226:229], v[64:67]
	v_mfma_f32_16x16x32_bf16 v[120:123], v[190:193], v[206:209], v[120:123]
	v_mfma_f32_16x16x32_bf16 v[112:115], v[198:201], v[206:209], v[112:115]
	v_mfma_f32_16x16x32_bf16 v[104:107], v[190:193], v[214:217], v[104:107]
	v_mfma_f32_16x16x32_bf16 v[96:99], v[198:201], v[214:217], v[96:99]
	v_mfma_f32_16x16x32_bf16 v[88:91], v[190:193], v[222:225], v[88:91]
	v_mfma_f32_16x16x32_bf16 v[80:83], v[198:201], v[222:225], v[80:83]
	v_mfma_f32_16x16x32_bf16 v[72:75], v[190:193], v[232:235], v[72:75]
	v_mfma_f32_16x16x32_bf16 v[64:67], v[198:201], v[232:235], v[64:67]
	s_setprio 0
	s_barrier
	s_add_i32 s38, s59, s43
	v_lshl_add_u64 v[150:151], v[150:151], 0, s[12:13]
	s_mov_b32 m0, s38
	ds_read_b128 v[202:205], v169 offset:49152
	ds_read_b128 v[206:209], v169 offset:50176
	ds_read_b128 v[210:213], v169 offset:51200
	ds_read_b128 v[214:217], v169 offset:52224
	ds_read_b128 v[218:221], v169 offset:53248
	ds_read_b128 v[222:225], v169 offset:54272
	ds_read_b128 v[226:229], v169 offset:55296
	ds_read_b128 v[232:235], v169 offset:56320
	global_load_lds_dwordx4 v[150:151], off
	s_add_i32 m0, s38, 0x2000
	s_add_u32 s36, s36, 0x40080
	v_lshl_add_u64 v[150:151], v[154:155], 0, s[12:13]
	s_addc_u32 s37, s37, 0
	s_add_i32 s38, s60, s43
	global_load_lds_dwordx4 v[150:151], off
	v_lshl_add_u64 v[150:151], s[36:37], 0, v[130:131]
	s_mov_b32 m0, s38
	s_nop 0
	global_load_lds_dwordx4 v[150:151], off
	v_lshl_add_u64 v[150:151], s[36:37], 0, v[134:135]
	s_add_i32 m0, s38, 0x2000
	s_nop 0
	global_load_lds_dwordx4 v[150:151], off
	v_lshl_add_u64 v[150:151], v[158:159], 0, s[12:13]
	s_mov_b32 m0, s47
	s_nop 0
	global_load_lds_dwordx4 v[150:151], off
	v_lshl_add_u64 v[150:151], v[162:163], 0, s[12:13]
	s_mov_b32 m0, s48
	s_nop 0
	global_load_lds_dwordx4 v[150:151], off
	s_waitcnt vmcnt(8)
	s_waitcnt lgkmcnt(0)
	s_barrier
	s_setprio 1
	s_waitcnt lgkmcnt(0)
	v_mfma_f32_16x16x32_bf16 v[60:63], v[144:147], v[202:205], v[60:63]
	v_mfma_f32_16x16x32_bf16 v[52:55], v[178:181], v[202:205], v[52:55]
	v_mfma_f32_16x16x32_bf16 v[44:47], v[144:147], v[210:213], v[44:47]
	v_mfma_f32_16x16x32_bf16 v[36:39], v[178:181], v[210:213], v[36:39]
	v_mfma_f32_16x16x32_bf16 v[28:31], v[144:147], v[218:221], v[28:31]
	v_mfma_f32_16x16x32_bf16 v[20:23], v[178:181], v[218:221], v[20:23]
	v_mfma_f32_16x16x32_bf16 v[12:15], v[144:147], v[226:229], v[12:15]
	v_mfma_f32_16x16x32_bf16 v[4:7], v[178:181], v[226:229], v[4:7]
	v_mfma_f32_16x16x32_bf16 v[60:63], v[170:173], v[206:209], v[60:63]
	v_mfma_f32_16x16x32_bf16 v[52:55], v[182:185], v[206:209], v[52:55]
	v_mfma_f32_16x16x32_bf16 v[44:47], v[170:173], v[214:217], v[44:47]
	v_mfma_f32_16x16x32_bf16 v[36:39], v[182:185], v[214:217], v[36:39]
	v_mfma_f32_16x16x32_bf16 v[28:31], v[170:173], v[222:225], v[28:31]
	v_mfma_f32_16x16x32_bf16 v[20:23], v[182:185], v[222:225], v[20:23]
	v_mfma_f32_16x16x32_bf16 v[12:15], v[170:173], v[232:235], v[12:15]
	v_mfma_f32_16x16x32_bf16 v[4:7], v[182:185], v[232:235], v[4:7]
	s_setprio 0
	s_setprio 1
	v_mfma_f32_16x16x32_bf16 v[56:59], v[186:189], v[202:205], v[56:59]
	v_mfma_f32_16x16x32_bf16 v[48:51], v[194:197], v[202:205], v[48:51]
	v_mfma_f32_16x16x32_bf16 v[40:43], v[186:189], v[210:213], v[40:43]
	v_mfma_f32_16x16x32_bf16 v[32:35], v[194:197], v[210:213], v[32:35]
	v_mfma_f32_16x16x32_bf16 v[24:27], v[186:189], v[218:221], v[24:27]
	v_mfma_f32_16x16x32_bf16 v[16:19], v[194:197], v[218:221], v[16:19]
	v_mfma_f32_16x16x32_bf16 v[8:11], v[186:189], v[226:229], v[8:11]
	v_mfma_f32_16x16x32_bf16 v[0:3], v[194:197], v[226:229], v[0:3]
	v_mfma_f32_16x16x32_bf16 v[56:59], v[190:193], v[206:209], v[56:59]
	v_mfma_f32_16x16x32_bf16 v[48:51], v[198:201], v[206:209], v[48:51]
	v_mfma_f32_16x16x32_bf16 v[40:43], v[190:193], v[214:217], v[40:43]
	v_mfma_f32_16x16x32_bf16 v[32:35], v[198:201], v[214:217], v[32:35]
	v_mfma_f32_16x16x32_bf16 v[24:27], v[190:193], v[222:225], v[24:27]
	v_mfma_f32_16x16x32_bf16 v[16:19], v[198:201], v[222:225], v[16:19]
	v_mfma_f32_16x16x32_bf16 v[8:11], v[190:193], v[232:235], v[8:11]
	v_mfma_f32_16x16x32_bf16 v[0:3], v[198:201], v[232:235], v[0:3]
	s_setprio 0
	s_barrier
	s_add_i32 s58, s58, 2
	s_add_u32 s34, s34, 0x100
	s_addc_u32 s35, s35, 0
	s_add_u32 s56, s56, 0x100
	s_addc_u32 s57, s57, 0
	s_cmp_gt_u32 s58, 13
	s_cbranch_scc0 .LBB0_977
	s_and_b64 vcc, exec, s[16:17]
	s_cbranch_vccz .LBB0_980
	s_barrier
; __device__ __forceinline__ float fast_sigmoid(float x) { return __builtin_amdgcn_rcpf(1.0f + __expf(-x)); }
; __device__ __forceinline__ void rows_rstd(const float* ssq, int row0, int fq, float (&rs)[2][4]) {
;     f32x4 pr[2][4];
; #pragma unroll
;     for (int ai = 0; ai < 2; ++ai)
; #pragma unroll
;         for (int m = 0; m < 4; ++m) pr[ai][m] = *(const f32x4*)(ssq + (size_t)(row0 + ai * HALF + m * 16) * 16 + 4 * fq);
; #pragma unroll
;     for (int ai = 0; ai < 2; ++ai)
; #pragma unroll
;         for (int m = 0; m < 4; ++m) { float t = (pr[ai][m][0] + pr[ai][m][1]) + (pr[ai][m][2] + pr[ai][m][3]); t += __shfl_xor(t, 16); t += __shfl_xor(t, 32); rs[ai][m] = __builtin_amdgcn_rsqf(t * (1.0f / 1024.0f) + 1e-6f); }
;     __device__ __forceinline__ void operator()(const f32x4 (&acc)[2][2][4][2], const Unit& u, int wr, int wc, int fr, int fq) const {
;         const int col0 = u.pn * HALF + wc * 32 + 8 * fq;
;         float rsv[2][4]; rows_rstd(ssq, u.pm * BM + wr * 64 + fr, fq, rsv);
; #pragma unroll
;         for (int ai = 0; ai < 2; ++ai)
; #pragma unroll
;             for (int m = 0; m < 4; ++m) {
;                 const int row = u.pm * BM + ai * HALF + wr * 64 + m * 16 + fr;
;                 const float rs = rsv[ai][m];
;                 float h[8];
; #pragma unroll
;                 for (int n = 0; n < 2; ++n)
; #pragma unroll
;                     for (int i = 0; i < 4; ++i) { const float g = acc[ai][0][m][n][i] * rs, up = acc[ai][1][m][n][i] * rs; h[4 * n + i] = g * up * fast_sigmoid(g); }
.LBB0_980:
	v_mbcnt_lo_u32_b32 v252, -1, 0
	v_mbcnt_hi_u32_b32 v252, -1, v252
	v_and_b32_e32 v252, 48, v252
	v_lshl_add_u32 v252, v149, 6, v252
	v_add_u32_e32 v252, 0x20000, v252
	v_lshl_add_u32 v170, s30, 8, v149
	v_ashrrev_i32_e32 v171, 31, v170
	v_or_b32_e32 v166, 16, v170
	v_lshlrev_b64 v[144:145], 6, v[170:171]
	v_ashrrev_i32_e32 v167, 31, v166
	v_or_b32_e32 v162, 32, v170
	v_lshl_add_u64 v[144:145], v[136:137], 0, v[144:145]
	v_lshlrev_b64 v[146:147], 6, v[166:167]
	v_ashrrev_i32_e32 v163, 31, v162
	v_or_b32_e32 v158, 48, v170
	v_lshl_add_u64 v[146:147], v[136:137], 0, v[146:147]
	ds_read_b128 v[178:181], v252 offset:0
	ds_read_b128 v[182:185], v252 offset:1024
	v_lshlrev_b64 v[144:145], 6, v[162:163]
	v_ashrrev_i32_e32 v159, 31, v158
	v_add_u32_e32 v154, 0x80, v170
	v_lshl_add_u64 v[144:145], v[136:137], 0, v[144:145]
	v_lshlrev_b64 v[146:147], 6, v[158:159]
	v_ashrrev_i32_e32 v155, 31, v154
	v_lshl_add_u64 v[146:147], v[136:137], 0, v[146:147]
	ds_read_b128 v[186:189], v252 offset:2048
	ds_read_b128 v[190:193], v252 offset:3072
	v_lshlrev_b64 v[144:145], 6, v[154:155]
	v_lshl_add_u64 v[144:145], v[136:137], 0, v[144:145]
	ds_read_b128 v[194:197], v252 offset:8192
	v_add_u32_e32 v150, 0x90, v170
	v_ashrrev_i32_e32 v151, 31, v150
	v_lshlrev_b64 v[144:145], 6, v[150:151]
	v_add_u32_e32 v146, 0xa0, v170
	v_lshl_add_u64 v[144:145], v[136:137], 0, v[144:145]
	v_ashrrev_i32_e32 v147, 31, v146
	ds_read_b128 v[198:201], v252 offset:9216
	v_lshlrev_b64 v[144:145], 6, v[146:147]
	v_lshl_add_u64 v[144:145], v[136:137], 0, v[144:145]
	ds_read_b128 v[202:205], v252 offset:10240
	v_add_u32_e32 v144, 0xb0, v170
	v_ashrrev_i32_e32 v145, 31, v144
	v_lshlrev_b64 v[206:207], 6, v[144:145]
	v_lshl_add_u64 v[206:207], v[136:137], 0, v[206:207]
	ds_read_b128 v[206:209], v252 offset:11264
	v_and_b32_e32 v147, 64, v175
	v_xor_b32_e32 v145, 16, v175
	v_add_u32_e32 v147, 64, v147
	v_xor_b32_e32 v148, 32, v175
	v_cmp_lt_i32_e32 vcc, v145, v147
	v_lshl_or_b32 v172, s28, 7, v157
	v_ashrrev_i32_e32 v173, 31, v172
	v_cndmask_b32_e32 v145, v175, v145, vcc
	v_cmp_lt_i32_e32 vcc, v148, v147
	v_lshlrev_b32_e32 v145, 2, v145
	s_waitcnt lgkmcnt(0)
	v_mov_b32_e32 v210, v179
	v_mov_b32_e32 v211, v180
	v_mov_b32_e32 v179, v181
	v_pk_add_f32 v[178:179], v[210:211], v[178:179]
	v_mov_b32_e32 v180, v183
	v_mov_b32_e32 v181, v184
	v_mov_b32_e32 v183, v185
	v_cndmask_b32_e32 v147, v175, v148, vcc
	v_mov_b32_e32 v184, v187
	v_mov_b32_e32 v185, v188
	v_mov_b32_e32 v187, v189
	v_mov_b32_e32 v188, v191
	v_mov_b32_e32 v189, v192
	v_mov_b32_e32 v191, v193
	v_add_f32_e32 v148, v178, v179
	v_pk_add_f32 v[178:179], v[180:181], v[182:183]
	v_pk_add_f32 v[180:181], v[184:185], v[186:187]
	v_pk_add_f32 v[182:183], v[188:189], v[190:191]
	v_mov_b32_e32 v192, v195
	v_mov_b32_e32 v193, v196
	v_mov_b32_e32 v195, v197
	ds_bpermute_b32 v151, v145, v148
	v_add_f32_e32 v152, v178, v179
	v_add_f32_e32 v155, v180, v181
	v_add_f32_e32 v156, v182, v183
	v_pk_add_f32 v[184:185], v[192:193], v[194:195]
	ds_bpermute_b32 v160, v145, v152
	ds_bpermute_b32 v163, v145, v155
	ds_bpermute_b32 v164, v145, v156
	v_add_f32_e32 v159, v184, v185
	ds_bpermute_b32 v167, v145, v159
	v_lshlrev_b32_e32 v147, 2, v147
	s_waitcnt lgkmcnt(4)
	v_add_f32_e32 v148, v148, v151
	ds_bpermute_b32 v151, v147, v148
	s_waitcnt lgkmcnt(4)
	v_add_f32_e32 v152, v152, v160
	s_waitcnt lgkmcnt(3)
	v_add_f32_e32 v155, v155, v163
	s_waitcnt lgkmcnt(2)
	v_add_f32_e32 v156, v156, v164
	ds_bpermute_b32 v160, v147, v152
	ds_bpermute_b32 v163, v147, v155
	ds_bpermute_b32 v164, v147, v156
	s_waitcnt lgkmcnt(4)
	v_add_f32_e32 v159, v159, v167
	ds_bpermute_b32 v167, v147, v159
	s_waitcnt lgkmcnt(4)
	v_add_f32_e32 v148, v148, v151
	v_fmamk_f32 v148, v148, 0x3a800000, v176
	s_waitcnt lgkmcnt(3)
	v_add_f32_e32 v151, v152, v160
	s_waitcnt lgkmcnt(2)
	v_add_f32_e32 v152, v155, v163
	s_waitcnt lgkmcnt(1)
	v_add_f32_e32 v155, v156, v164
	v_mov_b32_e32 v180, v199
	v_mov_b32_e32 v181, v200
	v_mov_b32_e32 v199, v201
	v_rsq_f32_e32 v178, v148
	v_fmamk_f32 v148, v151, 0x3a800000, v176
	v_fmamk_f32 v151, v152, 0x3a800000, v176
	v_fmamk_f32 v152, v155, 0x3a800000, v176
	v_pk_add_f32 v[180:181], v[180:181], v[198:199]
	v_rsq_f32_e32 v174, v148
	v_add_f32_e32 v148, v180, v181
	v_rsq_f32_e32 v164, v152
	s_waitcnt lgkmcnt(0)
	v_add_f32_e32 v152, v159, v167
	v_mov_b32_e32 v180, v203
	v_mov_b32_e32 v181, v204
	v_mov_b32_e32 v203, v205
	v_fmamk_f32 v152, v152, 0x3a800000, v176
	v_pk_add_f32 v[180:181], v[180:181], v[202:203]
	v_rsq_f32_e32 v160, v152
	v_add_f32_e32 v152, v180, v181
	v_mov_b32_e32 v180, v207
	v_mov_b32_e32 v181, v208
	v_mov_b32_e32 v207, v209
	v_pk_add_f32 v[180:181], v[180:181], v[206:207]
	v_rsq_f32_e32 v168, v151
	v_add_f32_e32 v156, v180, v181
	v_mov_b32_e32 v180, v124
	v_mov_b32_e32 v181, v120
	v_pk_mul_f32 v[180:181], v[180:181], v[178:179] op_sel_hi:[1,0]
	ds_bpermute_b32 v151, v145, v148
	v_mul_f32_e32 v120, 0xbfb8aa3b, v180
	v_exp_f32_e32 v124, v120
	v_mov_b32_e32 v120, v125
	v_pk_mul_f32 v[120:121], v[120:121], v[178:179] op_sel_hi:[1,0]
	s_waitcnt lgkmcnt(0)
	v_add_f32_e32 v148, v148, v151
	v_mul_f32_e32 v125, 0xbfb8aa3b, v120
	v_exp_f32_e32 v125, v125
	ds_bpermute_b32 v151, v147, v148
	ds_bpermute_b32 v155, v145, v152
	ds_bpermute_b32 v145, v145, v156
	v_add_f32_e32 v125, 1.0, v125
	v_rcp_f32_e32 v125, v125
	v_mul_f32_e32 v120, v120, v121
	s_waitcnt lgkmcnt(2)
	v_add_f32_e32 v148, v148, v151
	s_waitcnt lgkmcnt(1)
	v_add_f32_e32 v151, v152, v155
	s_waitcnt lgkmcnt(0)
; __device__ __forceinline__ unsigned cvt_pk_bf16(float lo, float hi) { unsigned r; asm volatile("v_cvt_pk_bf16_f32 %0, %1, %2" : "=v"(r) : "v"(lo), "v"(hi)); return r; }
; __device__ __forceinline__ float fast_sigmoid(float x) { return __builtin_amdgcn_rcpf(1.0f + __expf(-x)); }
;     __device__ __forceinline__ void operator()(const f32x4 (&acc)[2][2][4][2], const Unit& u, int wr, int wc, int fr, int fq) const {
;     ...
;         for (int ai = 0; ai < 2; ++ai)
; #pragma unroll
;             for (int m = 0; m < 4; ++m) {
;                 const int row = u.pm * BM + ai * HALF + wr * 64 + m * 16 + fr;
;                 const float rs = rsv[ai][m];
;                 float h[8];
; #pragma unroll
;                 for (int n = 0; n < 2; ++n)
; #pragma unroll
;                     for (int i = 0; i < 4; ++i) { const float g = acc[ai][0][m][n][i] * rs, up = acc[ai][1][m][n][i] * rs; h[4 * n + i] = g * up * fast_sigmoid(g); }
;                 u32x4 w; w.x = cvt_pk_bf16(h[0], h[1]); w.y = cvt_pk_bf16(h[2], h[3]); w.z = cvt_pk_bf16(h[4], h[5]); w.w = cvt_pk_bf16(h[6], h[7]);
;                 *(u32x4*)(H + (size_t)row * 2816 + col0) = w;
	v_add_f32_e32 v145, v156, v145
	v_mul_f32_e32 v125, v120, v125
	v_mov_b32_e32 v120, v126
	v_mov_b32_e32 v121, v122
	ds_bpermute_b32 v152, v147, v151
	ds_bpermute_b32 v147, v147, v145
	v_pk_mul_f32 v[120:121], v[120:121], v[178:179] op_sel_hi:[1,0]
	v_add_f32_e32 v124, 1.0, v124
	v_mul_f32_e32 v122, 0xbfb8aa3b, v120
	v_exp_f32_e32 v126, v122
	v_mov_b32_e32 v122, v127
	v_pk_mul_f32 v[122:123], v[122:123], v[178:179] op_sel_hi:[1,0]
	v_fmamk_f32 v148, v148, 0x3a800000, v176
	v_rcp_f32_e32 v124, v124
	v_mul_f32_e32 v127, 0xbfb8aa3b, v122
	v_rsq_f32_e32 v156, v148
	s_waitcnt lgkmcnt(1)
	v_add_f32_e32 v148, v151, v152
	s_waitcnt lgkmcnt(0)
	v_add_f32_e32 v145, v145, v147
	v_exp_f32_e32 v127, v127
	v_fmamk_f32 v148, v148, 0x3a800000, v176
	v_fmamk_f32 v145, v145, 0x3a800000, v176
	v_rsq_f32_e32 v152, v148
	v_rsq_f32_e32 v148, v145
	v_mul_f32_e32 v145, v180, v181
	v_mul_f32_e32 v124, v145, v124
	v_mul_f32_e32 v145, v120, v121
	v_add_f32_e32 v120, 1.0, v126
	v_rcp_f32_e32 v126, v120
	v_add_f32_e32 v120, 1.0, v127
	v_rcp_f32_e32 v127, v120
	v_mov_b32_e32 v120, v116
	v_mov_b32_e32 v121, v112
	v_pk_mul_f32 v[120:121], v[120:121], v[178:179] op_sel_hi:[1,0]
	v_mul_f32_e32 v116, v122, v123
	v_mul_f32_e32 v112, 0xbfb8aa3b, v120
	v_exp_f32_e32 v112, v112
	v_mul_f32_e32 v122, v116, v127
	v_mul_f32_e32 v120, v120, v121
	v_mul_f32_e32 v126, v145, v126
	v_add_f32_e32 v112, 1.0, v112
	v_rcp_f32_e32 v116, v112
	v_mov_b32_e32 v112, v117
	v_pk_mul_f32 v[112:113], v[112:113], v[178:179] op_sel_hi:[1,0]
	v_mov_b32_e32 v123, v104
	v_mul_f32_e32 v117, 0xbfb8aa3b, v112
	v_exp_f32_e32 v117, v117
	v_mul_f32_e32 v120, v120, v116
	v_mul_f32_e32 v116, v112, v113
	v_mov_b32_e32 v113, v114
	v_add_f32_e32 v112, 1.0, v117
	v_rcp_f32_e32 v117, v112
	v_mov_b32_e32 v112, v118
	v_pk_mul_f32 v[112:113], v[112:113], v[178:179] op_sel_hi:[1,0]
	s_andn2_b64 vcc, exec, s[22:23]
	v_mul_f32_e32 v114, 0xbfb8aa3b, v112
	v_exp_f32_e32 v118, v114
	v_mov_b32_e32 v114, v119
	v_pk_mul_f32 v[114:115], v[114:115], v[178:179] op_sel_hi:[1,0]
	v_mul_f32_e32 v121, v116, v117
	v_mul_f32_e32 v119, 0xbfb8aa3b, v114
	v_exp_f32_e32 v119, v119
	v_add_f32_e32 v116, 1.0, v118
	v_rcp_f32_e32 v116, v116
	v_mul_f32_e32 v112, v112, v113
	v_add_f32_e32 v117, 1.0, v119
	v_rcp_f32_e32 v117, v117
	v_mul_f32_e32 v113, v114, v115
	v_mul_f32_e32 v112, v112, v116
	v_cvt_pk_bf16_f32 v116, v124, v125
	v_mul_f32_e32 v113, v113, v117
	v_cvt_pk_bf16_f32 v117, v126, v122
	v_mov_b32_e32 v122, v108
	v_pk_mul_f32 v[122:123], v[122:123], v[174:175] op_sel_hi:[1,0]
	v_cvt_pk_bf16_f32 v118, v120, v121
	v_cvt_pk_bf16_f32 v119, v112, v113
	v_mov_b64_e32 v[112:113], s[6:7]
	v_mul_f32_e32 v104, 0xbfb8aa3b, v122
	v_exp_f32_e32 v108, v104
	v_mov_b32_e32 v104, v109
	v_pk_mul_f32 v[104:105], v[104:105], v[174:175] op_sel_hi:[1,0]
	v_mad_i64_i32 v[120:121], s[34:35], v170, s52, v[112:113]
	v_mul_f32_e32 v109, 0xbfb8aa3b, v104
	v_exp_f32_e32 v109, v109
	v_mul_f32_e32 v104, v104, v105
	v_mov_b32_e32 v105, v106
	v_add_f32_e32 v108, 1.0, v108
	v_add_f32_e32 v109, 1.0, v109
	v_rcp_f32_e32 v109, v109
	v_rcp_f32_e32 v108, v108
	v_lshlrev_b64 v[114:115], 1, v[172:173]
	v_lshl_add_u64 v[120:121], v[120:121], 0, v[114:115]
	v_mul_f32_e32 v109, v104, v109
	v_mov_b32_e32 v104, v110
	v_pk_mul_f32 v[104:105], v[104:105], v[174:175] op_sel_hi:[1,0]
	global_store_dwordx4 v[120:121], v[116:119], off
	v_mul_f32_e32 v106, 0xbfb8aa3b, v104
	v_exp_f32_e32 v110, v106
	v_mov_b32_e32 v106, v111
	v_pk_mul_f32 v[106:107], v[106:107], v[174:175] op_sel_hi:[1,0]
	v_mul_f32_e32 v116, v122, v123
	v_mul_f32_e32 v111, 0xbfb8aa3b, v106
	v_exp_f32_e32 v111, v111
	v_mul_f32_e32 v108, v116, v108
	v_mul_f32_e32 v116, v104, v105
	v_add_f32_e32 v104, 1.0, v110
	v_rcp_f32_e32 v110, v104
	v_add_f32_e32 v104, 1.0, v111
	v_rcp_f32_e32 v111, v104
	v_mov_b32_e32 v104, v100
	v_mov_b32_e32 v105, v96
	v_pk_mul_f32 v[104:105], v[104:105], v[174:175] op_sel_hi:[1,0]
	v_mul_f32_e32 v106, v106, v107
	v_mul_f32_e32 v96, 0xbfb8aa3b, v104
	v_exp_f32_e32 v96, v96
	v_mul_f32_e32 v104, v104, v105
	v_mul_f32_e32 v100, v116, v110
	v_mul_f32_e32 v106, v106, v111
	v_add_f32_e32 v96, 1.0, v96
	v_rcp_f32_e32 v107, v96
	v_mov_b32_e32 v96, v101
	v_pk_mul_f32 v[96:97], v[96:97], v[174:175] op_sel_hi:[1,0]
	s_mov_b64 s[22:23], -1
	v_mul_f32_e32 v101, 0xbfb8aa3b, v96
	v_exp_f32_e32 v101, v101
	v_mul_f32_e32 v105, v96, v97
	v_mov_b32_e32 v97, v98
	v_mul_f32_e32 v104, v104, v107
	v_add_f32_e32 v96, 1.0, v101
	v_rcp_f32_e32 v101, v96
	v_mov_b32_e32 v96, v102
	v_pk_mul_f32 v[96:97], v[96:97], v[174:175] op_sel_hi:[1,0]
	v_mul_f32_e32 v101, v105, v101
	v_mul_f32_e32 v98, 0xbfb8aa3b, v96
	v_exp_f32_e32 v102, v98
	v_mov_b32_e32 v98, v103
	v_pk_mul_f32 v[98:99], v[98:99], v[174:175] op_sel_hi:[1,0]
	v_mul_f32_e32 v96, v96, v97
	v_mul_f32_e32 v103, 0xbfb8aa3b, v98
	v_exp_f32_e32 v103, v103
	v_add_f32_e32 v102, 1.0, v102
	v_rcp_f32_e32 v102, v102
	v_add_f32_e32 v103, 1.0, v103
	v_rcp_f32_e32 v103, v103
	v_mul_f32_e32 v102, v96, v102
	v_mul_f32_e32 v96, v98, v99
	v_mul_f32_e32 v99, v96, v103
	v_cvt_pk_bf16_f32 v96, v108, v109
	v_cvt_pk_bf16_f32 v97, v100, v106
	v_cvt_pk_bf16_f32 v98, v104, v101
	v_cvt_pk_bf16_f32 v99, v102, v99
	v_mov_b32_e32 v102, v92
	v_mov_b32_e32 v103, v88
	v_pk_mul_f32 v[102:103], v[102:103], v[168:169] op_sel_hi:[1,0]
	v_mad_i64_i32 v[100:101], s[34:35], v166, s52, v[112:113]
	v_mul_f32_e32 v88, 0xbfb8aa3b, v102
	v_exp_f32_e32 v92, v88
	v_mov_b32_e32 v88, v93
	v_pk_mul_f32 v[88:89], v[88:89], v[168:169] op_sel_hi:[1,0]
	v_lshl_add_u64 v[100:101], v[100:101], 0, v[114:115]
	v_mul_f32_e32 v93, 0xbfb8aa3b, v88
	v_exp_f32_e32 v93, v93
	v_mul_f32_e32 v88, v88, v89
	v_mov_b32_e32 v89, v90
; __device__ __forceinline__ unsigned cvt_pk_bf16(float lo, float hi) { unsigned r; asm volatile("v_cvt_pk_bf16_f32 %0, %1, %2" : "=v"(r) : "v"(lo), "v"(hi)); return r; }
; __device__ __forceinline__ float fast_sigmoid(float x) { return __builtin_amdgcn_rcpf(1.0f + __expf(-x)); }
;     __device__ __forceinline__ void operator()(const f32x4 (&acc)[2][2][4][2], const Unit& u, int wr, int wc, int fr, int fq) const {
;     ...
;         for (int ai = 0; ai < 2; ++ai)
; #pragma unroll
;             for (int m = 0; m < 4; ++m) {
;                 const int row = u.pm * BM + ai * HALF + wr * 64 + m * 16 + fr;
;                 const float rs = rsv[ai][m];
;                 float h[8];
; #pragma unroll
;                 for (int n = 0; n < 2; ++n)
; #pragma unroll
;                     for (int i = 0; i < 4; ++i) { const float g = acc[ai][0][m][n][i] * rs, up = acc[ai][1][m][n][i] * rs; h[4 * n + i] = g * up * fast_sigmoid(g); }
;                 u32x4 w; w.x = cvt_pk_bf16(h[0], h[1]); w.y = cvt_pk_bf16(h[2], h[3]); w.z = cvt_pk_bf16(h[4], h[5]); w.w = cvt_pk_bf16(h[6], h[7]);
;                 *(u32x4*)(H + (size_t)row * 2816 + col0) = w;
	v_add_f32_e32 v92, 1.0, v92
	v_add_f32_e32 v93, 1.0, v93
	v_rcp_f32_e32 v93, v93
	v_rcp_f32_e32 v92, v92
	global_store_dwordx4 v[100:101], v[96:99], off
	v_mul_f32_e32 v93, v88, v93
	v_mov_b32_e32 v88, v94
	v_pk_mul_f32 v[88:89], v[88:89], v[168:169] op_sel_hi:[1,0]
	v_mul_f32_e32 v96, v102, v103
	v_mul_f32_e32 v90, 0xbfb8aa3b, v88
	v_exp_f32_e32 v94, v90
	v_mov_b32_e32 v90, v95
	v_pk_mul_f32 v[90:91], v[90:91], v[168:169] op_sel_hi:[1,0]
	v_mul_f32_e32 v92, v96, v92
	v_mul_f32_e32 v95, 0xbfb8aa3b, v90
	v_exp_f32_e32 v95, v95
	v_mul_f32_e32 v96, v88, v89
	v_add_f32_e32 v88, 1.0, v94
	v_rcp_f32_e32 v94, v88
	v_add_f32_e32 v88, 1.0, v95
	v_rcp_f32_e32 v95, v88
	v_mov_b32_e32 v88, v84
	v_mov_b32_e32 v89, v80
	v_pk_mul_f32 v[88:89], v[88:89], v[168:169] op_sel_hi:[1,0]
	v_mul_f32_e32 v90, v90, v91
	v_mul_f32_e32 v80, 0xbfb8aa3b, v88
	v_exp_f32_e32 v80, v80
	v_mul_f32_e32 v88, v88, v89
	v_mul_f32_e32 v84, v96, v94
	v_mul_f32_e32 v90, v90, v95
	v_add_f32_e32 v80, 1.0, v80
	v_rcp_f32_e32 v91, v80
	v_mov_b32_e32 v80, v85
	v_pk_mul_f32 v[80:81], v[80:81], v[168:169] op_sel_hi:[1,0]
	v_mul_f32_e32 v88, v88, v91
	v_mul_f32_e32 v85, 0xbfb8aa3b, v80
	v_exp_f32_e32 v85, v85
	v_mul_f32_e32 v89, v80, v81
	v_mov_b32_e32 v81, v82
	v_add_f32_e32 v80, 1.0, v85
	v_rcp_f32_e32 v85, v80
	v_mov_b32_e32 v80, v86
	v_pk_mul_f32 v[80:81], v[80:81], v[168:169] op_sel_hi:[1,0]
	v_mul_f32_e32 v85, v89, v85
	v_mul_f32_e32 v82, 0xbfb8aa3b, v80
	v_exp_f32_e32 v86, v82
	v_mov_b32_e32 v82, v87
	v_pk_mul_f32 v[82:83], v[82:83], v[168:169] op_sel_hi:[1,0]
	v_mul_f32_e32 v80, v80, v81
	v_mul_f32_e32 v87, 0xbfb8aa3b, v82
	v_exp_f32_e32 v87, v87
	v_add_f32_e32 v86, 1.0, v86
	v_rcp_f32_e32 v86, v86
	v_add_f32_e32 v87, 1.0, v87
	v_rcp_f32_e32 v87, v87
	v_mul_f32_e32 v86, v80, v86
	v_mul_f32_e32 v80, v82, v83
	v_mul_f32_e32 v83, v80, v87
	v_cvt_pk_bf16_f32 v80, v92, v93
	v_cvt_pk_bf16_f32 v81, v84, v90
	v_cvt_pk_bf16_f32 v82, v88, v85
	v_cvt_pk_bf16_f32 v83, v86, v83
	v_mov_b32_e32 v86, v76
	v_mov_b32_e32 v87, v72
	v_pk_mul_f32 v[86:87], v[86:87], v[164:165] op_sel_hi:[1,0]
	v_mad_i64_i32 v[84:85], s[34:35], v162, s52, v[112:113]
	v_mul_f32_e32 v72, 0xbfb8aa3b, v86
	v_exp_f32_e32 v76, v72
	v_mov_b32_e32 v72, v77
	v_pk_mul_f32 v[72:73], v[72:73], v[164:165] op_sel_hi:[1,0]
	v_lshl_add_u64 v[84:85], v[84:85], 0, v[114:115]
	v_mul_f32_e32 v77, 0xbfb8aa3b, v72
	v_exp_f32_e32 v77, v77
	v_mul_f32_e32 v72, v72, v73
	v_mov_b32_e32 v73, v74
	v_add_f32_e32 v76, 1.0, v76
	v_add_f32_e32 v77, 1.0, v77
	v_rcp_f32_e32 v77, v77
	v_rcp_f32_e32 v76, v76
	global_store_dwordx4 v[84:85], v[80:83], off
	v_mul_f32_e32 v77, v72, v77
	v_mov_b32_e32 v72, v78
	v_pk_mul_f32 v[72:73], v[72:73], v[164:165] op_sel_hi:[1,0]
	v_mul_f32_e32 v80, v86, v87
	v_mul_f32_e32 v74, 0xbfb8aa3b, v72
	v_exp_f32_e32 v78, v74
	v_mov_b32_e32 v74, v79
	v_pk_mul_f32 v[74:75], v[74:75], v[164:165] op_sel_hi:[1,0]
	v_mul_f32_e32 v76, v80, v76
	v_mul_f32_e32 v79, 0xbfb8aa3b, v74
	v_exp_f32_e32 v79, v79
	v_mul_f32_e32 v80, v72, v73
	v_add_f32_e32 v72, 1.0, v78
	v_rcp_f32_e32 v78, v72
	v_add_f32_e32 v72, 1.0, v79
	v_rcp_f32_e32 v79, v72
	v_mov_b32_e32 v72, v68
	v_mov_b32_e32 v73, v64
	v_pk_mul_f32 v[72:73], v[72:73], v[164:165] op_sel_hi:[1,0]
	v_mul_f32_e32 v74, v74, v75
	v_mul_f32_e32 v64, 0xbfb8aa3b, v72
	v_exp_f32_e32 v64, v64
	v_mul_f32_e32 v72, v72, v73
	v_mul_f32_e32 v68, v80, v78
	v_mul_f32_e32 v74, v74, v79
	v_add_f32_e32 v64, 1.0, v64
	v_rcp_f32_e32 v75, v64
	v_mov_b32_e32 v64, v69
	v_pk_mul_f32 v[64:65], v[64:65], v[164:165] op_sel_hi:[1,0]
	v_mul_f32_e32 v72, v72, v75
	v_mul_f32_e32 v69, 0xbfb8aa3b, v64
	v_exp_f32_e32 v69, v69
	v_mul_f32_e32 v73, v64, v65
	v_mov_b32_e32 v65, v66
	v_add_f32_e32 v64, 1.0, v69
	v_rcp_f32_e32 v69, v64
	v_mov_b32_e32 v64, v70
	v_pk_mul_f32 v[64:65], v[64:65], v[164:165] op_sel_hi:[1,0]
	v_mul_f32_e32 v69, v73, v69
	v_mul_f32_e32 v66, 0xbfb8aa3b, v64
	v_exp_f32_e32 v70, v66
	v_mov_b32_e32 v66, v71
	v_pk_mul_f32 v[66:67], v[66:67], v[164:165] op_sel_hi:[1,0]
	v_mul_f32_e32 v64, v64, v65
	v_mul_f32_e32 v71, 0xbfb8aa3b, v66
	v_exp_f32_e32 v71, v71
	v_add_f32_e32 v70, 1.0, v70
	v_rcp_f32_e32 v70, v70
	v_add_f32_e32 v71, 1.0, v71
	v_rcp_f32_e32 v71, v71
	v_mul_f32_e32 v70, v64, v70
	v_mul_f32_e32 v64, v66, v67
	v_mul_f32_e32 v67, v64, v71
	v_cvt_pk_bf16_f32 v64, v76, v77
	v_cvt_pk_bf16_f32 v65, v68, v74
	v_cvt_pk_bf16_f32 v66, v72, v69
	v_cvt_pk_bf16_f32 v67, v70, v67
	v_mov_b32_e32 v70, v60
	v_mov_b32_e32 v71, v56
	v_pk_mul_f32 v[70:71], v[70:71], v[160:161] op_sel_hi:[1,0]
	v_mad_i64_i32 v[68:69], s[34:35], v158, s52, v[112:113]
	v_mul_f32_e32 v56, 0xbfb8aa3b, v70
	v_exp_f32_e32 v60, v56
	v_mov_b32_e32 v56, v61
	v_pk_mul_f32 v[56:57], v[56:57], v[160:161] op_sel_hi:[1,0]
	v_lshl_add_u64 v[68:69], v[68:69], 0, v[114:115]
	v_mul_f32_e32 v61, 0xbfb8aa3b, v56
	v_exp_f32_e32 v61, v61
	v_mul_f32_e32 v56, v56, v57
	v_mov_b32_e32 v57, v58
	v_add_f32_e32 v60, 1.0, v60
	v_add_f32_e32 v61, 1.0, v61
	v_rcp_f32_e32 v61, v61
	v_rcp_f32_e32 v60, v60
	global_store_dwordx4 v[68:69], v[64:67], off
	v_mul_f32_e32 v61, v56, v61
	v_mov_b32_e32 v56, v62
	v_pk_mul_f32 v[56:57], v[56:57], v[160:161] op_sel_hi:[1,0]
	v_mul_f32_e32 v64, v70, v71
	v_mul_f32_e32 v58, 0xbfb8aa3b, v56
	v_exp_f32_e32 v62, v58
	v_mov_b32_e32 v58, v63
	v_pk_mul_f32 v[58:59], v[58:59], v[160:161] op_sel_hi:[1,0]
	v_mul_f32_e32 v60, v64, v60
	v_mul_f32_e32 v63, 0xbfb8aa3b, v58
	v_exp_f32_e32 v63, v63
	v_mul_f32_e32 v64, v56, v57
	v_add_f32_e32 v56, 1.0, v62
	v_rcp_f32_e32 v62, v56
	v_add_f32_e32 v56, 1.0, v63
	v_rcp_f32_e32 v63, v56
	v_mov_b32_e32 v56, v52
	v_mov_b32_e32 v57, v48
	v_pk_mul_f32 v[56:57], v[56:57], v[160:161] op_sel_hi:[1,0]
; __device__ __forceinline__ unsigned cvt_pk_bf16(float lo, float hi) { unsigned r; asm volatile("v_cvt_pk_bf16_f32 %0, %1, %2" : "=v"(r) : "v"(lo), "v"(hi)); return r; }
; __device__ __forceinline__ float fast_sigmoid(float x) { return __builtin_amdgcn_rcpf(1.0f + __expf(-x)); }
;     __device__ __forceinline__ void operator()(const f32x4 (&acc)[2][2][4][2], const Unit& u, int wr, int wc, int fr, int fq) const {
;     ...
;         for (int ai = 0; ai < 2; ++ai)
; #pragma unroll
;             for (int m = 0; m < 4; ++m) {
;                 const int row = u.pm * BM + ai * HALF + wr * 64 + m * 16 + fr;
;                 const float rs = rsv[ai][m];
;                 float h[8];
; #pragma unroll
;                 for (int n = 0; n < 2; ++n)
; #pragma unroll
;                     for (int i = 0; i < 4; ++i) { const float g = acc[ai][0][m][n][i] * rs, up = acc[ai][1][m][n][i] * rs; h[4 * n + i] = g * up * fast_sigmoid(g); }
;                 u32x4 w; w.x = cvt_pk_bf16(h[0], h[1]); w.y = cvt_pk_bf16(h[2], h[3]); w.z = cvt_pk_bf16(h[4], h[5]); w.w = cvt_pk_bf16(h[6], h[7]);
;                 *(u32x4*)(H + (size_t)row * 2816 + col0) = w;
	v_mul_f32_e32 v58, v58, v59
	v_mul_f32_e32 v48, 0xbfb8aa3b, v56
	v_exp_f32_e32 v48, v48
	v_mul_f32_e32 v56, v56, v57
	v_mul_f32_e32 v52, v64, v62
	v_mul_f32_e32 v58, v58, v63
	v_add_f32_e32 v48, 1.0, v48
	v_rcp_f32_e32 v59, v48
	v_mov_b32_e32 v48, v53
	v_pk_mul_f32 v[48:49], v[48:49], v[160:161] op_sel_hi:[1,0]
	v_mul_f32_e32 v56, v56, v59
	v_mul_f32_e32 v53, 0xbfb8aa3b, v48
	v_exp_f32_e32 v53, v53
	v_mul_f32_e32 v57, v48, v49
	v_mov_b32_e32 v49, v50
	v_add_f32_e32 v48, 1.0, v53
	v_rcp_f32_e32 v53, v48
	v_mov_b32_e32 v48, v54
	v_pk_mul_f32 v[48:49], v[48:49], v[160:161] op_sel_hi:[1,0]
	v_mul_f32_e32 v53, v57, v53
	v_mul_f32_e32 v50, 0xbfb8aa3b, v48
	v_exp_f32_e32 v54, v50
	v_mov_b32_e32 v50, v55
	v_pk_mul_f32 v[50:51], v[50:51], v[160:161] op_sel_hi:[1,0]
	v_mul_f32_e32 v48, v48, v49
	v_mul_f32_e32 v55, 0xbfb8aa3b, v50
	v_exp_f32_e32 v55, v55
	v_add_f32_e32 v54, 1.0, v54
	v_rcp_f32_e32 v54, v54
	v_add_f32_e32 v55, 1.0, v55
	v_rcp_f32_e32 v55, v55
	v_mul_f32_e32 v54, v48, v54
	v_mul_f32_e32 v48, v50, v51
	v_mul_f32_e32 v51, v48, v55
	v_cvt_pk_bf16_f32 v48, v60, v61
	v_cvt_pk_bf16_f32 v49, v52, v58
	v_cvt_pk_bf16_f32 v50, v56, v53
	v_cvt_pk_bf16_f32 v51, v54, v51
	v_mov_b32_e32 v54, v44
	v_mov_b32_e32 v55, v40
	v_pk_mul_f32 v[54:55], v[54:55], v[156:157] op_sel_hi:[1,0]
	v_mad_i64_i32 v[52:53], s[34:35], v154, s52, v[112:113]
	v_mul_f32_e32 v40, 0xbfb8aa3b, v54
	v_exp_f32_e32 v44, v40
	v_mov_b32_e32 v40, v45
	v_pk_mul_f32 v[40:41], v[40:41], v[156:157] op_sel_hi:[1,0]
	v_lshl_add_u64 v[52:53], v[52:53], 0, v[114:115]
	v_mul_f32_e32 v45, 0xbfb8aa3b, v40
	v_exp_f32_e32 v45, v45
	v_mul_f32_e32 v40, v40, v41
	v_mov_b32_e32 v41, v42
	v_add_f32_e32 v44, 1.0, v44
	v_add_f32_e32 v45, 1.0, v45
	v_rcp_f32_e32 v45, v45
	v_rcp_f32_e32 v44, v44
	global_store_dwordx4 v[52:53], v[48:51], off
	v_mul_f32_e32 v45, v40, v45
	v_mov_b32_e32 v40, v46
	v_pk_mul_f32 v[40:41], v[40:41], v[156:157] op_sel_hi:[1,0]
	v_mul_f32_e32 v48, v54, v55
	v_mul_f32_e32 v42, 0xbfb8aa3b, v40
	v_exp_f32_e32 v46, v42
	v_mov_b32_e32 v42, v47
	v_pk_mul_f32 v[42:43], v[42:43], v[156:157] op_sel_hi:[1,0]
	v_mul_f32_e32 v44, v48, v44
	v_mul_f32_e32 v47, 0xbfb8aa3b, v42
	v_exp_f32_e32 v47, v47
	v_mul_f32_e32 v48, v40, v41
	v_add_f32_e32 v40, 1.0, v46
	v_rcp_f32_e32 v46, v40
	v_add_f32_e32 v40, 1.0, v47
	v_rcp_f32_e32 v47, v40
	v_mov_b32_e32 v40, v36
	v_mov_b32_e32 v41, v32
	v_pk_mul_f32 v[40:41], v[40:41], v[156:157] op_sel_hi:[1,0]
	v_mul_f32_e32 v42, v42, v43
	v_mul_f32_e32 v32, 0xbfb8aa3b, v40
	v_exp_f32_e32 v32, v32
	v_mul_f32_e32 v40, v40, v41
	v_mul_f32_e32 v36, v48, v46
	v_mul_f32_e32 v42, v42, v47
	v_add_f32_e32 v32, 1.0, v32
	v_rcp_f32_e32 v43, v32
	v_mov_b32_e32 v32, v37
	v_pk_mul_f32 v[32:33], v[32:33], v[156:157] op_sel_hi:[1,0]
	v_mul_f32_e32 v40, v40, v43
	v_mul_f32_e32 v37, 0xbfb8aa3b, v32
	v_exp_f32_e32 v37, v37
	v_mul_f32_e32 v41, v32, v33
	v_mov_b32_e32 v33, v34
	v_add_f32_e32 v32, 1.0, v37
	v_rcp_f32_e32 v37, v32
	v_mov_b32_e32 v32, v38
	v_pk_mul_f32 v[32:33], v[32:33], v[156:157] op_sel_hi:[1,0]
	v_mul_f32_e32 v37, v41, v37
	v_mul_f32_e32 v34, 0xbfb8aa3b, v32
	v_exp_f32_e32 v38, v34
	v_mov_b32_e32 v34, v39
	v_pk_mul_f32 v[34:35], v[34:35], v[156:157] op_sel_hi:[1,0]
	v_mul_f32_e32 v32, v32, v33
	v_mul_f32_e32 v39, 0xbfb8aa3b, v34
	v_exp_f32_e32 v39, v39
	v_add_f32_e32 v38, 1.0, v38
	v_rcp_f32_e32 v38, v38
	v_add_f32_e32 v39, 1.0, v39
	v_rcp_f32_e32 v39, v39
	v_mul_f32_e32 v38, v32, v38
	v_mul_f32_e32 v32, v34, v35
	v_mul_f32_e32 v35, v32, v39
	v_cvt_pk_bf16_f32 v32, v44, v45
	v_cvt_pk_bf16_f32 v33, v36, v42
	v_cvt_pk_bf16_f32 v34, v40, v37
	v_cvt_pk_bf16_f32 v35, v38, v35
	v_mov_b32_e32 v38, v28
	v_mov_b32_e32 v39, v24
	v_pk_mul_f32 v[38:39], v[38:39], v[152:153] op_sel_hi:[1,0]
	v_mad_i64_i32 v[36:37], s[34:35], v150, s52, v[112:113]
	v_mul_f32_e32 v24, 0xbfb8aa3b, v38
	v_exp_f32_e32 v28, v24
	v_mov_b32_e32 v24, v29
	v_pk_mul_f32 v[24:25], v[24:25], v[152:153] op_sel_hi:[1,0]
	v_lshl_add_u64 v[36:37], v[36:37], 0, v[114:115]
	v_mul_f32_e32 v29, 0xbfb8aa3b, v24
	v_exp_f32_e32 v29, v29
	v_mul_f32_e32 v24, v24, v25
	v_mov_b32_e32 v25, v26
	v_add_f32_e32 v28, 1.0, v28
	v_add_f32_e32 v29, 1.0, v29
	v_rcp_f32_e32 v29, v29
	v_rcp_f32_e32 v28, v28
	global_store_dwordx4 v[36:37], v[32:35], off
	v_mul_f32_e32 v29, v24, v29
	v_mov_b32_e32 v24, v30
; __device__ __forceinline__ unsigned cvt_pk_bf16(float lo, float hi) { unsigned r; asm volatile("v_cvt_pk_bf16_f32 %0, %1, %2" : "=v"(r) : "v"(lo), "v"(hi)); return r; }
; __device__ __forceinline__ float fast_sigmoid(float x) { return __builtin_amdgcn_rcpf(1.0f + __expf(-x)); }
;     __device__ __forceinline__ void operator()(const f32x4 (&acc)[2][2][4][2], const Unit& u, int wr, int wc, int fr, int fq) const {
;     ...
;         for (int ai = 0; ai < 2; ++ai)
; #pragma unroll
;             for (int m = 0; m < 4; ++m) {
;                 const int row = u.pm * BM + ai * HALF + wr * 64 + m * 16 + fr;
;                 const float rs = rsv[ai][m];
;                 float h[8];
; #pragma unroll
;                 for (int n = 0; n < 2; ++n)
; #pragma unroll
;                     for (int i = 0; i < 4; ++i) { const float g = acc[ai][0][m][n][i] * rs, up = acc[ai][1][m][n][i] * rs; h[4 * n + i] = g * up * fast_sigmoid(g); }
;                 u32x4 w; w.x = cvt_pk_bf16(h[0], h[1]); w.y = cvt_pk_bf16(h[2], h[3]); w.z = cvt_pk_bf16(h[4], h[5]); w.w = cvt_pk_bf16(h[6], h[7]);
;                 *(u32x4*)(H + (size_t)row * 2816 + col0) = w;
;             }
	v_pk_mul_f32 v[24:25], v[24:25], v[152:153] op_sel_hi:[1,0]
	v_mul_f32_e32 v32, v38, v39
	v_mul_f32_e32 v26, 0xbfb8aa3b, v24
	v_exp_f32_e32 v30, v26
	v_mov_b32_e32 v26, v31
	v_pk_mul_f32 v[26:27], v[26:27], v[152:153] op_sel_hi:[1,0]
	v_mul_f32_e32 v28, v32, v28
	v_mul_f32_e32 v31, 0xbfb8aa3b, v26
	v_exp_f32_e32 v31, v31
	v_mul_f32_e32 v32, v24, v25
	v_add_f32_e32 v24, 1.0, v30
	v_rcp_f32_e32 v30, v24
	v_add_f32_e32 v24, 1.0, v31
	v_rcp_f32_e32 v31, v24
	v_mov_b32_e32 v24, v20
	v_mov_b32_e32 v25, v16
	v_pk_mul_f32 v[24:25], v[24:25], v[152:153] op_sel_hi:[1,0]
	v_mul_f32_e32 v26, v26, v27
	v_mul_f32_e32 v16, 0xbfb8aa3b, v24
	v_exp_f32_e32 v16, v16
	v_mul_f32_e32 v24, v24, v25
	v_mul_f32_e32 v20, v32, v30
	v_mul_f32_e32 v26, v26, v31
	v_add_f32_e32 v16, 1.0, v16
	v_rcp_f32_e32 v27, v16
	v_mov_b32_e32 v16, v21
	v_pk_mul_f32 v[16:17], v[16:17], v[152:153] op_sel_hi:[1,0]
	v_mul_f32_e32 v24, v24, v27
	v_mul_f32_e32 v21, 0xbfb8aa3b, v16
	v_exp_f32_e32 v21, v21
	v_mul_f32_e32 v25, v16, v17
	v_mov_b32_e32 v17, v18
	v_add_f32_e32 v16, 1.0, v21
	v_rcp_f32_e32 v21, v16
	v_mov_b32_e32 v16, v22
	v_pk_mul_f32 v[16:17], v[16:17], v[152:153] op_sel_hi:[1,0]
	v_mul_f32_e32 v21, v25, v21
	v_mul_f32_e32 v18, 0xbfb8aa3b, v16
	v_exp_f32_e32 v22, v18
	v_mov_b32_e32 v18, v23
	v_pk_mul_f32 v[18:19], v[18:19], v[152:153] op_sel_hi:[1,0]
	v_mul_f32_e32 v16, v16, v17
	v_mul_f32_e32 v23, 0xbfb8aa3b, v18
	v_exp_f32_e32 v23, v23
	v_add_f32_e32 v22, 1.0, v22
	v_rcp_f32_e32 v22, v22
	v_add_f32_e32 v23, 1.0, v23
	v_rcp_f32_e32 v23, v23
	v_mul_f32_e32 v22, v16, v22
	v_mul_f32_e32 v16, v18, v19
	v_mul_f32_e32 v19, v16, v23
	v_cvt_pk_bf16_f32 v16, v28, v29
	v_cvt_pk_bf16_f32 v17, v20, v26
	v_cvt_pk_bf16_f32 v18, v24, v21
	v_cvt_pk_bf16_f32 v19, v22, v19
	v_mov_b32_e32 v22, v12
	v_mov_b32_e32 v23, v8
	v_pk_mul_f32 v[22:23], v[22:23], v[148:149] op_sel_hi:[1,0]
	v_mad_i64_i32 v[20:21], s[34:35], v146, s52, v[112:113]
	v_mul_f32_e32 v8, 0xbfb8aa3b, v22
	v_exp_f32_e32 v12, v8
	v_mov_b32_e32 v8, v13
	v_pk_mul_f32 v[8:9], v[8:9], v[148:149] op_sel_hi:[1,0]
	v_lshl_add_u64 v[20:21], v[20:21], 0, v[114:115]
	v_mul_f32_e32 v13, 0xbfb8aa3b, v8
	v_exp_f32_e32 v13, v13
	v_mul_f32_e32 v8, v8, v9
	v_mov_b32_e32 v9, v10
	v_add_f32_e32 v12, 1.0, v12
	v_add_f32_e32 v13, 1.0, v13
	v_rcp_f32_e32 v13, v13
	v_rcp_f32_e32 v12, v12
	global_store_dwordx4 v[20:21], v[16:19], off
	v_mul_f32_e32 v13, v8, v13
	v_mov_b32_e32 v8, v14
	v_pk_mul_f32 v[8:9], v[8:9], v[148:149] op_sel_hi:[1,0]
	v_mul_f32_e32 v16, v22, v23
	v_mul_f32_e32 v10, 0xbfb8aa3b, v8
	v_exp_f32_e32 v14, v10
	v_mov_b32_e32 v10, v15
	v_pk_mul_f32 v[10:11], v[10:11], v[148:149] op_sel_hi:[1,0]
	v_mul_f32_e32 v12, v16, v12
	v_mul_f32_e32 v15, 0xbfb8aa3b, v10
	v_exp_f32_e32 v15, v15
	v_mul_f32_e32 v16, v8, v9
	v_add_f32_e32 v8, 1.0, v14
	v_rcp_f32_e32 v14, v8
	v_add_f32_e32 v8, 1.0, v15
	v_rcp_f32_e32 v15, v8
	v_mov_b32_e32 v8, v4
	v_mov_b32_e32 v9, v0
	v_pk_mul_f32 v[8:9], v[8:9], v[148:149] op_sel_hi:[1,0]
	v_mul_f32_e32 v10, v10, v11
	v_mul_f32_e32 v0, 0xbfb8aa3b, v8
	v_exp_f32_e32 v0, v0
	v_mul_f32_e32 v8, v8, v9
	v_mul_f32_e32 v4, v16, v14
	v_mul_f32_e32 v10, v10, v15
	v_add_f32_e32 v0, 1.0, v0
	v_rcp_f32_e32 v11, v0
	v_mov_b32_e32 v0, v5
	v_pk_mul_f32 v[0:1], v[0:1], v[148:149] op_sel_hi:[1,0]
	v_mul_f32_e32 v8, v8, v11
	v_mul_f32_e32 v5, 0xbfb8aa3b, v0
	v_exp_f32_e32 v5, v5
	v_mul_f32_e32 v9, v0, v1
	v_mov_b32_e32 v1, v2
	v_add_f32_e32 v0, 1.0, v5
	v_rcp_f32_e32 v5, v0
	v_mov_b32_e32 v0, v6
	v_pk_mul_f32 v[0:1], v[0:1], v[148:149] op_sel_hi:[1,0]
	v_mul_f32_e32 v5, v9, v5
	v_mul_f32_e32 v2, 0xbfb8aa3b, v0
	v_exp_f32_e32 v6, v2
	v_mov_b32_e32 v2, v7
	v_pk_mul_f32 v[2:3], v[2:3], v[148:149] op_sel_hi:[1,0]
	v_mul_f32_e32 v0, v0, v1
	v_mul_f32_e32 v7, 0xbfb8aa3b, v2
	v_exp_f32_e32 v7, v7
	v_add_f32_e32 v6, 1.0, v6
	v_rcp_f32_e32 v6, v6
	v_add_f32_e32 v7, 1.0, v7
	v_rcp_f32_e32 v7, v7
	v_mul_f32_e32 v6, v0, v6
	v_mul_f32_e32 v0, v2, v3
	v_mul_f32_e32 v3, v0, v7
	v_cvt_pk_bf16_f32 v0, v12, v13
	v_cvt_pk_bf16_f32 v1, v4, v10
	v_cvt_pk_bf16_f32 v2, v8, v5
	v_mad_i64_i32 v[4:5], s[34:35], v144, s52, v[112:113]
	v_lshl_add_u64 v[4:5], v[4:5], 0, v[114:115]
	v_cvt_pk_bf16_f32 v3, v6, v3
	global_store_dwordx4 v[4:5], v[0:3], off
	s_cbranch_vccnz .LBB0_972
	s_andn2_b64 vcc, exec, s[8:9]
	s_cbranch_vccnz .LBB0_971
	s_barrier
	s_branch .LBB0_971

; __global__ void __launch_bounds__(512, 2) fwd_kernel(Params p) {
	.amdhsa_kernel _ZN2mk10fwd_kernelENS_6ParamsE
		.amdhsa_group_segment_fixed_size 0
		.amdhsa_private_segment_fixed_size 0
		.amdhsa_kernarg_size 472
		.amdhsa_user_sgpr_count 2
		.amdhsa_user_sgpr_dispatch_ptr 0
		.amdhsa_user_sgpr_queue_ptr 0
		.amdhsa_user_sgpr_kernarg_segment_ptr 1
		.amdhsa_user_sgpr_dispatch_id 0
		.amdhsa_user_sgpr_kernarg_preload_length 0
		.amdhsa_user_sgpr_kernarg_preload_offset 0
		.amdhsa_user_sgpr_private_segment_size 0
		.amdhsa_uses_dynamic_stack 0
		.amdhsa_enable_private_segment 0
		.amdhsa_system_sgpr_workgroup_id_x 1
		.amdhsa_system_sgpr_workgroup_id_y 0
		.amdhsa_system_sgpr_workgroup_id_z 0
		.amdhsa_system_sgpr_workgroup_info 0
		.amdhsa_system_vgpr_workitem_id 2
		.amdhsa_next_free_vgpr 255
		.amdhsa_next_free_sgpr 102
		.amdhsa_accum_offset 256
		.amdhsa_reserve_vcc 1
		.amdhsa_float_round_mode_32 0
		.amdhsa_float_round_mode_16_64 0
		.amdhsa_float_denorm_mode_32 3
		.amdhsa_float_denorm_mode_16_64 3
		.amdhsa_dx10_clamp 1
		.amdhsa_ieee_mode 1
		.amdhsa_fp16_overflow 0
		.amdhsa_tg_split 0
		.amdhsa_exception_fp_ieee_invalid_op 0
		.amdhsa_exception_fp_denorm_src 0
		.amdhsa_exception_fp_ieee_div_zero 0
		.amdhsa_exception_fp_ieee_overflow 0
		.amdhsa_exception_fp_ieee_underflow 0
		.amdhsa_exception_fp_ieee_inexact 0
		.amdhsa_exception_int_div_zero 0
	.end_amdhsa_kernel

; __global__ void __launch_bounds__(512, 2) fwd_kernel(Params p) {
amdhsa.kernels:
  - .agpr_count:     0
    .args:
      - .offset:         0
        .size:           216
        .value_kind:     by_value
      - .offset:         216
        .size:           4
        .value_kind:     hidden_block_count_x
      - .offset:         220
        .size:           4
        .value_kind:     hidden_block_count_y
      - .offset:         224
        .size:           4
        .value_kind:     hidden_block_count_z
      - .offset:         228
        .size:           2
        .value_kind:     hidden_group_size_x
      - .offset:         230
        .size:           2
        .value_kind:     hidden_group_size_y
      - .offset:         232
        .size:           2
        .value_kind:     hidden_group_size_z
      - .offset:         234
        .size:           2
        .value_kind:     hidden_remainder_x
      - .offset:         236
        .size:           2
        .value_kind:     hidden_remainder_y
      - .offset:         238
        .size:           2
        .value_kind:     hidden_remainder_z
      - .offset:         256
        .size:           8
        .value_kind:     hidden_global_offset_x
      - .offset:         264
        .size:           8
        .value_kind:     hidden_global_offset_y
      - .offset:         272
        .size:           8
        .value_kind:     hidden_global_offset_z
      - .offset:         280
        .size:           2
        .value_kind:     hidden_grid_dims
      - .offset:         304
        .size:           8
        .value_kind:     hidden_multigrid_sync_arg
      - .offset:         336
        .size:           4
        .value_kind:     hidden_dynamic_lds_size
    .group_segment_fixed_size: 0
    .kernarg_segment_align: 8
    .kernarg_segment_size: 472
    .language:       OpenCL C
    .language_version:
      - 2
      - 0
    .max_flat_workgroup_size: 512
    .name:           _ZN2mk10fwd_kernelENS_6ParamsE
    .private_segment_fixed_size: 0
    .sgpr_count:     108
    .sgpr_spill_count: 17
    .symbol:         _ZN2mk10fwd_kernelENS_6ParamsE.kd
    .uniform_work_group_size: 1
    .uses_dynamic_stack: false
    .vgpr_count:     255
    .vgpr_spill_count: 0
    .wavefront_size: 64
